# saddr GEMM loops + remaining phase-1 stagings converted (zero-extended offsets) + LDS read-base adds hoisted to one phase-invariant VGPR (K-loops now VALU-free besides MFMA)
# baseline (speedup 1.0000x reference)
; #define PG8_STAGE(bufoff, gbase, voff) do { _Pragma("unroll") for (int _i = 0; _i < 2; ++_i) \
;         __builtin_amdgcn_global_load_lds((const unsigned*)((const char*)(gbase) + (voff)[_i]), (LAS unsigned*)(lds + (bufoff) + ldsw + _i * 8192), 16, 0, 0); } while (0)
; #define PG8_WAIT_V(n) asm volatile("s_waitcnt vmcnt(" #n ")" ::: "memory")
; #define PG8_BAR __builtin_amdgcn_s_barrier()
; template <class Epi, class Sched>
; __device__ __forceinline__ void gemm_phase(LAS unsigned char* lds, const Gemm g, const Sched& S, const Epi& E) {
;     ...
;     for (int i = 0; i < 2; ++i) { int R, C; stage_rc(tid * 16 + i * 8192, R, C); const int Rb = Epi::PERM ? ((R & ~31) + perm32(R & 31)) : R;
;         voffA[i] = (unsigned)(R * g.ld + C) * 2u; voffB[i] = (unsigned)(Rb * g.ld + C) * 2u; }
;     const size_t kstep = (size_t)(BK * 2);
;     const size_t hstep = (size_t)HALF * g.ld * 2;
;     const size_t tstep = 2 * hstep, sstep = (size_t)K * 2;
;     const unsigned ldsw = (unsigned)wid * 1024u;
;     const int aoff = lds_byte(wr * 64 + fr, fq * 8), boff = lds_byte(wc * 32 + fr, fq * 8);
;     ...
;     PG8_STAGE(PG8_SB(0, 0), cB, voffB); PG8_STAGE(PG8_SA(0, 0), cA, voffA); PG8_STAGE(PG8_SB(0, 1), cB + hstep, voffB); PG8_STAGE(PG8_SA(0, 1), cA + hstep, voffA);
;     if (wr == 1) PG8_BAR;
;     PG8_WAIT_V(4); PG8_BAR;
;     PG8_STAGE(PG8_SB(1, 0), cB + kstep, voffB); PG8_STAGE(PG8_SA(1, 0), cA + kstep, voffA); PG8_STAGE(PG8_SB(1, 1), cB + hstep + kstep, voffB);
;     PG8_WAIT_V(6); PG8_BAR;
.LBB0_33:
	s_sext_i32_i8 s70, s24
	v_readlane_b32 s24, v255, 7
	v_bfe_u32 v19, v18, 4, 2
	s_add_u32 s64, s24, 0xa000
	v_readlane_b32 s24, v255, 8
	v_and_b32_e32 v20, 15, v18
	v_lshlrev_b32_e32 v21, 4, v19
	v_lshlrev_b32_e32 v18, 2, v18
	s_addc_u32 s65, s24, 0
	v_lshl_or_b32 v162, s25, 6, v20
	v_lshl_or_b32 v20, v20, 6, v21
	s_lshl_b32 s24, s25, 13
	v_and_b32_e32 v18, 32, v18
	v_bitop3_b32 v21, v20, s24, v18 bitop3:0xde
	s_lshl_b32 s24, s26, 5
	s_and_b32 s26, s24, 0x60
	s_add_i32 m0, s9, 0x18000
	v_lshl_add_u64 v[8:9], v[8:9], 0, s[36:37]
	s_lshl_b32 s24, s26, 7
	s_waitcnt vmcnt(4)
	s_barrier
	global_load_lds_dwordx4 v[8:9], off
	v_lshl_add_u64 v[6:7], v[6:7], 0, s[36:37]
	s_add_i32 m0, s9, 0x1a000
	s_add_i32 s66, s9, 0x8000
	s_add_i32 s67, s9, 0xa000
	v_bitop3_b32 v163, v20, s24, v18 bitop3:0xde
	v_add_u32_e32 v226, 0x10000, v163
	global_load_lds_dwordx4 v[6:7], off
	v_lshl_add_u64 v[4:5], v[4:5], 0, s[36:37]
	s_mov_b32 m0, s66
	s_add_u32 s24, s50, 0x200080
	global_load_lds_dwordx4 v[4:5], off
	v_lshl_add_u64 v[2:3], v[2:3], 0, s[36:37]
	s_mov_b32 m0, s67
	s_addc_u32 s25, s51, 0
	global_load_lds_dwordx4 v[2:3], off
	s_add_i32 m0, s9, 0x1c000
	v_lshl_add_u64 v[2:3], s[24:25], 0, v[0:1]
	global_load_lds_dwordx4 v[2:3], off
	v_lshl_add_u64 v[2:3], s[24:25], 0, v[146:147]
	s_add_i32 m0, s9, 0x1e000
	s_mov_b64 s[24:25], 0x200080
	global_load_lds_dwordx4 v[2:3], off
	v_lshlrev_b32_e32 v2, 16, v14
	v_and_b32_e32 v2, 0x7ffe0000, v2
	v_lshl_add_u32 v2, v15, 13, v2
	v_or_b32_e32 v2, v2, v16
	v_add_lshl_u32 v2, v2, v17, 1
	v_mov_b32_e32 v3, v1
	v_lshl_add_u64 v[148:149], v[2:3], 0, s[24:25]
	v_lshlrev_b32_e32 v2, 16, v10
	v_and_b32_e32 v2, 0x7ffe0000, v2
	v_lshl_add_u32 v2, v11, 13, v2
	s_waitcnt vmcnt(6)
	v_or_b32_e32 v2, v2, v12
	v_add_lshl_u32 v2, v2, v13, 1
	s_ashr_i32 s68, s58, 31
	v_lshl_or_b32 v164, v19, 2, s26
	v_lshl_add_u64 v[150:151], v[2:3], 0, s[24:25]
	s_mov_b32 s69, 0
	v_add_u32_e32 v165, 0, v21
	s_barrier
	s_branch .LBB0_37

; #define PG8_STAGE(bufoff, gbase, voff) do { _Pragma("unroll") for (int _i = 0; _i < 2; ++_i) \
;         __builtin_amdgcn_global_load_lds((const unsigned*)((const char*)(gbase) + (voff)[_i]), (LAS unsigned*)(lds + (bufoff) + ldsw + _i * 8192), 16, 0, 0); } while (0)
; #define PG8_LDA(dst, b, h) do { _Pragma("unroll") for (int m = 0; m < 4; ++m) _Pragma("unroll") for (int k = 0; k < 2; ++k) dst[m][k] = *(const LAS bf16x8*)(lds + PG8_SA(b, h) + aoff + m * 2048 + k * 1024); } while (0)
; #define PG8_LDB(dst, b, h) do { _Pragma("unroll") for (int n = 0; n < 2; ++n) _Pragma("unroll") for (int k = 0; k < 2; ++k) dst[n][k] = *(const LAS bf16x8*)(lds + PG8_SB(b, h) + boff + n * 2048 + k * 1024); } while (0)
; #define PG8_MMA(ai, bj, At, Bt) do { __builtin_amdgcn_s_setprio(1); _Pragma("unroll") for (int m = 0; m < 4; ++m) _Pragma("unroll") for (int n = 0; n < 2; ++n) _Pragma("unroll") for (int k = 0; k < 2; ++k) \
;         acc[ai][bj][m][n] = __builtin_amdgcn_mfma_f32_16x16x32_bf16(Bt[n][k], At[m][k], acc[ai][bj][m][n], 0, 0, 0); __builtin_amdgcn_s_setprio(0); } while (0)
; #define PG8_WAIT_V(n) asm volatile("s_waitcnt vmcnt(" #n ")" ::: "memory")
; #define PG8_WAIT_L(n) asm volatile("s_waitcnt lgkmcnt(" #n ")" ::: "memory")
; #define PG8_BAR __builtin_amdgcn_s_barrier()
; #define PG8_SCHED __builtin_amdgcn_sched_barrier(0)
; template <class Epi, class Sched>
; __device__ __forceinline__ void gemm_phase(LAS unsigned char* lds, const Gemm g, const Sched& S, const Epi& E) {
;     ...
;             PG8_LDB(B0, 0, 0); PG8_SCHED; PG8_LDA(At, 0, 0); PG8_STAGE(PG8_SA(1, 1), a1 + hstep, voffA);
;             PG8_WAIT_L(8); PG8_BAR; PG8_WAIT_L(0); PG8_MMA(0, 0, At, B0); PG8_BAR; PG8_SCHED;
;             PG8_LDB(B1, 0, 1); PG8_STAGE(PG8_SB(0, 0), b2, voffB);
;             PG8_BAR; PG8_WAIT_L(0); PG8_MMA(0, 1, At, B1); PG8_BAR;
;             PG8_LDA(At, 0, 1); PG8_STAGE(PG8_SA(0, 0), a2, voffA);
;             PG8_BAR; PG8_WAIT_L(0); PG8_MMA(1, 0, At, B0); PG8_BAR; PG8_SCHED;
;             PG8_STAGE(PG8_SB(0, 1), b2 + hstep, voffB);
;             PG8_WAIT_V(6); PG8_BAR; PG8_MMA(1, 1, At, B1); PG8_BAR;
.LBB0_44:
	s_add_u32 s50, s28, 0x100
	s_addc_u32 s51, s29, 0
	s_cmpk_eq_i32 s75, 0x7c
	s_cselect_b32 s55, s27, s51
	s_cselect_b32 s54, s71, s50
	s_cselect_b32 s53, s25, s74
	s_cselect_b32 s52, s72, s73
	s_add_i32 m0, s9, 0xc000
	s_nop 0
	global_load_lds_dwordx4 v150, s[28:29]
	s_add_i32 m0, s9, 0xe000
	s_nop 0
	global_load_lds_dwordx4 v148, s[28:29]
	s_add_i32 s38, 0, 0x10000
	ds_read_b128 v[66:69], v226
	ds_read_b128 v[70:73], v226 offset:1024
	ds_read_b128 v[74:77], v226 offset:2048
	ds_read_b128 v[78:81], v226 offset:3072
	ds_read_b128 v[152:155], v165
	ds_read_b128 v[166:169], v165 offset:1024
	ds_read_b128 v[170:173], v165 offset:2048
	ds_read_b128 v[174:177], v165 offset:3072
	ds_read_b128 v[178:181], v165 offset:4096
	ds_read_b128 v[182:185], v165 offset:5120
	ds_read_b128 v[186:189], v165 offset:6144
	ds_read_b128 v[190:193], v165 offset:7168
	s_add_i32 s39, 0, 0x14000
	ds_read_b128 v[194:197], v226 offset:16384
	ds_read_b128 v[198:201], v226 offset:17408
	ds_read_b128 v[202:205], v226 offset:18432
	ds_read_b128 v[210:213], v226 offset:19456
	s_waitcnt lgkmcnt(4)
	s_barrier
	s_waitcnt lgkmcnt(0)
	v_mfma_f32_16x16x32_bf16 v[142:145], v[66:69], v[152:155], v[142:145]
	v_mfma_f32_16x16x32_bf16 v[138:141], v[74:77], v[152:155], v[138:141]
	v_mfma_f32_16x16x32_bf16 v[126:129], v[66:69], v[170:173], v[126:129]
	v_mfma_f32_16x16x32_bf16 v[122:125], v[74:77], v[170:173], v[122:125]
	v_mfma_f32_16x16x32_bf16 v[110:113], v[66:69], v[178:181], v[110:113]
	v_mfma_f32_16x16x32_bf16 v[106:109], v[74:77], v[178:181], v[106:109]
	v_mfma_f32_16x16x32_bf16 v[102:105], v[66:69], v[186:189], v[102:105]
	v_mfma_f32_16x16x32_bf16 v[98:101], v[74:77], v[186:189], v[98:101]
	v_mfma_f32_16x16x32_bf16 v[142:145], v[70:73], v[166:169], v[142:145]
	v_mfma_f32_16x16x32_bf16 v[138:141], v[78:81], v[166:169], v[138:141]
	v_mfma_f32_16x16x32_bf16 v[126:129], v[70:73], v[174:177], v[126:129]
	v_mfma_f32_16x16x32_bf16 v[122:125], v[78:81], v[174:177], v[122:125]
	v_mfma_f32_16x16x32_bf16 v[110:113], v[70:73], v[182:185], v[110:113]
	v_mfma_f32_16x16x32_bf16 v[106:109], v[78:81], v[182:185], v[106:109]
	v_mfma_f32_16x16x32_bf16 v[102:105], v[70:73], v[190:193], v[102:105]
	v_mfma_f32_16x16x32_bf16 v[98:101], v[78:81], v[190:193], v[98:101]
	v_mfma_f32_16x16x32_bf16 v[134:137], v[194:197], v[152:155], v[134:137]
	v_mfma_f32_16x16x32_bf16 v[130:133], v[202:205], v[152:155], v[130:133]
	v_mfma_f32_16x16x32_bf16 v[118:121], v[194:197], v[170:173], v[118:121]
	v_mfma_f32_16x16x32_bf16 v[114:117], v[202:205], v[170:173], v[114:117]
	v_mfma_f32_16x16x32_bf16 v[94:97], v[194:197], v[178:181], v[94:97]
	v_mfma_f32_16x16x32_bf16 v[90:93], v[202:205], v[178:181], v[90:93]
	v_mfma_f32_16x16x32_bf16 v[86:89], v[194:197], v[186:189], v[86:89]
	v_mfma_f32_16x16x32_bf16 v[82:85], v[202:205], v[186:189], v[82:85]
	v_mfma_f32_16x16x32_bf16 v[134:137], v[198:201], v[166:169], v[134:137]
	v_mfma_f32_16x16x32_bf16 v[130:133], v[210:213], v[166:169], v[130:133]
	v_mfma_f32_16x16x32_bf16 v[118:121], v[198:201], v[174:177], v[118:121]
	v_mfma_f32_16x16x32_bf16 v[114:117], v[210:213], v[174:177], v[114:117]
	v_mfma_f32_16x16x32_bf16 v[94:97], v[198:201], v[182:185], v[94:97]
	v_mfma_f32_16x16x32_bf16 v[90:93], v[210:213], v[182:185], v[90:93]
	v_mfma_f32_16x16x32_bf16 v[86:89], v[198:201], v[190:193], v[86:89]
	v_mfma_f32_16x16x32_bf16 v[82:85], v[210:213], v[190:193], v[82:85]
	s_barrier
	s_add_i32 s28, s38, s60
	s_mov_b32 m0, s28
	s_nop 0
	global_load_lds_dwordx4 v0, s[52:53]
	s_add_i32 m0, s28, 0x2000
	s_nop 0
	global_load_lds_dwordx4 v146, s[52:53]
	s_mov_b32 m0, s9
	s_nop 0
	global_load_lds_dwordx4 v0, s[54:55]
	s_mov_b32 m0, s61
	s_nop 0
	global_load_lds_dwordx4 v146, s[54:55]
	ds_read_b128 v[152:155], v165 offset:16384
	ds_read_b128 v[166:169], v165 offset:17408
	ds_read_b128 v[170:173], v165 offset:18432
	ds_read_b128 v[174:177], v165 offset:19456
	ds_read_b128 v[178:181], v165 offset:20480
	ds_read_b128 v[182:185], v165 offset:21504
	ds_read_b128 v[186:189], v165 offset:22528
	ds_read_b128 v[190:193], v165 offset:23552
	s_waitcnt vmcnt(4)
	s_waitcnt lgkmcnt(0)
	s_barrier
	v_mfma_f32_16x16x32_bf16 v[62:65], v[66:69], v[152:155], v[62:65]
	v_mfma_f32_16x16x32_bf16 v[58:61], v[74:77], v[152:155], v[58:61]
	v_mfma_f32_16x16x32_bf16 v[46:49], v[66:69], v[170:173], v[46:49]
	v_mfma_f32_16x16x32_bf16 v[42:45], v[74:77], v[170:173], v[42:45]
	v_mfma_f32_16x16x32_bf16 v[30:33], v[66:69], v[178:181], v[30:33]
	v_mfma_f32_16x16x32_bf16 v[26:29], v[74:77], v[178:181], v[26:29]
	v_mfma_f32_16x16x32_bf16 v[22:25], v[66:69], v[186:189], v[22:25]
	v_mfma_f32_16x16x32_bf16 v[14:17], v[74:77], v[186:189], v[14:17]
	v_mfma_f32_16x16x32_bf16 v[62:65], v[70:73], v[166:169], v[62:65]
	v_mfma_f32_16x16x32_bf16 v[58:61], v[78:81], v[166:169], v[58:61]
	v_mfma_f32_16x16x32_bf16 v[46:49], v[70:73], v[174:177], v[46:49]
	v_mfma_f32_16x16x32_bf16 v[42:45], v[78:81], v[174:177], v[42:45]
	v_mfma_f32_16x16x32_bf16 v[30:33], v[70:73], v[182:185], v[30:33]
	v_mfma_f32_16x16x32_bf16 v[26:29], v[78:81], v[182:185], v[26:29]
	v_mfma_f32_16x16x32_bf16 v[22:25], v[70:73], v[190:193], v[22:25]
	v_mfma_f32_16x16x32_bf16 v[14:17], v[78:81], v[190:193], v[14:17]
	v_mfma_f32_16x16x32_bf16 v[54:57], v[194:197], v[152:155], v[54:57]
	v_mfma_f32_16x16x32_bf16 v[50:53], v[202:205], v[152:155], v[50:53]
	v_mfma_f32_16x16x32_bf16 v[38:41], v[194:197], v[170:173], v[38:41]
	v_mfma_f32_16x16x32_bf16 v[34:37], v[202:205], v[170:173], v[34:37]
	v_mfma_f32_16x16x32_bf16 v[18:21], v[194:197], v[178:181], v[18:21]
	v_mfma_f32_16x16x32_bf16 v[10:13], v[202:205], v[178:181], v[10:13]
	v_mfma_f32_16x16x32_bf16 v[6:9], v[194:197], v[186:189], v[6:9]
	v_mfma_f32_16x16x32_bf16 v[2:5], v[202:205], v[186:189], v[2:5]
	v_mfma_f32_16x16x32_bf16 v[54:57], v[198:201], v[166:169], v[54:57]
	v_mfma_f32_16x16x32_bf16 v[50:53], v[210:213], v[166:169], v[50:53]
	v_mfma_f32_16x16x32_bf16 v[38:41], v[198:201], v[174:177], v[38:41]
	v_mfma_f32_16x16x32_bf16 v[34:37], v[210:213], v[174:177], v[34:37]
	v_mfma_f32_16x16x32_bf16 v[18:21], v[198:201], v[182:185], v[18:21]
	v_mfma_f32_16x16x32_bf16 v[10:13], v[210:213], v[182:185], v[10:13]
	v_mfma_f32_16x16x32_bf16 v[6:9], v[198:201], v[190:193], v[6:9]
	v_mfma_f32_16x16x32_bf16 v[2:5], v[210:213], v[190:193], v[2:5]
	s_barrier
; #define PG8_STAGE(bufoff, gbase, voff) do { _Pragma("unroll") for (int _i = 0; _i < 2; ++_i) \
;         __builtin_amdgcn_global_load_lds((const unsigned*)((const char*)(gbase) + (voff)[_i]), (LAS unsigned*)(lds + (bufoff) + ldsw + _i * 8192), 16, 0, 0); } while (0)
; #define PG8_LDA(dst, b, h) do { _Pragma("unroll") for (int m = 0; m < 4; ++m) _Pragma("unroll") for (int k = 0; k < 2; ++k) dst[m][k] = *(const LAS bf16x8*)(lds + PG8_SA(b, h) + aoff + m * 2048 + k * 1024); } while (0)
; #define PG8_LDB(dst, b, h) do { _Pragma("unroll") for (int n = 0; n < 2; ++n) _Pragma("unroll") for (int k = 0; k < 2; ++k) dst[n][k] = *(const LAS bf16x8*)(lds + PG8_SB(b, h) + boff + n * 2048 + k * 1024); } while (0)
; #define PG8_MMA(ai, bj, At, Bt) do { __builtin_amdgcn_s_setprio(1); _Pragma("unroll") for (int m = 0; m < 4; ++m) _Pragma("unroll") for (int n = 0; n < 2; ++n) _Pragma("unroll") for (int k = 0; k < 2; ++k) \
;         acc[ai][bj][m][n] = __builtin_amdgcn_mfma_f32_16x16x32_bf16(Bt[n][k], At[m][k], acc[ai][bj][m][n], 0, 0, 0); __builtin_amdgcn_s_setprio(0); } while (0)
; #define PG8_WAIT_V(n) asm volatile("s_waitcnt vmcnt(" #n ")" ::: "memory")
; #define PG8_WAIT_L(n) asm volatile("s_waitcnt lgkmcnt(" #n ")" ::: "memory")
; #define PG8_BAR __builtin_amdgcn_s_barrier()
; #define PG8_SCHED __builtin_amdgcn_sched_barrier(0)
; template <class Epi, class Sched>
; __device__ __forceinline__ void gemm_phase(LAS unsigned char* lds, const Gemm g, const Sched& S, const Epi& E) {
;     ...
;             PG8_STAGE(PG8_SB(0, 1), b2 + hstep, voffB);
;             PG8_WAIT_V(6); PG8_BAR; PG8_MMA(1, 1, At, B1); PG8_BAR;
;             PG8_LDB(B0, 1, 0); PG8_SCHED; PG8_LDA(At, 1, 0); PG8_STAGE(PG8_SA(0, 1), a2 + hstep, voffA);
;             PG8_WAIT_L(8); PG8_BAR; PG8_WAIT_L(0); PG8_MMA(0, 0, At, B0); PG8_BAR; PG8_SCHED;
;             PG8_LDB(B1, 1, 1); PG8_STAGE(PG8_SB(1, 0), b3, voffB);
;             PG8_BAR; PG8_WAIT_L(0); PG8_MMA(0, 1, At, B1); PG8_BAR;
;             PG8_LDA(At, 1, 1); PG8_STAGE(PG8_SA(1, 0), a3, voffA);
;             PG8_BAR; PG8_WAIT_L(0); PG8_MMA(1, 0, At, B0); PG8_BAR; PG8_SCHED;
;             PG8_STAGE(PG8_SB(1, 1), b3 + hstep, voffB);
;             PG8_WAIT_V(6); PG8_BAR; PG8_MMA(1, 1, At, B1); PG8_BAR;
;         }
;         E(acc, cur, wr, wc, fr, fq);
;         if (!has_next) break;
	s_add_u32 s28, s52, 0x200000
	s_addc_u32 s29, s53, 0
	s_add_i32 s38, s39, s60
	s_mov_b32 m0, s38
	s_nop 0
	global_load_lds_dwordx4 v0, s[28:29]
	s_add_i32 m0, s38, 0x2000
	s_nop 0
	global_load_lds_dwordx4 v146, s[28:29]
	s_add_u32 s28, s54, 0x200000
	s_addc_u32 s29, s55, 0
	s_mov_b32 m0, s62
	s_nop 0
	global_load_lds_dwordx4 v0, s[28:29]
	s_mov_b32 m0, s63
	s_nop 0
	global_load_lds_dwordx4 v146, s[28:29]
	s_add_i32 s38, 0, 0x18000
	ds_read_b128 v[66:69], v226 offset:32768
	ds_read_b128 v[70:73], v226 offset:33792
	ds_read_b128 v[74:77], v226 offset:34816
	ds_read_b128 v[78:81], v226 offset:35840
	ds_read_b128 v[152:155], v165 offset:32768
	ds_read_b128 v[166:169], v165 offset:33792
	ds_read_b128 v[170:173], v165 offset:34816
	ds_read_b128 v[174:177], v165 offset:35840
	ds_read_b128 v[178:181], v165 offset:36864
	ds_read_b128 v[182:185], v165 offset:37888
	ds_read_b128 v[186:189], v165 offset:38912
	ds_read_b128 v[190:193], v165 offset:39936
	s_add_i32 s39, 0, 0x1c000
	ds_read_b128 v[194:197], v226 offset:49152
	ds_read_b128 v[198:201], v226 offset:50176
	ds_read_b128 v[202:205], v226 offset:51200
	ds_read_b128 v[210:213], v226 offset:52224
	s_waitcnt lgkmcnt(4)
	s_barrier
	s_waitcnt lgkmcnt(0)
	v_mfma_f32_16x16x32_bf16 v[142:145], v[66:69], v[152:155], v[142:145]
	v_mfma_f32_16x16x32_bf16 v[138:141], v[74:77], v[152:155], v[138:141]
	v_mfma_f32_16x16x32_bf16 v[126:129], v[66:69], v[170:173], v[126:129]
	v_mfma_f32_16x16x32_bf16 v[122:125], v[74:77], v[170:173], v[122:125]
	v_mfma_f32_16x16x32_bf16 v[110:113], v[66:69], v[178:181], v[110:113]
	v_mfma_f32_16x16x32_bf16 v[106:109], v[74:77], v[178:181], v[106:109]
	v_mfma_f32_16x16x32_bf16 v[102:105], v[66:69], v[186:189], v[102:105]
	v_mfma_f32_16x16x32_bf16 v[98:101], v[74:77], v[186:189], v[98:101]
	v_mfma_f32_16x16x32_bf16 v[142:145], v[70:73], v[166:169], v[142:145]
	v_mfma_f32_16x16x32_bf16 v[138:141], v[78:81], v[166:169], v[138:141]
	v_mfma_f32_16x16x32_bf16 v[126:129], v[70:73], v[174:177], v[126:129]
	v_mfma_f32_16x16x32_bf16 v[122:125], v[78:81], v[174:177], v[122:125]
	v_mfma_f32_16x16x32_bf16 v[110:113], v[70:73], v[182:185], v[110:113]
	v_mfma_f32_16x16x32_bf16 v[106:109], v[78:81], v[182:185], v[106:109]
	v_mfma_f32_16x16x32_bf16 v[102:105], v[70:73], v[190:193], v[102:105]
	v_mfma_f32_16x16x32_bf16 v[98:101], v[78:81], v[190:193], v[98:101]
	v_mfma_f32_16x16x32_bf16 v[134:137], v[194:197], v[152:155], v[134:137]
	v_mfma_f32_16x16x32_bf16 v[130:133], v[202:205], v[152:155], v[130:133]
	v_mfma_f32_16x16x32_bf16 v[118:121], v[194:197], v[170:173], v[118:121]
	v_mfma_f32_16x16x32_bf16 v[114:117], v[202:205], v[170:173], v[114:117]
	v_mfma_f32_16x16x32_bf16 v[94:97], v[194:197], v[178:181], v[94:97]
	v_mfma_f32_16x16x32_bf16 v[90:93], v[202:205], v[178:181], v[90:93]
	v_mfma_f32_16x16x32_bf16 v[86:89], v[194:197], v[186:189], v[86:89]
	v_mfma_f32_16x16x32_bf16 v[82:85], v[202:205], v[186:189], v[82:85]
	v_mfma_f32_16x16x32_bf16 v[134:137], v[198:201], v[166:169], v[134:137]
	v_mfma_f32_16x16x32_bf16 v[130:133], v[210:213], v[166:169], v[130:133]
	v_mfma_f32_16x16x32_bf16 v[118:121], v[198:201], v[174:177], v[118:121]
	v_mfma_f32_16x16x32_bf16 v[114:117], v[210:213], v[174:177], v[114:117]
	v_mfma_f32_16x16x32_bf16 v[94:97], v[198:201], v[182:185], v[94:97]
	v_mfma_f32_16x16x32_bf16 v[90:93], v[210:213], v[182:185], v[90:93]
	v_mfma_f32_16x16x32_bf16 v[86:89], v[198:201], v[190:193], v[86:89]
	v_mfma_f32_16x16x32_bf16 v[82:85], v[210:213], v[190:193], v[82:85]
	s_barrier
	s_add_i32 s28, s38, s60
	s_add_u32 s100, s52, s36
	s_addc_u32 s101, s53, s37
	s_mov_b32 m0, s28
	s_nop 0
	global_load_lds_dwordx4 v0, s[100:101]
	s_add_i32 m0, s28, 0x2000
	s_nop 0
	global_load_lds_dwordx4 v146, s[100:101]
	s_mov_b32 m0, s66
	s_add_u32 s100, s54, s36
	s_addc_u32 s101, s55, s37
	global_load_lds_dwordx4 v0, s[100:101]
	s_mov_b32 m0, s67
	s_nop 0
	global_load_lds_dwordx4 v146, s[100:101]
	ds_read_b128 v[152:155], v165 offset:49152
	ds_read_b128 v[166:169], v165 offset:50176
	ds_read_b128 v[170:173], v165 offset:51200
	ds_read_b128 v[174:177], v165 offset:52224
	ds_read_b128 v[178:181], v165 offset:53248
	ds_read_b128 v[182:185], v165 offset:54272
	ds_read_b128 v[186:189], v165 offset:55296
	ds_read_b128 v[190:193], v165 offset:56320
	s_waitcnt vmcnt(4)
	s_waitcnt lgkmcnt(0)
	s_barrier
	v_mfma_f32_16x16x32_bf16 v[62:65], v[66:69], v[152:155], v[62:65]
	v_mfma_f32_16x16x32_bf16 v[58:61], v[74:77], v[152:155], v[58:61]
	v_mfma_f32_16x16x32_bf16 v[46:49], v[66:69], v[170:173], v[46:49]
	v_mfma_f32_16x16x32_bf16 v[42:45], v[74:77], v[170:173], v[42:45]
	v_mfma_f32_16x16x32_bf16 v[30:33], v[66:69], v[178:181], v[30:33]
	v_mfma_f32_16x16x32_bf16 v[26:29], v[74:77], v[178:181], v[26:29]
	v_mfma_f32_16x16x32_bf16 v[22:25], v[66:69], v[186:189], v[22:25]
	v_mfma_f32_16x16x32_bf16 v[14:17], v[74:77], v[186:189], v[14:17]
	v_mfma_f32_16x16x32_bf16 v[62:65], v[70:73], v[166:169], v[62:65]
	v_mfma_f32_16x16x32_bf16 v[58:61], v[78:81], v[166:169], v[58:61]
	v_mfma_f32_16x16x32_bf16 v[46:49], v[70:73], v[174:177], v[46:49]
	v_mfma_f32_16x16x32_bf16 v[42:45], v[78:81], v[174:177], v[42:45]
	v_mfma_f32_16x16x32_bf16 v[30:33], v[70:73], v[182:185], v[30:33]
	v_mfma_f32_16x16x32_bf16 v[26:29], v[78:81], v[182:185], v[26:29]
	v_mfma_f32_16x16x32_bf16 v[22:25], v[70:73], v[190:193], v[22:25]
	v_mfma_f32_16x16x32_bf16 v[14:17], v[78:81], v[190:193], v[14:17]
	s_add_u32 s28, s52, 0x200080
	s_addc_u32 s29, s53, 0
	s_add_i32 s38, s39, s60
	s_mov_b32 m0, s38
	s_nop 0
	global_load_lds_dwordx4 v0, s[28:29]
	s_add_i32 m0, s38, 0x2000
	s_nop 0
	global_load_lds_dwordx4 v146, s[28:29]
	v_mfma_f32_16x16x32_bf16 v[54:57], v[194:197], v[152:155], v[54:57]
	v_mfma_f32_16x16x32_bf16 v[50:53], v[202:205], v[152:155], v[50:53]
	v_mfma_f32_16x16x32_bf16 v[38:41], v[194:197], v[170:173], v[38:41]
	v_mfma_f32_16x16x32_bf16 v[34:37], v[202:205], v[170:173], v[34:37]
	v_mfma_f32_16x16x32_bf16 v[18:21], v[194:197], v[178:181], v[18:21]
	v_mfma_f32_16x16x32_bf16 v[10:13], v[202:205], v[178:181], v[10:13]
	v_mfma_f32_16x16x32_bf16 v[6:9], v[194:197], v[186:189], v[6:9]
	v_mfma_f32_16x16x32_bf16 v[2:5], v[202:205], v[186:189], v[2:5]
	v_mfma_f32_16x16x32_bf16 v[54:57], v[198:201], v[166:169], v[54:57]
	v_mfma_f32_16x16x32_bf16 v[50:53], v[210:213], v[166:169], v[50:53]
	v_mfma_f32_16x16x32_bf16 v[38:41], v[198:201], v[174:177], v[38:41]
	v_mfma_f32_16x16x32_bf16 v[34:37], v[210:213], v[174:177], v[34:37]
	v_mfma_f32_16x16x32_bf16 v[18:21], v[198:201], v[182:185], v[18:21]
	v_mfma_f32_16x16x32_bf16 v[10:13], v[210:213], v[182:185], v[10:13]
	v_mfma_f32_16x16x32_bf16 v[6:9], v[198:201], v[190:193], v[6:9]
	v_mfma_f32_16x16x32_bf16 v[2:5], v[210:213], v[190:193], v[2:5]
	s_add_i32 s75, s75, 2
	s_add_u32 s73, s73, 0x100
	s_addc_u32 s74, s74, 0
	s_cmpk_gt_u32 s75, 0x7d
	s_mov_b64 s[28:29], s[50:51]
	s_barrier
	s_cbranch_scc0 .LBB0_44
	s_cmp_lt_i32 s8, 64
	s_cselect_b64 s[50:51], -1, 0
	s_cmp_gt_i32 s8, 63
	s_cbranch_scc0 .LBB0_35
	s_mov_b64 s[52:53], 0x18000
	s_mov_b64 s[28:29], s[46:47]
	s_branch .LBB0_36

; __device__ __forceinline__ int tid_o() { int t = (int)threadIdx.x; asm volatile("" : "+v"(t)); return t; }
; #define PG8_STAGE(bufoff, gbase, voff) do { _Pragma("unroll") for (int _i = 0; _i < 2; ++_i) \
;         __builtin_amdgcn_global_load_lds((const unsigned*)((const char*)(gbase) + (voff)[_i]), (LAS unsigned*)(lds + (bufoff) + ldsw + _i * 8192), 16, 0, 0); } while (0)
; #define PG8_WAIT_V(n) asm volatile("s_waitcnt vmcnt(" #n ")" ::: "memory")
; #define PG8_BAR __builtin_amdgcn_s_barrier()
; template <class Epi, class Sched>
; __device__ __forceinline__ void gemm_phase(LAS unsigned char* lds, const Gemm g, const Sched& S, const Epi& E) {
;     const int tid = tid_o(), wid = __builtin_amdgcn_readfirstlane(tid >> 6), lane = tid & 63, wr = wid >> 2, wc = wid & 3, fr = lane & 15, fq = lane >> 4;
;     const int K = g.K, nt = K / BK;
;     unsigned voffA[2], voffB[2];
; #pragma unroll
;     for (int i = 0; i < 2; ++i) { int R, C; stage_rc(tid * 16 + i * 8192, R, C); const int Rb = Epi::PERM ? ((R & ~31) + perm32(R & 31)) : R;
;         voffA[i] = (unsigned)(R * g.ld + C) * 2u; voffB[i] = (unsigned)(Rb * g.ld + C) * 2u; }
;     const size_t kstep = (size_t)(BK * 2);
;     const size_t hstep = (size_t)HALF * g.ld * 2;
;     const size_t tstep = 2 * hstep, sstep = (size_t)K * 2;
;     const unsigned ldsw = (unsigned)wid * 1024u;
;     const int aoff = lds_byte(wr * 64 + fr, fq * 8), boff = lds_byte(wc * 32 + fr, fq * 8);
;     ...
;     const char* cA = (const char*)g.A + (size_t)cur.pm * tstep + (size_t)cur.ks * sstep; const char* cB = (const char*)g.Bt + (size_t)cur.pn * tstep + (size_t)cur.ks * sstep;
;     PG8_STAGE(PG8_SB(0, 0), cB, voffB); PG8_STAGE(PG8_SA(0, 0), cA, voffA); PG8_STAGE(PG8_SB(0, 1), cB + hstep, voffB); PG8_STAGE(PG8_SA(0, 1), cA + hstep, voffA);
;     if (wr == 1) PG8_BAR;
;     PG8_WAIT_V(4); PG8_BAR;
;     PG8_STAGE(PG8_SB(1, 0), cB + kstep, voffB); PG8_STAGE(PG8_SA(1, 0), cA + kstep, voffA); PG8_STAGE(PG8_SB(1, 1), cB + hstep + kstep, voffB);
;     PG8_WAIT_V(6); PG8_BAR;
.LBB0_54:
	v_bfe_u32 v20, v10, 4, 2
	v_and_b32_e32 v11, 15, v10
	v_lshlrev_b32_e32 v21, 4, v20
	v_lshlrev_b32_e32 v10, 2, v10
	v_lshl_or_b32 v136, s29, 6, v11
	v_lshl_or_b32 v11, v11, 6, v21
	s_lshl_b32 s11, s29, 13
	v_and_b32_e32 v10, 32, v10
	v_bitop3_b32 v21, v11, s11, v10 bitop3:0xde
	s_lshl_b32 s11, s28, 5
	s_and_b32 s11, s11, 0x60
	v_lshl_add_u64 v[12:13], s[52:53], 0, v[0:1]
	v_mov_b32_e32 v131, v1
	s_lshl_b32 s28, s11, 7
	v_lshl_add_u64 v[14:15], s[52:53], 0, v[130:131]
	v_bitop3_b32 v137, v11, s28, v10 bitop3:0xde
	v_add_u32_e32 v226, 0x10000, v137
	s_add_i32 m0, s25, 0x18000
	v_lshl_add_u64 v[10:11], v[12:13], 0, s[36:37]
	v_lshl_add_u64 v[16:17], s[50:51], 0, v[0:1]
	s_waitcnt vmcnt(4)
	s_barrier
	global_load_lds_dwordx4 v[10:11], off
	v_lshl_add_u64 v[10:11], v[14:15], 0, s[36:37]
	s_add_i32 m0, s25, 0x1a000
	s_add_i32 s66, s25, 0x8000
	s_add_i32 s67, s25, 0xa000
	v_lshl_add_u64 v[18:19], s[50:51], 0, v[130:131]
	global_load_lds_dwordx4 v[10:11], off
	v_lshl_add_u64 v[10:11], v[16:17], 0, s[36:37]
	s_mov_b32 m0, s66
	s_add_u32 s28, s52, 0x200080
	global_load_lds_dwordx4 v[10:11], off
	v_lshl_add_u64 v[10:11], v[18:19], 0, s[36:37]
	s_mov_b32 m0, s67
	s_addc_u32 s29, s53, 0
	global_load_lds_dwordx4 v[10:11], off
	s_add_i32 m0, s25, 0x1c000
	v_lshl_add_u64 v[10:11], s[28:29], 0, v[0:1]
	global_load_lds_dwordx4 v[10:11], off
	v_lshl_add_u64 v[10:11], s[28:29], 0, v[130:131]
	s_add_i32 m0, s25, 0x1e000
	v_lshlrev_b32_e32 v2, 16, v2
	global_load_lds_dwordx4 v[10:11], off
	v_and_b32_e32 v2, 0x7ffe0000, v2
	v_lshl_add_u32 v2, v3, 13, v2
	v_or_b32_e32 v2, v2, v4
	v_add_lshl_u32 v2, v2, v5, 1
	v_mov_b32_e32 v3, v1
	s_mov_b64 s[28:29], 0x200080
	v_lshl_add_u64 v[132:133], v[2:3], 0, s[28:29]
	v_lshlrev_b32_e32 v2, 16, v7
	v_and_b32_e32 v2, 0x7ffe0000, v2
	v_lshl_add_u32 v2, v6, 13, v2
	s_waitcnt vmcnt(6)
	v_or_b32_e32 v2, v2, v8
	v_add_lshl_u32 v2, v2, v9, 1
	v_lshl_or_b32 v138, v20, 2, s11
	v_lshl_add_u64 v[134:135], v[2:3], 0, s[28:29]
	s_mov_b32 s68, 0
	v_add_u32_e32 v139, 0, v21
	s_barrier

; #define PG8_STAGE(bufoff, gbase, voff) do { _Pragma("unroll") for (int _i = 0; _i < 2; ++_i) \
;         __builtin_amdgcn_global_load_lds((const unsigned*)((const char*)(gbase) + (voff)[_i]), (LAS unsigned*)(lds + (bufoff) + ldsw + _i * 8192), 16, 0, 0); } while (0)
; #define PG8_LDA(dst, b, h) do { _Pragma("unroll") for (int m = 0; m < 4; ++m) _Pragma("unroll") for (int k = 0; k < 2; ++k) dst[m][k] = *(const LAS bf16x8*)(lds + PG8_SA(b, h) + aoff + m * 2048 + k * 1024); } while (0)
; #define PG8_LDB(dst, b, h) do { _Pragma("unroll") for (int n = 0; n < 2; ++n) _Pragma("unroll") for (int k = 0; k < 2; ++k) dst[n][k] = *(const LAS bf16x8*)(lds + PG8_SB(b, h) + boff + n * 2048 + k * 1024); } while (0)
; #define PG8_WAIT_V(n) asm volatile("s_waitcnt vmcnt(" #n ")" ::: "memory")
; #define PG8_WAIT_L(n) asm volatile("s_waitcnt lgkmcnt(" #n ")" ::: "memory")
; #define PG8_BAR __builtin_amdgcn_s_barrier()
; #define PG8_SCHED __builtin_amdgcn_sched_barrier(0)
; template <class Epi, class Sched>
; __device__ __forceinline__ void gemm_phase(LAS unsigned char* lds, const Gemm g, const Sched& S, const Epi& E) {
;     ...
;         const bool has_next = S.next(ui + 1, nxt);
;         const char* nA = has_next ? (const char*)g.A + (size_t)nxt.pm * tstep + (size_t)nxt.ks * sstep : cA; const char* nB = has_next ? (const char*)g.Bt + (size_t)nxt.pn * tstep + (size_t)nxt.ks * sstep : cB;
;         for (int t = 0; t < nt; t += 2) {
;             const bool last = (t == nt - 2);
;             const char* a1 = cA + (size_t)(t + 1) * kstep;
;             const char* a2 = last ? nA : cA + (size_t)(t + 2) * kstep; const char* b2 = last ? nB : cB + (size_t)(t + 2) * kstep;
;             const char* a3 = a2 + kstep; const char* b3 = b2 + kstep;
;             PG8_LDB(B0, 0, 0); PG8_SCHED; PG8_LDA(At, 0, 0); PG8_STAGE(PG8_SA(1, 1), a1 + hstep, voffA);
;             PG8_WAIT_L(8); PG8_BAR; PG8_WAIT_L(0); PG8_MMA(0, 0, At, B0); PG8_BAR; PG8_SCHED;
;             PG8_LDB(B1, 0, 1); PG8_STAGE(PG8_SB(0, 0), b2, voffB);
;             PG8_BAR; PG8_WAIT_L(0); PG8_MMA(0, 1, At, B1); PG8_BAR;
;             PG8_LDA(At, 0, 1); PG8_STAGE(PG8_SA(0, 0), a2, voffA);
;             PG8_BAR; PG8_WAIT_L(0); PG8_MMA(1, 0, At, B0); PG8_BAR; PG8_SCHED;
;             PG8_STAGE(PG8_SB(0, 1), b2 + hstep, voffB);
;             PG8_WAIT_V(6); PG8_BAR; PG8_MMA(1, 1, At, B1); PG8_BAR;
.LBB0_58:
	s_add_u32 s52, s50, 0x100
	s_addc_u32 s53, s51, 0
	s_cmp_eq_u32 s71, 28
	s_cselect_b32 s57, s11, s53
	s_cselect_b32 s56, s29, s52
	s_cselect_b32 s55, s41, s70
	s_cselect_b32 s54, s43, s69
	s_add_i32 m0, s25, 0xc000
	s_nop 0
	global_load_lds_dwordx4 v134, s[50:51]
	s_add_i32 m0, s25, 0xe000
	s_nop 0
	global_load_lds_dwordx4 v132, s[50:51]
	s_add_i32 s38, 0, 0x10000
	ds_read_b128 v[140:143], v226
	ds_read_b128 v[144:147], v226 offset:1024
	ds_read_b128 v[148:151], v226 offset:2048
	ds_read_b128 v[152:155], v226 offset:3072
	ds_read_b128 v[160:163], v139
	ds_read_b128 v[164:167], v139 offset:1024
	ds_read_b128 v[168:171], v139 offset:2048
	ds_read_b128 v[172:175], v139 offset:3072
	ds_read_b128 v[176:179], v139 offset:4096
	ds_read_b128 v[180:183], v139 offset:5120
	ds_read_b128 v[184:187], v139 offset:6144
	ds_read_b128 v[188:191], v139 offset:7168
	s_add_i32 s50, 0, 0x14000
	ds_read_b128 v[192:195], v226 offset:16384
	ds_read_b128 v[196:199], v226 offset:17408
	ds_read_b128 v[200:203], v226 offset:18432
	ds_read_b128 v[204:207], v226 offset:19456
	s_waitcnt lgkmcnt(4)
	s_barrier
	s_waitcnt lgkmcnt(0)
	v_mfma_f32_16x16x32_bf16 v[126:129], v[140:143], v[160:163], v[126:129]
	v_mfma_f32_16x16x32_bf16 v[122:125], v[148:151], v[160:163], v[122:125]
	v_mfma_f32_16x16x32_bf16 v[118:121], v[140:143], v[168:171], v[118:121]
	v_mfma_f32_16x16x32_bf16 v[114:117], v[148:151], v[168:171], v[114:117]
	v_mfma_f32_16x16x32_bf16 v[106:109], v[140:143], v[176:179], v[106:109]
	v_mfma_f32_16x16x32_bf16 v[98:101], v[148:151], v[176:179], v[98:101]
	v_mfma_f32_16x16x32_bf16 v[90:93], v[140:143], v[184:187], v[90:93]
	v_mfma_f32_16x16x32_bf16 v[82:85], v[148:151], v[184:187], v[82:85]
	v_mfma_f32_16x16x32_bf16 v[126:129], v[144:147], v[164:167], v[126:129]
	v_mfma_f32_16x16x32_bf16 v[122:125], v[152:155], v[164:167], v[122:125]
	v_mfma_f32_16x16x32_bf16 v[118:121], v[144:147], v[172:175], v[118:121]
	v_mfma_f32_16x16x32_bf16 v[114:117], v[152:155], v[172:175], v[114:117]
	v_mfma_f32_16x16x32_bf16 v[106:109], v[144:147], v[180:183], v[106:109]
	v_mfma_f32_16x16x32_bf16 v[98:101], v[152:155], v[180:183], v[98:101]
	v_mfma_f32_16x16x32_bf16 v[90:93], v[144:147], v[188:191], v[90:93]
	v_mfma_f32_16x16x32_bf16 v[82:85], v[152:155], v[188:191], v[82:85]
	v_mfma_f32_16x16x32_bf16 v[110:113], v[192:195], v[160:163], v[110:113]
	v_mfma_f32_16x16x32_bf16 v[102:105], v[200:203], v[160:163], v[102:105]
	v_mfma_f32_16x16x32_bf16 v[94:97], v[192:195], v[168:171], v[94:97]
	v_mfma_f32_16x16x32_bf16 v[86:89], v[200:203], v[168:171], v[86:89]
	v_mfma_f32_16x16x32_bf16 v[78:81], v[192:195], v[176:179], v[78:81]
	v_mfma_f32_16x16x32_bf16 v[74:77], v[200:203], v[176:179], v[74:77]
	v_mfma_f32_16x16x32_bf16 v[70:73], v[192:195], v[184:187], v[70:73]
	v_mfma_f32_16x16x32_bf16 v[66:69], v[200:203], v[184:187], v[66:69]
	v_mfma_f32_16x16x32_bf16 v[110:113], v[196:199], v[164:167], v[110:113]
	v_mfma_f32_16x16x32_bf16 v[102:105], v[204:207], v[164:167], v[102:105]
	v_mfma_f32_16x16x32_bf16 v[94:97], v[196:199], v[172:175], v[94:97]
	v_mfma_f32_16x16x32_bf16 v[86:89], v[204:207], v[172:175], v[86:89]
	v_mfma_f32_16x16x32_bf16 v[78:81], v[196:199], v[180:183], v[78:81]
	v_mfma_f32_16x16x32_bf16 v[74:77], v[204:207], v[180:183], v[74:77]
	v_mfma_f32_16x16x32_bf16 v[70:73], v[196:199], v[188:191], v[70:73]
	v_mfma_f32_16x16x32_bf16 v[66:69], v[204:207], v[188:191], v[66:69]
	s_barrier
	s_add_i32 s38, s38, s63
	s_mov_b32 m0, s38
	s_nop 0
	global_load_lds_dwordx4 v0, s[54:55]
	s_add_i32 m0, s38, 0x2000
	s_nop 0
	global_load_lds_dwordx4 v130, s[54:55]
	s_mov_b32 m0, s25
	s_nop 0
	global_load_lds_dwordx4 v0, s[56:57]
	s_mov_b32 m0, s27
	s_nop 0
	global_load_lds_dwordx4 v130, s[56:57]
	ds_read_b128 v[160:163], v139 offset:16384
	ds_read_b128 v[164:167], v139 offset:17408
	ds_read_b128 v[168:171], v139 offset:18432
	ds_read_b128 v[172:175], v139 offset:19456
	ds_read_b128 v[176:179], v139 offset:20480
	ds_read_b128 v[180:183], v139 offset:21504
	ds_read_b128 v[184:187], v139 offset:22528
	ds_read_b128 v[188:191], v139 offset:23552
	s_waitcnt vmcnt(4)
	s_waitcnt lgkmcnt(0)
	s_barrier
	v_mfma_f32_16x16x32_bf16 v[62:65], v[140:143], v[160:163], v[62:65]
	v_mfma_f32_16x16x32_bf16 v[58:61], v[148:151], v[160:163], v[58:61]
	v_mfma_f32_16x16x32_bf16 v[54:57], v[140:143], v[168:171], v[54:57]
	v_mfma_f32_16x16x32_bf16 v[50:53], v[148:151], v[168:171], v[50:53]
	v_mfma_f32_16x16x32_bf16 v[38:41], v[140:143], v[176:179], v[38:41]
	v_mfma_f32_16x16x32_bf16 v[34:37], v[148:151], v[176:179], v[34:37]
	v_mfma_f32_16x16x32_bf16 v[22:25], v[140:143], v[184:187], v[22:25]
	v_mfma_f32_16x16x32_bf16 v[18:21], v[148:151], v[184:187], v[18:21]
	v_mfma_f32_16x16x32_bf16 v[62:65], v[144:147], v[164:167], v[62:65]
	v_mfma_f32_16x16x32_bf16 v[58:61], v[152:155], v[164:167], v[58:61]
	v_mfma_f32_16x16x32_bf16 v[54:57], v[144:147], v[172:175], v[54:57]
	v_mfma_f32_16x16x32_bf16 v[50:53], v[152:155], v[172:175], v[50:53]
	v_mfma_f32_16x16x32_bf16 v[38:41], v[144:147], v[180:183], v[38:41]
	v_mfma_f32_16x16x32_bf16 v[34:37], v[152:155], v[180:183], v[34:37]
	v_mfma_f32_16x16x32_bf16 v[22:25], v[144:147], v[188:191], v[22:25]
	v_mfma_f32_16x16x32_bf16 v[18:21], v[152:155], v[188:191], v[18:21]
	v_mfma_f32_16x16x32_bf16 v[46:49], v[192:195], v[160:163], v[46:49]
	v_mfma_f32_16x16x32_bf16 v[42:45], v[200:203], v[160:163], v[42:45]
	v_mfma_f32_16x16x32_bf16 v[30:33], v[192:195], v[168:171], v[30:33]
	v_mfma_f32_16x16x32_bf16 v[26:29], v[200:203], v[168:171], v[26:29]
	v_mfma_f32_16x16x32_bf16 v[14:17], v[192:195], v[176:179], v[14:17]
	v_mfma_f32_16x16x32_bf16 v[10:13], v[200:203], v[176:179], v[10:13]
	v_mfma_f32_16x16x32_bf16 v[6:9], v[192:195], v[184:187], v[6:9]
	v_mfma_f32_16x16x32_bf16 v[2:5], v[200:203], v[184:187], v[2:5]
	v_mfma_f32_16x16x32_bf16 v[46:49], v[196:199], v[164:167], v[46:49]
	v_mfma_f32_16x16x32_bf16 v[42:45], v[204:207], v[164:167], v[42:45]
	v_mfma_f32_16x16x32_bf16 v[30:33], v[196:199], v[172:175], v[30:33]
	v_mfma_f32_16x16x32_bf16 v[26:29], v[204:207], v[172:175], v[26:29]
	v_mfma_f32_16x16x32_bf16 v[14:17], v[196:199], v[180:183], v[14:17]
	v_mfma_f32_16x16x32_bf16 v[10:13], v[204:207], v[180:183], v[10:13]
	v_mfma_f32_16x16x32_bf16 v[6:9], v[196:199], v[188:191], v[6:9]
	v_mfma_f32_16x16x32_bf16 v[2:5], v[204:207], v[188:191], v[2:5]
	s_barrier
; #define PG8_STAGE(bufoff, gbase, voff) do { _Pragma("unroll") for (int _i = 0; _i < 2; ++_i) \
;         __builtin_amdgcn_global_load_lds((const unsigned*)((const char*)(gbase) + (voff)[_i]), (LAS unsigned*)(lds + (bufoff) + ldsw + _i * 8192), 16, 0, 0); } while (0)
; #define PG8_LDA(dst, b, h) do { _Pragma("unroll") for (int m = 0; m < 4; ++m) _Pragma("unroll") for (int k = 0; k < 2; ++k) dst[m][k] = *(const LAS bf16x8*)(lds + PG8_SA(b, h) + aoff + m * 2048 + k * 1024); } while (0)
; #define PG8_LDB(dst, b, h) do { _Pragma("unroll") for (int n = 0; n < 2; ++n) _Pragma("unroll") for (int k = 0; k < 2; ++k) dst[n][k] = *(const LAS bf16x8*)(lds + PG8_SB(b, h) + boff + n * 2048 + k * 1024); } while (0)
; #define PG8_MMA(ai, bj, At, Bt) do { __builtin_amdgcn_s_setprio(1); _Pragma("unroll") for (int m = 0; m < 4; ++m) _Pragma("unroll") for (int n = 0; n < 2; ++n) _Pragma("unroll") for (int k = 0; k < 2; ++k) \
;         acc[ai][bj][m][n] = __builtin_amdgcn_mfma_f32_16x16x32_bf16(Bt[n][k], At[m][k], acc[ai][bj][m][n], 0, 0, 0); __builtin_amdgcn_s_setprio(0); } while (0)
; #define PG8_WAIT_V(n) asm volatile("s_waitcnt vmcnt(" #n ")" ::: "memory")
; #define PG8_WAIT_L(n) asm volatile("s_waitcnt lgkmcnt(" #n ")" ::: "memory")
; #define PG8_BAR __builtin_amdgcn_s_barrier()
; #define PG8_SCHED __builtin_amdgcn_sched_barrier(0)
; template <class Epi, class Sched>
; __device__ __forceinline__ void gemm_phase(LAS unsigned char* lds, const Gemm g, const Sched& S, const Epi& E) {
;     ...
;             PG8_STAGE(PG8_SB(0, 1), b2 + hstep, voffB);
;             PG8_WAIT_V(6); PG8_BAR; PG8_MMA(1, 1, At, B1); PG8_BAR;
;             PG8_LDB(B0, 1, 0); PG8_SCHED; PG8_LDA(At, 1, 0); PG8_STAGE(PG8_SA(0, 1), a2 + hstep, voffA);
;             PG8_WAIT_L(8); PG8_BAR; PG8_WAIT_L(0); PG8_MMA(0, 0, At, B0); PG8_BAR; PG8_SCHED;
;             PG8_LDB(B1, 1, 1); PG8_STAGE(PG8_SB(1, 0), b3, voffB);
;             PG8_BAR; PG8_WAIT_L(0); PG8_MMA(0, 1, At, B1); PG8_BAR;
	s_add_u32 s38, s54, 0x200000
	s_addc_u32 s39, s55, 0
	s_add_i32 s50, s50, s63
	s_mov_b32 m0, s50
	s_nop 0
	global_load_lds_dwordx4 v0, s[38:39]
	s_add_i32 m0, s50, 0x2000
	s_nop 0
	global_load_lds_dwordx4 v130, s[38:39]
	s_add_u32 s38, s56, 0x200000
	s_addc_u32 s39, s57, 0
	s_mov_b32 m0, s64
	s_nop 0
	global_load_lds_dwordx4 v0, s[38:39]
	s_mov_b32 m0, s65
	s_nop 0
	global_load_lds_dwordx4 v130, s[38:39]
	s_add_i32 s50, 0, 0x18000
	ds_read_b128 v[140:143], v226 offset:32768
	ds_read_b128 v[144:147], v226 offset:33792
	ds_read_b128 v[148:151], v226 offset:34816
	ds_read_b128 v[152:155], v226 offset:35840
	ds_read_b128 v[160:163], v139 offset:32768
	ds_read_b128 v[164:167], v139 offset:33792
	ds_read_b128 v[168:171], v139 offset:34816
	ds_read_b128 v[172:175], v139 offset:35840
	ds_read_b128 v[176:179], v139 offset:36864
	ds_read_b128 v[180:183], v139 offset:37888
	ds_read_b128 v[184:187], v139 offset:38912
	ds_read_b128 v[188:191], v139 offset:39936
	s_add_i32 s51, 0, 0x1c000
	ds_read_b128 v[192:195], v226 offset:49152
	ds_read_b128 v[196:199], v226 offset:50176
	ds_read_b128 v[200:203], v226 offset:51200
	ds_read_b128 v[204:207], v226 offset:52224
	s_waitcnt lgkmcnt(4)
	s_barrier
	s_waitcnt lgkmcnt(0)
	v_mfma_f32_16x16x32_bf16 v[126:129], v[140:143], v[160:163], v[126:129]
	v_mfma_f32_16x16x32_bf16 v[122:125], v[148:151], v[160:163], v[122:125]
	v_mfma_f32_16x16x32_bf16 v[118:121], v[140:143], v[168:171], v[118:121]
	v_mfma_f32_16x16x32_bf16 v[114:117], v[148:151], v[168:171], v[114:117]
	v_mfma_f32_16x16x32_bf16 v[106:109], v[140:143], v[176:179], v[106:109]
	v_mfma_f32_16x16x32_bf16 v[98:101], v[148:151], v[176:179], v[98:101]
	v_mfma_f32_16x16x32_bf16 v[90:93], v[140:143], v[184:187], v[90:93]
	v_mfma_f32_16x16x32_bf16 v[82:85], v[148:151], v[184:187], v[82:85]
	v_mfma_f32_16x16x32_bf16 v[126:129], v[144:147], v[164:167], v[126:129]
	v_mfma_f32_16x16x32_bf16 v[122:125], v[152:155], v[164:167], v[122:125]
	v_mfma_f32_16x16x32_bf16 v[118:121], v[144:147], v[172:175], v[118:121]
	v_mfma_f32_16x16x32_bf16 v[114:117], v[152:155], v[172:175], v[114:117]
	v_mfma_f32_16x16x32_bf16 v[106:109], v[144:147], v[180:183], v[106:109]
	v_mfma_f32_16x16x32_bf16 v[98:101], v[152:155], v[180:183], v[98:101]
	v_mfma_f32_16x16x32_bf16 v[90:93], v[144:147], v[188:191], v[90:93]
	v_mfma_f32_16x16x32_bf16 v[82:85], v[152:155], v[188:191], v[82:85]
	v_mfma_f32_16x16x32_bf16 v[110:113], v[192:195], v[160:163], v[110:113]
	v_mfma_f32_16x16x32_bf16 v[102:105], v[200:203], v[160:163], v[102:105]
	v_mfma_f32_16x16x32_bf16 v[94:97], v[192:195], v[168:171], v[94:97]
	v_mfma_f32_16x16x32_bf16 v[86:89], v[200:203], v[168:171], v[86:89]
	v_mfma_f32_16x16x32_bf16 v[78:81], v[192:195], v[176:179], v[78:81]
	v_mfma_f32_16x16x32_bf16 v[74:77], v[200:203], v[176:179], v[74:77]
	v_mfma_f32_16x16x32_bf16 v[70:73], v[192:195], v[184:187], v[70:73]
	v_mfma_f32_16x16x32_bf16 v[66:69], v[200:203], v[184:187], v[66:69]
	v_mfma_f32_16x16x32_bf16 v[110:113], v[196:199], v[164:167], v[110:113]
	v_mfma_f32_16x16x32_bf16 v[102:105], v[204:207], v[164:167], v[102:105]
	v_mfma_f32_16x16x32_bf16 v[94:97], v[196:199], v[172:175], v[94:97]
	v_mfma_f32_16x16x32_bf16 v[86:89], v[204:207], v[172:175], v[86:89]
	v_mfma_f32_16x16x32_bf16 v[78:81], v[196:199], v[180:183], v[78:81]
	v_mfma_f32_16x16x32_bf16 v[74:77], v[204:207], v[180:183], v[74:77]
	v_mfma_f32_16x16x32_bf16 v[70:73], v[196:199], v[188:191], v[70:73]
	v_mfma_f32_16x16x32_bf16 v[66:69], v[204:207], v[188:191], v[66:69]
	s_barrier
	s_add_i32 s38, s50, s63
	s_add_u32 s100, s54, s36
	s_addc_u32 s101, s55, s37
	s_mov_b32 m0, s38
	s_nop 0
	global_load_lds_dwordx4 v0, s[100:101]
	s_add_i32 m0, s38, 0x2000
	s_nop 0
	global_load_lds_dwordx4 v130, s[100:101]
	s_mov_b32 m0, s66
	s_add_u32 s100, s56, s36
	s_addc_u32 s101, s57, s37
	global_load_lds_dwordx4 v0, s[100:101]
	s_mov_b32 m0, s67
	s_nop 0
	global_load_lds_dwordx4 v130, s[100:101]
	ds_read_b128 v[160:163], v139 offset:49152
	ds_read_b128 v[164:167], v139 offset:50176
	ds_read_b128 v[168:171], v139 offset:51200
	ds_read_b128 v[172:175], v139 offset:52224
	ds_read_b128 v[176:179], v139 offset:53248
	ds_read_b128 v[180:183], v139 offset:54272
	ds_read_b128 v[184:187], v139 offset:55296
	ds_read_b128 v[188:191], v139 offset:56320
	s_waitcnt vmcnt(4)
	s_waitcnt lgkmcnt(0)
	s_barrier
; #define PG8_STAGE(bufoff, gbase, voff) do { _Pragma("unroll") for (int _i = 0; _i < 2; ++_i) \
;         __builtin_amdgcn_global_load_lds((const unsigned*)((const char*)(gbase) + (voff)[_i]), (LAS unsigned*)(lds + (bufoff) + ldsw + _i * 8192), 16, 0, 0); } while (0)
; #define PG8_LDA(dst, b, h) do { _Pragma("unroll") for (int m = 0; m < 4; ++m) _Pragma("unroll") for (int k = 0; k < 2; ++k) dst[m][k] = *(const LAS bf16x8*)(lds + PG8_SA(b, h) + aoff + m * 2048 + k * 1024); } while (0)
; #define PG8_MMA(ai, bj, At, Bt) do { __builtin_amdgcn_s_setprio(1); _Pragma("unroll") for (int m = 0; m < 4; ++m) _Pragma("unroll") for (int n = 0; n < 2; ++n) _Pragma("unroll") for (int k = 0; k < 2; ++k) \
;         acc[ai][bj][m][n] = __builtin_amdgcn_mfma_f32_16x16x32_bf16(Bt[n][k], At[m][k], acc[ai][bj][m][n], 0, 0, 0); __builtin_amdgcn_s_setprio(0); } while (0)
; #define PG8_WAIT_V(n) asm volatile("s_waitcnt vmcnt(" #n ")" ::: "memory")
; #define PG8_WAIT_L(n) asm volatile("s_waitcnt lgkmcnt(" #n ")" ::: "memory")
; #define PG8_BAR __builtin_amdgcn_s_barrier()
; #define PG8_SCHED __builtin_amdgcn_sched_barrier(0)
;     __device__ __forceinline__ void operator()(const f32x4 (&acc)[2][2][4][2], const Unit& u, int wr, int wc, int fr, int fq) const {
;         const int row0 = u.pm * BM + wr * 64 + fr, col0 = u.pn * BM + wc * 32 + 4 * fq;
;         float* base = part + (size_t)u.ks * Mp * ldc;
; #pragma unroll
;         for (int ai = 0; ai < 2; ++ai)
; #pragma unroll
;             for (int m = 0; m < 4; ++m) { float* rowp = base + (size_t)(row0 + ai * HALF + m * 16) * ldc + col0;
; #pragma unroll
;                 for (int bj = 0; bj < 2; ++bj)
; #pragma unroll
;                     for (int n = 0; n < 2; ++n) *(f32x4*)(rowp + bj * HALF + n * 16) = acc[ai][bj][m][n]; }
; template <class Epi, class Sched>
; __device__ __forceinline__ void gemm_phase(LAS unsigned char* lds, const Gemm g, const Sched& S, const Epi& E) {
;     ...
;             PG8_LDA(At, 1, 1); PG8_STAGE(PG8_SA(1, 0), a3, voffA);
;             PG8_BAR; PG8_WAIT_L(0); PG8_MMA(1, 0, At, B0); PG8_BAR; PG8_SCHED;
;             PG8_STAGE(PG8_SB(1, 1), b3 + hstep, voffB);
;             PG8_WAIT_V(6); PG8_BAR; PG8_MMA(1, 1, At, B1); PG8_BAR;
;         }
;         E(acc, cur, wr, wc, fr, fq);
;         if (!has_next) break;
	v_mfma_f32_16x16x32_bf16 v[62:65], v[140:143], v[160:163], v[62:65]
	v_mfma_f32_16x16x32_bf16 v[58:61], v[148:151], v[160:163], v[58:61]
	v_mfma_f32_16x16x32_bf16 v[54:57], v[140:143], v[168:171], v[54:57]
	v_mfma_f32_16x16x32_bf16 v[50:53], v[148:151], v[168:171], v[50:53]
	v_mfma_f32_16x16x32_bf16 v[38:41], v[140:143], v[176:179], v[38:41]
	v_mfma_f32_16x16x32_bf16 v[34:37], v[148:151], v[176:179], v[34:37]
	v_mfma_f32_16x16x32_bf16 v[22:25], v[140:143], v[184:187], v[22:25]
	v_mfma_f32_16x16x32_bf16 v[18:21], v[148:151], v[184:187], v[18:21]
	v_mfma_f32_16x16x32_bf16 v[62:65], v[144:147], v[164:167], v[62:65]
	v_mfma_f32_16x16x32_bf16 v[58:61], v[152:155], v[164:167], v[58:61]
	v_mfma_f32_16x16x32_bf16 v[54:57], v[144:147], v[172:175], v[54:57]
	v_mfma_f32_16x16x32_bf16 v[50:53], v[152:155], v[172:175], v[50:53]
	v_mfma_f32_16x16x32_bf16 v[38:41], v[144:147], v[180:183], v[38:41]
	v_mfma_f32_16x16x32_bf16 v[34:37], v[152:155], v[180:183], v[34:37]
	v_mfma_f32_16x16x32_bf16 v[22:25], v[144:147], v[188:191], v[22:25]
	v_mfma_f32_16x16x32_bf16 v[18:21], v[152:155], v[188:191], v[18:21]
	s_add_u32 s38, s54, 0x200080
	s_addc_u32 s39, s55, 0
	s_add_i32 s50, s51, s63
	s_mov_b32 m0, s50
	s_nop 0
	global_load_lds_dwordx4 v0, s[38:39]
	s_add_i32 m0, s50, 0x2000
	s_nop 0
	global_load_lds_dwordx4 v130, s[38:39]
	v_mfma_f32_16x16x32_bf16 v[46:49], v[192:195], v[160:163], v[46:49]
	v_mfma_f32_16x16x32_bf16 v[42:45], v[200:203], v[160:163], v[42:45]
	v_mfma_f32_16x16x32_bf16 v[30:33], v[192:195], v[168:171], v[30:33]
	v_mfma_f32_16x16x32_bf16 v[26:29], v[200:203], v[168:171], v[26:29]
	v_mfma_f32_16x16x32_bf16 v[14:17], v[192:195], v[176:179], v[14:17]
	v_mfma_f32_16x16x32_bf16 v[10:13], v[200:203], v[176:179], v[10:13]
	v_mfma_f32_16x16x32_bf16 v[6:9], v[192:195], v[184:187], v[6:9]
	v_mfma_f32_16x16x32_bf16 v[2:5], v[200:203], v[184:187], v[2:5]
	v_mfma_f32_16x16x32_bf16 v[46:49], v[196:199], v[164:167], v[46:49]
	v_mfma_f32_16x16x32_bf16 v[42:45], v[204:207], v[164:167], v[42:45]
	v_mfma_f32_16x16x32_bf16 v[30:33], v[196:199], v[172:175], v[30:33]
	v_mfma_f32_16x16x32_bf16 v[26:29], v[204:207], v[172:175], v[26:29]
	v_mfma_f32_16x16x32_bf16 v[14:17], v[196:199], v[180:183], v[14:17]
	v_mfma_f32_16x16x32_bf16 v[10:13], v[204:207], v[180:183], v[10:13]
	v_mfma_f32_16x16x32_bf16 v[6:9], v[196:199], v[188:191], v[6:9]
	v_mfma_f32_16x16x32_bf16 v[2:5], v[204:207], v[188:191], v[2:5]
	s_add_i32 s71, s71, 2
	s_add_u32 s69, s69, 0x100
	s_addc_u32 s70, s70, 0
	s_cmp_gt_u32 s71, 29
	s_mov_b64 s[50:51], s[52:53]
	s_barrier
	s_cbranch_scc0 .LBB0_58
	s_ashr_i32 s11, s10, 31
	s_lshl_b64 s[10:11], s[10:11], 24
	v_lshl_or_b32 v140, s26, 8, v138
	s_add_u32 s10, s8, s10
	v_lshl_add_u32 v142, s24, 8, v136
	s_addc_u32 s11, s9, s11
	v_ashrrev_i32_e32 v141, 31, v140
	v_ashrrev_i32_e32 v143, 31, v142
	v_lshl_add_u64 v[140:141], v[140:141], 2, s[10:11]
	v_lshlrev_b64 v[144:145], 13, v[142:143]
	v_lshl_add_u64 v[144:145], v[140:141], 0, v[144:145]
	global_store_dwordx4 v[144:145], v[126:129], off
	global_store_dwordx4 v[144:145], v[122:125], off offset:64
	global_store_dwordx4 v[144:145], v[110:113], off offset:512
	global_store_dwordx4 v[144:145], v[102:105], off offset:576
	s_mov_b64 s[10:11], 0x100000
	s_mov_b32 s26, s40
	v_or_b32_e32 v102, 16, v142
	v_ashrrev_i32_e32 v103, 31, v102
	v_lshlrev_b64 v[102:103], 13, v[102:103]
	v_lshl_add_u64 v[102:103], v[140:141], 0, v[102:103]
	global_store_dwordx4 v[102:103], v[118:121], off
	global_store_dwordx4 v[102:103], v[114:117], off offset:64
	global_store_dwordx4 v[102:103], v[94:97], off offset:512
	global_store_dwordx4 v[102:103], v[86:89], off offset:576
	s_mov_b32 s24, s42
	s_mov_b64 s[52:53], s[48:49]
	v_or_b32_e32 v86, 32, v142
	v_ashrrev_i32_e32 v87, 31, v86
	v_lshlrev_b64 v[86:87], 13, v[86:87]
	v_lshl_add_u64 v[86:87], v[140:141], 0, v[86:87]
	global_store_dwordx4 v[86:87], v[106:109], off
	global_store_dwordx4 v[86:87], v[98:101], off offset:64
	global_store_dwordx4 v[86:87], v[78:81], off offset:512
	global_store_dwordx4 v[86:87], v[74:77], off offset:576
	s_mov_b64 s[50:51], s[46:47]
	s_nop 0
	v_or_b32_e32 v74, 48, v142
	v_ashrrev_i32_e32 v75, 31, v74
	v_lshlrev_b64 v[74:75], 13, v[74:75]
	v_lshl_add_u64 v[74:75], v[140:141], 0, v[74:75]
	global_store_dwordx4 v[74:75], v[90:93], off
	global_store_dwordx4 v[74:75], v[82:85], off offset:64
	global_store_dwordx4 v[74:75], v[70:73], off offset:512
	global_store_dwordx4 v[74:75], v[66:69], off offset:576
	s_nop 1
	v_add_co_u32_e32 v68, vcc, s93, v144
	v_lshl_add_u64 v[66:67], v[144:145], 0, s[10:11]
	s_nop 0
	v_addc_co_u32_e32 v69, vcc, 0, v145, vcc
	s_mov_b64 s[10:11], 0x120000
	global_store_dwordx4 v[68:69], v[62:65], off
	global_store_dwordx4 v[66:67], v[58:61], off offset:64
	global_store_dwordx4 v[66:67], v[46:49], off offset:512
	global_store_dwordx4 v[66:67], v[42:45], off offset:576
	s_nop 1
	v_lshl_add_u64 v[42:43], v[144:145], 0, s[10:11]
	s_mov_b32 s10, 0x120000
	v_add_co_u32_e32 v44, vcc, s10, v144
	s_mov_b64 s[10:11], 0x140000
	s_nop 0
	v_addc_co_u32_e32 v45, vcc, 0, v145, vcc
	global_store_dwordx4 v[44:45], v[54:57], off
	global_store_dwordx4 v[42:43], v[50:53], off offset:64
	global_store_dwordx4 v[42:43], v[30:33], off offset:512
	global_store_dwordx4 v[42:43], v[26:29], off offset:576
	s_nop 1
	v_lshl_add_u64 v[26:27], v[144:145], 0, s[10:11]
	s_mov_b32 s10, 0x140000
	v_add_co_u32_e32 v28, vcc, s10, v144
	s_mov_b64 s[10:11], 0x160000
	s_nop 0
	v_addc_co_u32_e32 v29, vcc, 0, v145, vcc
	global_store_dwordx4 v[28:29], v[38:41], off
	global_store_dwordx4 v[26:27], v[34:37], off offset:64
	global_store_dwordx4 v[26:27], v[14:17], off offset:512
	global_store_dwordx4 v[26:27], v[10:13], off offset:576
	s_nop 1
	v_add_co_u32_e32 v12, vcc, 0x160000, v144
	v_lshl_add_u64 v[10:11], v[144:145], 0, s[10:11]
	s_nop 0
	v_addc_co_u32_e32 v13, vcc, 0, v145, vcc
	s_and_b64 vcc, exec, s[44:45]
	s_mov_b32 s10, s28
	global_store_dwordx4 v[12:13], v[22:25], off
	global_store_dwordx4 v[10:11], v[18:21], off offset:64
	global_store_dwordx4 v[10:11], v[6:9], off offset:512
	global_store_dwordx4 v[10:11], v[2:5], off offset:576
	s_cbranch_vccz .LBB0_55
	s_waitcnt vmcnt(0)
	s_cmpk_gt_u32 s60, 0xff
	s_cbranch_scc1 .LBB0_62
	s_barrier

; __device__ __forceinline__ int tid_o() { int t = (int)threadIdx.x; asm volatile("" : "+v"(t)); return t; }
; #define PG8_STAGE(bufoff, gbase, voff) do { _Pragma("unroll") for (int _i = 0; _i < 2; ++_i) \
;         __builtin_amdgcn_global_load_lds((const unsigned*)((const char*)(gbase) + (voff)[_i]), (LAS unsigned*)(lds + (bufoff) + ldsw + _i * 8192), 16, 0, 0); } while (0)
; #define PG8_WAIT_V(n) asm volatile("s_waitcnt vmcnt(" #n ")" ::: "memory")
; #define PG8_BAR __builtin_amdgcn_s_barrier()
; template <class Epi, class Sched>
; __device__ __forceinline__ void gemm_phase(LAS unsigned char* lds, const Gemm g, const Sched& S, const Epi& E) {
;     const int tid = tid_o(), wid = __builtin_amdgcn_readfirstlane(tid >> 6), lane = tid & 63, wr = wid >> 2, wc = wid & 3, fr = lane & 15, fq = lane >> 4;
;     const int K = g.K, nt = K / BK;
;     unsigned voffA[2], voffB[2];
; #pragma unroll
;     for (int i = 0; i < 2; ++i) { int R, C; stage_rc(tid * 16 + i * 8192, R, C); const int Rb = Epi::PERM ? ((R & ~31) + perm32(R & 31)) : R;
;         voffA[i] = (unsigned)(R * g.ld + C) * 2u; voffB[i] = (unsigned)(Rb * g.ld + C) * 2u; }
;     const size_t kstep = (size_t)(BK * 2);
;     const size_t hstep = (size_t)HALF * g.ld * 2;
;     const size_t tstep = 2 * hstep, sstep = (size_t)K * 2;
;     const unsigned ldsw = (unsigned)wid * 1024u;
;     const int aoff = lds_byte(wr * 64 + fr, fq * 8), boff = lds_byte(wc * 32 + fr, fq * 8);
;     ...
;     const char* cA = (const char*)g.A + (size_t)cur.pm * tstep + (size_t)cur.ks * sstep; const char* cB = (const char*)g.Bt + (size_t)cur.pn * tstep + (size_t)cur.ks * sstep;
;     PG8_STAGE(PG8_SB(0, 0), cB, voffB); PG8_STAGE(PG8_SA(0, 0), cA, voffA); PG8_STAGE(PG8_SB(0, 1), cB + hstep, voffB); PG8_STAGE(PG8_SA(0, 1), cA + hstep, voffA);
;     if (wr == 1) PG8_BAR;
;     PG8_WAIT_V(4); PG8_BAR;
;     PG8_STAGE(PG8_SB(1, 0), cB + kstep, voffB); PG8_STAGE(PG8_SA(1, 0), cA + kstep, voffA); PG8_STAGE(PG8_SB(1, 1), cB + hstep + kstep, voffB);
;     PG8_WAIT_V(6); PG8_BAR;
.LBB0_69:
	s_waitcnt vmcnt(0)
	v_lshrrev_b32_e32 v18, 1, v16
	v_and_b32_e32 v18, 24, v18
	v_and_b32_e32 v17, 15, v16
	v_lshlrev_b32_e32 v19, 1, v18
	v_lshlrev_b32_e32 v16, 2, v16
	s_sext_i32_i16 s68, s26
	v_lshl_or_b32 v142, s28, 6, v17
	v_lshl_or_b32 v17, v17, 6, v19
	s_lshl_b32 s26, s28, 13
	v_and_b32_e32 v16, 32, v16
	v_bitop3_b32 v19, v17, s26, v16 bitop3:0xde
	s_lshl_b32 s26, s27, 5
	s_and_b32 s28, s26, 0x60
	s_add_i32 m0, s9, 0x18000
	v_lshl_add_u64 v[8:9], v[8:9], 0, s[36:37]
	s_lshl_b32 s26, s28, 7
	s_waitcnt vmcnt(4)
	s_barrier
	global_load_lds_dwordx4 v[8:9], off
	v_lshl_add_u64 v[6:7], v[6:7], 0, s[36:37]
	s_add_i32 m0, s9, 0x1a000
	s_add_i32 s64, s9, 0x8000
	s_add_i32 s65, s9, 0xa000
	v_bitop3_b32 v143, v17, s26, v16 bitop3:0xde
	v_add_u32_e32 v226, 0x10000, v143
	global_load_lds_dwordx4 v[6:7], off
	v_lshl_add_u64 v[4:5], v[4:5], 0, s[36:37]
	s_mov_b32 m0, s64
	s_add_u32 s26, s46, 0x80080
	global_load_lds_dwordx4 v[4:5], off
	v_lshl_add_u64 v[2:3], v[2:3], 0, s[36:37]
	s_mov_b32 m0, s65
	s_addc_u32 s27, s47, 0
	global_load_lds_dwordx4 v[2:3], off
	s_add_i32 m0, s9, 0x1c000
	v_lshl_add_u64 v[2:3], s[26:27], 0, v[0:1]
	global_load_lds_dwordx4 v[2:3], off
	v_lshl_add_u64 v[2:3], s[26:27], 0, v[130:131]
	s_add_i32 m0, s9, 0x1e000
	s_waitcnt lgkmcnt(0)
	s_ashr_i32 s66, s63, 31
	global_load_lds_dwordx4 v[2:3], off
	v_lshlrev_b32_e32 v2, 15, v10
	v_and_b32_e32 v2, 0xffff0000, v2
	v_lshl_add_u32 v2, v11, 12, v2
	v_and_b32_e32 v3, 1, v10
	v_lshl_or_b32 v2, v3, 6, v2
	v_lshl_add_u32 v136, v12, 1, v2
	v_lshlrev_b32_e32 v2, 15, v14
	v_and_b32_e32 v2, 0xffff0000, v2
	s_waitcnt vmcnt(6)
	v_lshl_add_u32 v2, v13, 12, v2
	v_and_b32_e32 v3, 1, v14
	v_lshl_or_b32 v2, v3, 6, v2
	v_or_b32_e32 v144, s28, v18
	v_mov_b32_e32 v137, v1
	v_lshl_add_u32 v138, v15, 1, v2
	v_mov_b32_e32 v139, v1
	s_mov_b32 s67, 0
	v_add_u32_e32 v145, 0, v19
	s_mov_b64 s[34:35], 0x1000000
	s_barrier

; #define PG8_STAGE(bufoff, gbase, voff) do { _Pragma("unroll") for (int _i = 0; _i < 2; ++_i) \
;         __builtin_amdgcn_global_load_lds((const unsigned*)((const char*)(gbase) + (voff)[_i]), (LAS unsigned*)(lds + (bufoff) + ldsw + _i * 8192), 16, 0, 0); } while (0)
; #define PG8_LDA(dst, b, h) do { _Pragma("unroll") for (int m = 0; m < 4; ++m) _Pragma("unroll") for (int k = 0; k < 2; ++k) dst[m][k] = *(const LAS bf16x8*)(lds + PG8_SA(b, h) + aoff + m * 2048 + k * 1024); } while (0)
; #define PG8_LDB(dst, b, h) do { _Pragma("unroll") for (int n = 0; n < 2; ++n) _Pragma("unroll") for (int k = 0; k < 2; ++k) dst[n][k] = *(const LAS bf16x8*)(lds + PG8_SB(b, h) + boff + n * 2048 + k * 1024); } while (0)
; #define PG8_WAIT_V(n) asm volatile("s_waitcnt vmcnt(" #n ")" ::: "memory")
; #define PG8_WAIT_L(n) asm volatile("s_waitcnt lgkmcnt(" #n ")" ::: "memory")
; #define PG8_BAR __builtin_amdgcn_s_barrier()
; #define PG8_SCHED __builtin_amdgcn_sched_barrier(0)
; template <class Epi, class Sched>
; __device__ __forceinline__ void gemm_phase(LAS unsigned char* lds, const Gemm g, const Sched& S, const Epi& E) {
;     ...
;         const bool has_next = S.next(ui + 1, nxt);
;         const char* nA = has_next ? (const char*)g.A + (size_t)nxt.pm * tstep + (size_t)nxt.ks * sstep : cA; const char* nB = has_next ? (const char*)g.Bt + (size_t)nxt.pn * tstep + (size_t)nxt.ks * sstep : cB;
;         for (int t = 0; t < nt; t += 2) {
;             const bool last = (t == nt - 2);
;             const char* a1 = cA + (size_t)(t + 1) * kstep;
;             const char* a2 = last ? nA : cA + (size_t)(t + 2) * kstep; const char* b2 = last ? nB : cB + (size_t)(t + 2) * kstep;
;             const char* a3 = a2 + kstep; const char* b3 = b2 + kstep;
;             PG8_LDB(B0, 0, 0); PG8_SCHED; PG8_LDA(At, 0, 0); PG8_STAGE(PG8_SA(1, 1), a1 + hstep, voffA);
;             PG8_WAIT_L(8); PG8_BAR; PG8_WAIT_L(0); PG8_MMA(0, 0, At, B0); PG8_BAR; PG8_SCHED;
;             PG8_LDB(B1, 0, 1); PG8_STAGE(PG8_SB(0, 0), b2, voffB);
;             PG8_BAR; PG8_WAIT_L(0); PG8_MMA(0, 1, At, B1); PG8_BAR;
;             PG8_LDA(At, 0, 1); PG8_STAGE(PG8_SA(0, 0), a2, voffA);
;             PG8_BAR; PG8_WAIT_L(0); PG8_MMA(1, 0, At, B0); PG8_BAR; PG8_SCHED;
;             PG8_STAGE(PG8_SB(0, 1), b2 + hstep, voffB);
;             PG8_WAIT_V(6); PG8_BAR; PG8_MMA(1, 1, At, B1); PG8_BAR;
.LBB0_73:
	s_add_u32 s38, s46, 0xfff80080
	s_addc_u32 s39, s47, -1
	s_cmp_eq_u32 s73, 28
	s_cselect_b32 s51, s29, s39
	s_cselect_b32 s50, s69, s38
	s_cselect_b32 s49, s27, s72
	s_cselect_b32 s48, s70, s71
	s_add_i32 m0, s9, 0xc000
	s_nop 0
	global_load_lds_dwordx4 v138, s[46:47]
	s_add_i32 m0, s9, 0xe000
	s_nop 0
	global_load_lds_dwordx4 v136, s[46:47]
	s_add_i32 s74, 0, 0x10000
	ds_read_b128 v[146:149], v226
	ds_read_b128 v[150:153], v226 offset:1024
	ds_read_b128 v[154:157], v226 offset:2048
	ds_read_b128 v[160:163], v226 offset:3072
	ds_read_b128 v[164:167], v145
	ds_read_b128 v[168:171], v145 offset:1024
	ds_read_b128 v[172:175], v145 offset:2048
	ds_read_b128 v[176:179], v145 offset:3072
	ds_read_b128 v[180:183], v145 offset:4096
	ds_read_b128 v[184:187], v145 offset:5120
	ds_read_b128 v[188:191], v145 offset:6144
	ds_read_b128 v[192:195], v145 offset:7168
	s_add_i32 s75, 0, 0x14000
	ds_read_b128 v[196:199], v226 offset:16384
	ds_read_b128 v[200:203], v226 offset:17408
	ds_read_b128 v[204:207], v226 offset:18432
	ds_read_b128 v[210:213], v226 offset:19456
	s_waitcnt lgkmcnt(4)
	s_barrier
	s_waitcnt lgkmcnt(0)
	v_mfma_f32_16x16x32_bf16 v[126:129], v[146:149], v[164:167], v[126:129]
	v_mfma_f32_16x16x32_bf16 v[122:125], v[154:157], v[164:167], v[122:125]
	v_mfma_f32_16x16x32_bf16 v[110:113], v[146:149], v[172:175], v[110:113]
	v_mfma_f32_16x16x32_bf16 v[106:109], v[154:157], v[172:175], v[106:109]
	v_mfma_f32_16x16x32_bf16 v[94:97], v[146:149], v[180:183], v[94:97]
	v_mfma_f32_16x16x32_bf16 v[90:93], v[154:157], v[180:183], v[90:93]
	v_mfma_f32_16x16x32_bf16 v[78:81], v[146:149], v[188:191], v[78:81]
	v_mfma_f32_16x16x32_bf16 v[74:77], v[154:157], v[188:191], v[74:77]
	v_mfma_f32_16x16x32_bf16 v[126:129], v[150:153], v[168:171], v[126:129]
	v_mfma_f32_16x16x32_bf16 v[122:125], v[160:163], v[168:171], v[122:125]
	v_mfma_f32_16x16x32_bf16 v[110:113], v[150:153], v[176:179], v[110:113]
	v_mfma_f32_16x16x32_bf16 v[106:109], v[160:163], v[176:179], v[106:109]
	v_mfma_f32_16x16x32_bf16 v[94:97], v[150:153], v[184:187], v[94:97]
	v_mfma_f32_16x16x32_bf16 v[90:93], v[160:163], v[184:187], v[90:93]
	v_mfma_f32_16x16x32_bf16 v[78:81], v[150:153], v[192:195], v[78:81]
	v_mfma_f32_16x16x32_bf16 v[74:77], v[160:163], v[192:195], v[74:77]
	v_mfma_f32_16x16x32_bf16 v[118:121], v[196:199], v[164:167], v[118:121]
	v_mfma_f32_16x16x32_bf16 v[114:117], v[204:207], v[164:167], v[114:117]
	v_mfma_f32_16x16x32_bf16 v[102:105], v[196:199], v[172:175], v[102:105]
	v_mfma_f32_16x16x32_bf16 v[98:101], v[204:207], v[172:175], v[98:101]
	v_mfma_f32_16x16x32_bf16 v[86:89], v[196:199], v[180:183], v[86:89]
	v_mfma_f32_16x16x32_bf16 v[82:85], v[204:207], v[180:183], v[82:85]
	v_mfma_f32_16x16x32_bf16 v[70:73], v[196:199], v[188:191], v[70:73]
	v_mfma_f32_16x16x32_bf16 v[66:69], v[204:207], v[188:191], v[66:69]
	v_mfma_f32_16x16x32_bf16 v[118:121], v[200:203], v[168:171], v[118:121]
	v_mfma_f32_16x16x32_bf16 v[114:117], v[210:213], v[168:171], v[114:117]
	v_mfma_f32_16x16x32_bf16 v[102:105], v[200:203], v[176:179], v[102:105]
	v_mfma_f32_16x16x32_bf16 v[98:101], v[210:213], v[176:179], v[98:101]
	v_mfma_f32_16x16x32_bf16 v[86:89], v[200:203], v[184:187], v[86:89]
	v_mfma_f32_16x16x32_bf16 v[82:85], v[210:213], v[184:187], v[82:85]
	v_mfma_f32_16x16x32_bf16 v[70:73], v[200:203], v[192:195], v[70:73]
	v_mfma_f32_16x16x32_bf16 v[66:69], v[210:213], v[192:195], v[66:69]
	s_barrier
	s_add_i32 s38, s74, s56
	s_mov_b32 m0, s38
	s_nop 0
	global_load_lds_dwordx4 v0, s[48:49]
	s_add_i32 m0, s38, 0x2000
	s_nop 0
	global_load_lds_dwordx4 v130, s[48:49]
	s_mov_b32 m0, s9
	s_nop 0
	global_load_lds_dwordx4 v134, s[50:51]
	s_mov_b32 m0, s60
	s_nop 0
	global_load_lds_dwordx4 v132, s[50:51]
	ds_read_b128 v[164:167], v145 offset:16384
	ds_read_b128 v[168:171], v145 offset:17408
	ds_read_b128 v[172:175], v145 offset:18432
	ds_read_b128 v[176:179], v145 offset:19456
	ds_read_b128 v[180:183], v145 offset:20480
	ds_read_b128 v[184:187], v145 offset:21504
	ds_read_b128 v[188:191], v145 offset:22528
	ds_read_b128 v[192:195], v145 offset:23552
	s_waitcnt vmcnt(4)
	s_waitcnt lgkmcnt(0)
	s_barrier
	v_mfma_f32_16x16x32_bf16 v[62:65], v[146:149], v[164:167], v[62:65]
	v_mfma_f32_16x16x32_bf16 v[58:61], v[154:157], v[164:167], v[58:61]
	v_mfma_f32_16x16x32_bf16 v[46:49], v[146:149], v[172:175], v[46:49]
	v_mfma_f32_16x16x32_bf16 v[42:45], v[154:157], v[172:175], v[42:45]
	v_mfma_f32_16x16x32_bf16 v[30:33], v[146:149], v[180:183], v[30:33]
	v_mfma_f32_16x16x32_bf16 v[26:29], v[154:157], v[180:183], v[26:29]
	v_mfma_f32_16x16x32_bf16 v[14:17], v[146:149], v[188:191], v[14:17]
	v_mfma_f32_16x16x32_bf16 v[10:13], v[154:157], v[188:191], v[10:13]
	v_mfma_f32_16x16x32_bf16 v[62:65], v[150:153], v[168:171], v[62:65]
	v_mfma_f32_16x16x32_bf16 v[58:61], v[160:163], v[168:171], v[58:61]
	v_mfma_f32_16x16x32_bf16 v[46:49], v[150:153], v[176:179], v[46:49]
	v_mfma_f32_16x16x32_bf16 v[42:45], v[160:163], v[176:179], v[42:45]
	v_mfma_f32_16x16x32_bf16 v[30:33], v[150:153], v[184:187], v[30:33]
	v_mfma_f32_16x16x32_bf16 v[26:29], v[160:163], v[184:187], v[26:29]
	v_mfma_f32_16x16x32_bf16 v[14:17], v[150:153], v[192:195], v[14:17]
	v_mfma_f32_16x16x32_bf16 v[10:13], v[160:163], v[192:195], v[10:13]
	v_mfma_f32_16x16x32_bf16 v[54:57], v[196:199], v[164:167], v[54:57]
	v_mfma_f32_16x16x32_bf16 v[50:53], v[204:207], v[164:167], v[50:53]
	v_mfma_f32_16x16x32_bf16 v[38:41], v[196:199], v[172:175], v[38:41]
	v_mfma_f32_16x16x32_bf16 v[34:37], v[204:207], v[172:175], v[34:37]
	v_mfma_f32_16x16x32_bf16 v[22:25], v[196:199], v[180:183], v[22:25]
	v_mfma_f32_16x16x32_bf16 v[18:21], v[204:207], v[180:183], v[18:21]
	v_mfma_f32_16x16x32_bf16 v[6:9], v[196:199], v[188:191], v[6:9]
	v_mfma_f32_16x16x32_bf16 v[2:5], v[204:207], v[188:191], v[2:5]
	v_mfma_f32_16x16x32_bf16 v[54:57], v[200:203], v[168:171], v[54:57]
	v_mfma_f32_16x16x32_bf16 v[50:53], v[210:213], v[168:171], v[50:53]
	v_mfma_f32_16x16x32_bf16 v[38:41], v[200:203], v[176:179], v[38:41]
	v_mfma_f32_16x16x32_bf16 v[34:37], v[210:213], v[176:179], v[34:37]
	v_mfma_f32_16x16x32_bf16 v[22:25], v[200:203], v[184:187], v[22:25]
	v_mfma_f32_16x16x32_bf16 v[18:21], v[210:213], v[184:187], v[18:21]
	v_mfma_f32_16x16x32_bf16 v[6:9], v[200:203], v[192:195], v[6:9]
	v_mfma_f32_16x16x32_bf16 v[2:5], v[210:213], v[192:195], v[2:5]
	s_barrier
; #define PG8_STAGE(bufoff, gbase, voff) do { _Pragma("unroll") for (int _i = 0; _i < 2; ++_i) \
;         __builtin_amdgcn_global_load_lds((const unsigned*)((const char*)(gbase) + (voff)[_i]), (LAS unsigned*)(lds + (bufoff) + ldsw + _i * 8192), 16, 0, 0); } while (0)
; #define PG8_LDA(dst, b, h) do { _Pragma("unroll") for (int m = 0; m < 4; ++m) _Pragma("unroll") for (int k = 0; k < 2; ++k) dst[m][k] = *(const LAS bf16x8*)(lds + PG8_SA(b, h) + aoff + m * 2048 + k * 1024); } while (0)
; #define PG8_LDB(dst, b, h) do { _Pragma("unroll") for (int n = 0; n < 2; ++n) _Pragma("unroll") for (int k = 0; k < 2; ++k) dst[n][k] = *(const LAS bf16x8*)(lds + PG8_SB(b, h) + boff + n * 2048 + k * 1024); } while (0)
; #define PG8_MMA(ai, bj, At, Bt) do { __builtin_amdgcn_s_setprio(1); _Pragma("unroll") for (int m = 0; m < 4; ++m) _Pragma("unroll") for (int n = 0; n < 2; ++n) _Pragma("unroll") for (int k = 0; k < 2; ++k) \
;         acc[ai][bj][m][n] = __builtin_amdgcn_mfma_f32_16x16x32_bf16(Bt[n][k], At[m][k], acc[ai][bj][m][n], 0, 0, 0); __builtin_amdgcn_s_setprio(0); } while (0)
; #define PG8_WAIT_V(n) asm volatile("s_waitcnt vmcnt(" #n ")" ::: "memory")
; #define PG8_WAIT_L(n) asm volatile("s_waitcnt lgkmcnt(" #n ")" ::: "memory")
; #define PG8_BAR __builtin_amdgcn_s_barrier()
; #define PG8_SCHED __builtin_amdgcn_sched_barrier(0)
; template <class Epi, class Sched>
; __device__ __forceinline__ void gemm_phase(LAS unsigned char* lds, const Gemm g, const Sched& S, const Epi& E) {
;     ...
;             PG8_STAGE(PG8_SB(0, 1), b2 + hstep, voffB);
;             PG8_WAIT_V(6); PG8_BAR; PG8_MMA(1, 1, At, B1); PG8_BAR;
;             PG8_LDB(B0, 1, 0); PG8_SCHED; PG8_LDA(At, 1, 0); PG8_STAGE(PG8_SA(0, 1), a2 + hstep, voffA);
;             PG8_WAIT_L(8); PG8_BAR; PG8_WAIT_L(0); PG8_MMA(0, 0, At, B0); PG8_BAR; PG8_SCHED;
;             PG8_LDB(B1, 1, 1); PG8_STAGE(PG8_SB(1, 0), b3, voffB);
;             PG8_BAR; PG8_WAIT_L(0); PG8_MMA(0, 1, At, B1); PG8_BAR;
;             PG8_LDA(At, 1, 1); PG8_STAGE(PG8_SA(1, 0), a3, voffA);
;             PG8_BAR; PG8_WAIT_L(0); PG8_MMA(1, 0, At, B0); PG8_BAR; PG8_SCHED;
;             PG8_STAGE(PG8_SB(1, 1), b3 + hstep, voffB);
;             PG8_WAIT_V(6); PG8_BAR; PG8_MMA(1, 1, At, B1); PG8_BAR;
	s_add_u32 s38, s48, 0x80000
	s_addc_u32 s39, s49, 0
	s_add_i32 s74, s75, s56
	s_mov_b32 m0, s74
	s_nop 0
	global_load_lds_dwordx4 v0, s[38:39]
	s_add_i32 m0, s74, 0x2000
	s_nop 0
	global_load_lds_dwordx4 v130, s[38:39]
	s_add_u32 s38, s50, 0x80000
	s_addc_u32 s39, s51, 0
	s_mov_b32 m0, s61
	s_nop 0
	global_load_lds_dwordx4 v134, s[38:39]
	s_mov_b32 m0, s62
	s_nop 0
	global_load_lds_dwordx4 v132, s[38:39]
	s_add_i32 s74, 0, 0x18000
	ds_read_b128 v[146:149], v226 offset:32768
	ds_read_b128 v[150:153], v226 offset:33792
	ds_read_b128 v[154:157], v226 offset:34816
	ds_read_b128 v[160:163], v226 offset:35840
	ds_read_b128 v[164:167], v145 offset:32768
	ds_read_b128 v[168:171], v145 offset:33792
	ds_read_b128 v[172:175], v145 offset:34816
	ds_read_b128 v[176:179], v145 offset:35840
	ds_read_b128 v[180:183], v145 offset:36864
	ds_read_b128 v[184:187], v145 offset:37888
	ds_read_b128 v[188:191], v145 offset:38912
	ds_read_b128 v[192:195], v145 offset:39936
	s_nop 0
	ds_read_b128 v[196:199], v226 offset:49152
	ds_read_b128 v[200:203], v226 offset:50176
	ds_read_b128 v[204:207], v226 offset:51200
	ds_read_b128 v[210:213], v226 offset:52224
	s_waitcnt lgkmcnt(4)
	s_barrier
	s_waitcnt lgkmcnt(0)
	v_mfma_f32_16x16x32_bf16 v[126:129], v[146:149], v[164:167], v[126:129]
	v_mfma_f32_16x16x32_bf16 v[122:125], v[154:157], v[164:167], v[122:125]
	v_mfma_f32_16x16x32_bf16 v[110:113], v[146:149], v[172:175], v[110:113]
	v_mfma_f32_16x16x32_bf16 v[106:109], v[154:157], v[172:175], v[106:109]
	v_mfma_f32_16x16x32_bf16 v[94:97], v[146:149], v[180:183], v[94:97]
	v_mfma_f32_16x16x32_bf16 v[90:93], v[154:157], v[180:183], v[90:93]
	v_mfma_f32_16x16x32_bf16 v[78:81], v[146:149], v[188:191], v[78:81]
	v_mfma_f32_16x16x32_bf16 v[74:77], v[154:157], v[188:191], v[74:77]
	v_mfma_f32_16x16x32_bf16 v[126:129], v[150:153], v[168:171], v[126:129]
	v_mfma_f32_16x16x32_bf16 v[122:125], v[160:163], v[168:171], v[122:125]
	v_mfma_f32_16x16x32_bf16 v[110:113], v[150:153], v[176:179], v[110:113]
	v_mfma_f32_16x16x32_bf16 v[106:109], v[160:163], v[176:179], v[106:109]
	v_mfma_f32_16x16x32_bf16 v[94:97], v[150:153], v[184:187], v[94:97]
	v_mfma_f32_16x16x32_bf16 v[90:93], v[160:163], v[184:187], v[90:93]
	v_mfma_f32_16x16x32_bf16 v[78:81], v[150:153], v[192:195], v[78:81]
	v_mfma_f32_16x16x32_bf16 v[74:77], v[160:163], v[192:195], v[74:77]
	v_mfma_f32_16x16x32_bf16 v[118:121], v[196:199], v[164:167], v[118:121]
	v_mfma_f32_16x16x32_bf16 v[114:117], v[204:207], v[164:167], v[114:117]
	v_mfma_f32_16x16x32_bf16 v[102:105], v[196:199], v[172:175], v[102:105]
	v_mfma_f32_16x16x32_bf16 v[98:101], v[204:207], v[172:175], v[98:101]
	v_mfma_f32_16x16x32_bf16 v[86:89], v[196:199], v[180:183], v[86:89]
	v_mfma_f32_16x16x32_bf16 v[82:85], v[204:207], v[180:183], v[82:85]
	v_mfma_f32_16x16x32_bf16 v[70:73], v[196:199], v[188:191], v[70:73]
	v_mfma_f32_16x16x32_bf16 v[66:69], v[204:207], v[188:191], v[66:69]
	v_mfma_f32_16x16x32_bf16 v[118:121], v[200:203], v[168:171], v[118:121]
	v_mfma_f32_16x16x32_bf16 v[114:117], v[210:213], v[168:171], v[114:117]
	v_mfma_f32_16x16x32_bf16 v[102:105], v[200:203], v[176:179], v[102:105]
	v_mfma_f32_16x16x32_bf16 v[98:101], v[210:213], v[176:179], v[98:101]
	v_mfma_f32_16x16x32_bf16 v[86:89], v[200:203], v[184:187], v[86:89]
	v_mfma_f32_16x16x32_bf16 v[82:85], v[210:213], v[184:187], v[82:85]
	v_mfma_f32_16x16x32_bf16 v[70:73], v[200:203], v[192:195], v[70:73]
	v_mfma_f32_16x16x32_bf16 v[66:69], v[210:213], v[192:195], v[66:69]
	s_barrier
	s_add_i32 s38, s74, s56
	s_add_u32 s100, s48, s36
	s_addc_u32 s101, s49, s37
	s_mov_b32 m0, s38
	s_nop 0
	global_load_lds_dwordx4 v0, s[100:101]
	s_add_i32 m0, s38, 0x2000
	s_nop 0
	global_load_lds_dwordx4 v130, s[100:101]
	s_mov_b32 m0, s64
	s_add_u32 s100, s50, s36
	s_addc_u32 s101, s51, s37
	global_load_lds_dwordx4 v134, s[100:101]
	s_mov_b32 m0, s65
	s_nop 0
	global_load_lds_dwordx4 v132, s[100:101]
	ds_read_b128 v[164:167], v145 offset:49152
	ds_read_b128 v[168:171], v145 offset:50176
	ds_read_b128 v[172:175], v145 offset:51200
	ds_read_b128 v[176:179], v145 offset:52224
	ds_read_b128 v[180:183], v145 offset:53248
	ds_read_b128 v[184:187], v145 offset:54272
	ds_read_b128 v[188:191], v145 offset:55296
	ds_read_b128 v[192:195], v145 offset:56320
	s_waitcnt vmcnt(4)
	s_waitcnt lgkmcnt(0)
	s_barrier
	v_mfma_f32_16x16x32_bf16 v[62:65], v[146:149], v[164:167], v[62:65]
	v_mfma_f32_16x16x32_bf16 v[58:61], v[154:157], v[164:167], v[58:61]
	v_mfma_f32_16x16x32_bf16 v[46:49], v[146:149], v[172:175], v[46:49]
	v_mfma_f32_16x16x32_bf16 v[42:45], v[154:157], v[172:175], v[42:45]
	v_mfma_f32_16x16x32_bf16 v[30:33], v[146:149], v[180:183], v[30:33]
	v_mfma_f32_16x16x32_bf16 v[26:29], v[154:157], v[180:183], v[26:29]
	v_mfma_f32_16x16x32_bf16 v[14:17], v[146:149], v[188:191], v[14:17]
	v_mfma_f32_16x16x32_bf16 v[10:13], v[154:157], v[188:191], v[10:13]
	v_mfma_f32_16x16x32_bf16 v[62:65], v[150:153], v[168:171], v[62:65]
	v_mfma_f32_16x16x32_bf16 v[58:61], v[160:163], v[168:171], v[58:61]
	v_mfma_f32_16x16x32_bf16 v[46:49], v[150:153], v[176:179], v[46:49]
	v_mfma_f32_16x16x32_bf16 v[42:45], v[160:163], v[176:179], v[42:45]
	v_mfma_f32_16x16x32_bf16 v[30:33], v[150:153], v[184:187], v[30:33]
	v_mfma_f32_16x16x32_bf16 v[26:29], v[160:163], v[184:187], v[26:29]
	v_mfma_f32_16x16x32_bf16 v[14:17], v[150:153], v[192:195], v[14:17]
	v_mfma_f32_16x16x32_bf16 v[10:13], v[160:163], v[192:195], v[10:13]
	s_add_u32 s38, s48, 0x80080
	s_addc_u32 s39, s49, 0
	s_add_i32 s48, s56, 0x1c000
	s_mov_b32 m0, s48
	s_nop 0
	global_load_lds_dwordx4 v0, s[38:39]
	s_add_i32 m0, s48, 0x2000
	s_nop 0
	global_load_lds_dwordx4 v130, s[38:39]
	v_mfma_f32_16x16x32_bf16 v[54:57], v[196:199], v[164:167], v[54:57]
	v_mfma_f32_16x16x32_bf16 v[50:53], v[204:207], v[164:167], v[50:53]
	v_mfma_f32_16x16x32_bf16 v[38:41], v[196:199], v[172:175], v[38:41]
	v_mfma_f32_16x16x32_bf16 v[34:37], v[204:207], v[172:175], v[34:37]
	v_mfma_f32_16x16x32_bf16 v[22:25], v[196:199], v[180:183], v[22:25]
	v_mfma_f32_16x16x32_bf16 v[18:21], v[204:207], v[180:183], v[18:21]
	v_mfma_f32_16x16x32_bf16 v[6:9], v[196:199], v[188:191], v[6:9]
	v_mfma_f32_16x16x32_bf16 v[2:5], v[204:207], v[188:191], v[2:5]
	v_mfma_f32_16x16x32_bf16 v[54:57], v[200:203], v[168:171], v[54:57]
	v_mfma_f32_16x16x32_bf16 v[50:53], v[210:213], v[168:171], v[50:53]
	v_mfma_f32_16x16x32_bf16 v[38:41], v[200:203], v[176:179], v[38:41]
	v_mfma_f32_16x16x32_bf16 v[34:37], v[210:213], v[176:179], v[34:37]
	v_mfma_f32_16x16x32_bf16 v[22:25], v[200:203], v[184:187], v[22:25]
	v_mfma_f32_16x16x32_bf16 v[18:21], v[210:213], v[184:187], v[18:21]
	v_mfma_f32_16x16x32_bf16 v[6:9], v[200:203], v[192:195], v[6:9]
	v_mfma_f32_16x16x32_bf16 v[2:5], v[210:213], v[192:195], v[2:5]
	s_add_i32 s73, s73, 2
	s_add_u32 s71, s71, 0x100
	s_addc_u32 s72, s72, 0
	s_add_u32 s46, s46, 0x100
	s_addc_u32 s47, s47, 0
	s_cmp_gt_u32 s73, 29
	s_barrier
; __device__ __forceinline__ unsigned cvt_pk_bf16(float lo, float hi) { unsigned r; asm("v_cvt_pk_bf16_f32 %0, %1, %2" : "=v"(r) : "v"(lo), "v"(hi)); return r; }
;     __device__ __forceinline__ void operator()(const f32x4 (&acc)[2][2][4][2], const Unit& u, int wr, int wc, int fr, int fq) const {
;         const int row0 = u.pm * BM + wr * 64 + fr, col0 = u.pn * BM + wc * 32 + 8 * fq;
; #pragma unroll
;         for (int ai = 0; ai < 2; ++ai)
; #pragma unroll
;             for (int m = 0; m < 4; ++m) { bf16_t* rowp = O + (size_t)(row0 + ai * HALF + m * 16) * ldc + col0;
; #pragma unroll
;                 for (int bj = 0; bj < 2; ++bj) { f32x4 v0 = acc[ai][bj][m][0], v1 = acc[ai][bj][m][1];
;                     if (ACT == 1) {
; #pragma unroll
;                         for (int j = 0; j < 4; ++j) { float a = fmaxf(v0[j], 0.f), b = fmaxf(v1[j], 0.f); v0[j] = a * a; v1[j] = b * b; } }
;                     u32x4 w; w.x = cvt_pk_bf16(v0[0], v0[1]); w.y = cvt_pk_bf16(v0[2], v0[3]); w.z = cvt_pk_bf16(v1[0], v1[1]); w.w = cvt_pk_bf16(v1[2], v1[3]);
;                     if (ACT == 1) __builtin_nontemporal_store(w, (u32x4*)(rowp + bj * HALF));
;                     else *(u32x4*)(rowp + bj * HALF) = w; } }
	s_cbranch_scc0 .LBB0_73
	v_lshl_add_u32 v146, s8, 8, v142
	v_max_f32_e32 v122, v122, v122
	v_ashrrev_i32_e32 v147, 31, v146
	v_max_f32_e32 v122, 0, v122
	v_max_f32_e32 v123, v123, v123
	v_max_f32_e32 v124, v124, v124
	v_lshl_or_b32 v140, s68, 8, v144
	v_lshlrev_b64 v[148:149], 14, v[146:147]
	v_mul_f32_e32 v147, v122, v122
	v_max_f32_e32 v122, v127, v127
	v_max_f32_e32 v123, 0, v123
	v_max_f32_e32 v124, 0, v124
	v_ashrrev_i32_e32 v141, 31, v140
	v_max_f32_e32 v126, v126, v126
	v_max_f32_e32 v122, 0, v122
	v_mul_f32_e32 v127, v123, v123
	v_max_f32_e32 v123, v128, v128
	v_mul_f32_e32 v128, v124, v124
	v_max_f32_e32 v124, v129, v129
	v_max_f32_e32 v125, v125, v125
	v_lshl_add_u64 v[148:149], s[24:25], 0, v[148:149]
	v_lshlrev_b64 v[150:151], 1, v[140:141]
	v_max_f32_e32 v126, 0, v126
	v_mul_f32_e32 v122, v122, v122
	v_max_f32_e32 v123, 0, v123
	v_max_f32_e32 v124, 0, v124
	v_max_f32_e32 v125, 0, v125
	v_max_f32_e32 v114, v114, v114
	v_lshl_add_u64 v[140:141], v[148:149], 0, v[150:151]
	v_mul_f32_e32 v126, v126, v126
	v_mul_f32_e32 v123, v123, v123
	v_mul_f32_e32 v124, v124, v124
	v_mul_f32_e32 v125, v125, v125
	v_cvt_pk_bf16_f32 v122, v126, v122
	v_max_f32_e32 v114, 0, v114
	v_max_f32_e32 v115, v115, v115
	v_max_f32_e32 v116, v116, v116
	v_cvt_pk_bf16_f32 v123, v123, v124
	v_cvt_pk_bf16_f32 v124, v147, v127
	v_cvt_pk_bf16_f32 v125, v128, v125
	global_store_dwordx4 v[140:141], v[122:125], off nt
	v_max_f32_e32 v115, 0, v115
	v_max_f32_e32 v116, 0, v116
	v_mul_f32_e32 v122, v114, v114
	v_max_f32_e32 v114, v119, v119
	v_max_f32_e32 v118, v118, v118
	v_max_f32_e32 v114, 0, v114
	v_mul_f32_e32 v119, v115, v115
	v_max_f32_e32 v115, v120, v120
	v_mul_f32_e32 v120, v116, v116
	v_max_f32_e32 v116, v121, v121
	v_max_f32_e32 v117, v117, v117
	v_max_f32_e32 v118, 0, v118
	v_mul_f32_e32 v114, v114, v114
	v_max_f32_e32 v115, 0, v115
	v_max_f32_e32 v116, 0, v116
	v_max_f32_e32 v117, 0, v117
	v_mul_f32_e32 v118, v118, v118
	v_mul_f32_e32 v115, v115, v115
	v_mul_f32_e32 v116, v116, v116
	v_mul_f32_e32 v117, v117, v117
	v_cvt_pk_bf16_f32 v114, v118, v114
	v_max_f32_e32 v106, v106, v106
	v_cvt_pk_bf16_f32 v115, v115, v116
	v_cvt_pk_bf16_f32 v116, v122, v119
	v_cvt_pk_bf16_f32 v117, v120, v117
	global_store_dwordx4 v[140:141], v[114:117], off offset:256 nt
	v_max_f32_e32 v106, 0, v106
	v_max_f32_e32 v107, v107, v107
	v_or_b32_e32 v114, 16, v146
	v_max_f32_e32 v108, v108, v108
	v_ashrrev_i32_e32 v115, 31, v114
	v_mul_f32_e32 v116, v106, v106
	v_max_f32_e32 v106, v111, v111
	v_max_f32_e32 v107, 0, v107
	v_max_f32_e32 v108, 0, v108
	v_lshlrev_b64 v[114:115], 14, v[114:115]
	v_max_f32_e32 v110, v110, v110
	v_max_f32_e32 v106, 0, v106
	v_mul_f32_e32 v111, v107, v107
	v_max_f32_e32 v107, v112, v112
	v_mul_f32_e32 v112, v108, v108
	v_max_f32_e32 v108, v113, v113
	v_max_f32_e32 v109, v109, v109
	v_lshl_add_u64 v[114:115], s[24:25], 0, v[114:115]
	v_max_f32_e32 v110, 0, v110
	v_mul_f32_e32 v106, v106, v106
	v_max_f32_e32 v107, 0, v107
	v_max_f32_e32 v108, 0, v108
	v_max_f32_e32 v109, 0, v109
	v_max_f32_e32 v98, v98, v98
	v_lshl_add_u64 v[114:115], v[114:115], 0, v[150:151]
	v_mul_f32_e32 v110, v110, v110
	v_mul_f32_e32 v107, v107, v107
	v_mul_f32_e32 v108, v108, v108
	v_mul_f32_e32 v109, v109, v109
	v_cvt_pk_bf16_f32 v106, v110, v106
	v_max_f32_e32 v98, 0, v98
	v_max_f32_e32 v99, v99, v99
	v_max_f32_e32 v100, v100, v100
	v_cvt_pk_bf16_f32 v107, v107, v108
	v_cvt_pk_bf16_f32 v108, v116, v111
	v_cvt_pk_bf16_f32 v109, v112, v109
	global_store_dwordx4 v[114:115], v[106:109], off nt
	v_max_f32_e32 v99, 0, v99
	v_max_f32_e32 v100, 0, v100
	v_mul_f32_e32 v106, v98, v98
	v_max_f32_e32 v98, v103, v103
	v_max_f32_e32 v102, v102, v102
	v_max_f32_e32 v98, 0, v98
	v_mul_f32_e32 v103, v99, v99
	v_max_f32_e32 v99, v104, v104
	v_mul_f32_e32 v104, v100, v100
	v_max_f32_e32 v100, v105, v105
	v_max_f32_e32 v101, v101, v101
	v_max_f32_e32 v102, 0, v102
	v_mul_f32_e32 v98, v98, v98
	v_max_f32_e32 v99, 0, v99
	v_max_f32_e32 v100, 0, v100
	v_max_f32_e32 v101, 0, v101
	v_mul_f32_e32 v102, v102, v102
	v_mul_f32_e32 v99, v99, v99
	v_mul_f32_e32 v100, v100, v100
	v_mul_f32_e32 v101, v101, v101
	v_cvt_pk_bf16_f32 v98, v102, v98
	v_max_f32_e32 v90, v90, v90
	v_cvt_pk_bf16_f32 v99, v99, v100
	v_cvt_pk_bf16_f32 v100, v106, v103
	v_cvt_pk_bf16_f32 v101, v104, v101
	global_store_dwordx4 v[114:115], v[98:101], off offset:256 nt
	v_max_f32_e32 v90, 0, v90
	v_max_f32_e32 v91, v91, v91
	v_or_b32_e32 v98, 32, v146
	v_max_f32_e32 v92, v92, v92
	v_ashrrev_i32_e32 v99, 31, v98
	v_mul_f32_e32 v100, v90, v90
	v_max_f32_e32 v90, v95, v95
	v_max_f32_e32 v91, 0, v91
	v_max_f32_e32 v92, 0, v92
	v_lshlrev_b64 v[98:99], 14, v[98:99]
	v_max_f32_e32 v94, v94, v94
	v_max_f32_e32 v90, 0, v90
	v_mul_f32_e32 v95, v91, v91
	v_max_f32_e32 v91, v96, v96
	v_mul_f32_e32 v96, v92, v92
	v_max_f32_e32 v92, v97, v97
	v_max_f32_e32 v93, v93, v93
	v_lshl_add_u64 v[98:99], s[24:25], 0, v[98:99]
	v_max_f32_e32 v94, 0, v94
	v_mul_f32_e32 v90, v90, v90
	v_max_f32_e32 v91, 0, v91
	v_max_f32_e32 v92, 0, v92
	v_max_f32_e32 v93, 0, v93
	v_max_f32_e32 v82, v82, v82
	v_lshl_add_u64 v[98:99], v[98:99], 0, v[150:151]
	v_mul_f32_e32 v94, v94, v94
	v_mul_f32_e32 v91, v91, v91
	v_mul_f32_e32 v92, v92, v92
	v_mul_f32_e32 v93, v93, v93
	v_cvt_pk_bf16_f32 v90, v94, v90
	v_max_f32_e32 v82, 0, v82
	v_max_f32_e32 v83, v83, v83
	v_max_f32_e32 v84, v84, v84
	v_cvt_pk_bf16_f32 v91, v91, v92
	v_cvt_pk_bf16_f32 v92, v100, v95
	v_cvt_pk_bf16_f32 v93, v96, v93
	global_store_dwordx4 v[98:99], v[90:93], off nt
	v_max_f32_e32 v83, 0, v83
	v_max_f32_e32 v84, 0, v84
	v_mul_f32_e32 v90, v82, v82
	v_max_f32_e32 v82, v87, v87
	v_max_f32_e32 v86, v86, v86
; __device__ __forceinline__ unsigned cvt_pk_bf16(float lo, float hi) { unsigned r; asm("v_cvt_pk_bf16_f32 %0, %1, %2" : "=v"(r) : "v"(lo), "v"(hi)); return r; }
;     __device__ __forceinline__ void operator()(const f32x4 (&acc)[2][2][4][2], const Unit& u, int wr, int wc, int fr, int fq) const {
;         const int row0 = u.pm * BM + wr * 64 + fr, col0 = u.pn * BM + wc * 32 + 8 * fq;
; #pragma unroll
;         for (int ai = 0; ai < 2; ++ai)
; #pragma unroll
;             for (int m = 0; m < 4; ++m) { bf16_t* rowp = O + (size_t)(row0 + ai * HALF + m * 16) * ldc + col0;
; #pragma unroll
;                 for (int bj = 0; bj < 2; ++bj) { f32x4 v0 = acc[ai][bj][m][0], v1 = acc[ai][bj][m][1];
;                     if (ACT == 1) {
; #pragma unroll
;                         for (int j = 0; j < 4; ++j) { float a = fmaxf(v0[j], 0.f), b = fmaxf(v1[j], 0.f); v0[j] = a * a; v1[j] = b * b; } }
;                     u32x4 w; w.x = cvt_pk_bf16(v0[0], v0[1]); w.y = cvt_pk_bf16(v0[2], v0[3]); w.z = cvt_pk_bf16(v1[0], v1[1]); w.w = cvt_pk_bf16(v1[2], v1[3]);
;                     if (ACT == 1) __builtin_nontemporal_store(w, (u32x4*)(rowp + bj * HALF));
;                     else *(u32x4*)(rowp + bj * HALF) = w; } }
	v_max_f32_e32 v82, 0, v82
	v_mul_f32_e32 v87, v83, v83
	v_max_f32_e32 v83, v88, v88
	v_mul_f32_e32 v88, v84, v84
	v_max_f32_e32 v84, v89, v89
	v_max_f32_e32 v85, v85, v85
	v_max_f32_e32 v86, 0, v86
	v_mul_f32_e32 v82, v82, v82
	v_max_f32_e32 v83, 0, v83
	v_max_f32_e32 v84, 0, v84
	v_max_f32_e32 v85, 0, v85
	v_mul_f32_e32 v86, v86, v86
	v_mul_f32_e32 v83, v83, v83
	v_mul_f32_e32 v84, v84, v84
	v_mul_f32_e32 v85, v85, v85
	v_cvt_pk_bf16_f32 v82, v86, v82
	v_max_f32_e32 v74, v74, v74
	v_cvt_pk_bf16_f32 v83, v83, v84
	v_cvt_pk_bf16_f32 v84, v90, v87
	v_cvt_pk_bf16_f32 v85, v88, v85
	global_store_dwordx4 v[98:99], v[82:85], off offset:256 nt
	v_max_f32_e32 v74, 0, v74
	v_max_f32_e32 v75, v75, v75
	v_or_b32_e32 v82, 48, v146
	v_max_f32_e32 v76, v76, v76
	v_ashrrev_i32_e32 v83, 31, v82
	v_mul_f32_e32 v84, v74, v74
	v_max_f32_e32 v74, v79, v79
	v_max_f32_e32 v75, 0, v75
	v_max_f32_e32 v76, 0, v76
	v_lshlrev_b64 v[82:83], 14, v[82:83]
	v_max_f32_e32 v78, v78, v78
	v_max_f32_e32 v74, 0, v74
	v_mul_f32_e32 v79, v75, v75
	v_max_f32_e32 v75, v80, v80
	v_mul_f32_e32 v80, v76, v76
	v_max_f32_e32 v76, v81, v81
	v_max_f32_e32 v77, v77, v77
	v_lshl_add_u64 v[82:83], s[24:25], 0, v[82:83]
	v_max_f32_e32 v78, 0, v78
	v_mul_f32_e32 v74, v74, v74
	v_max_f32_e32 v75, 0, v75
	v_max_f32_e32 v76, 0, v76
	v_max_f32_e32 v77, 0, v77
	v_max_f32_e32 v66, v66, v66
	v_max_f32_e32 v67, v67, v67
	v_max_f32_e32 v68, v68, v68
	v_lshl_add_u64 v[82:83], v[82:83], 0, v[150:151]
	v_mul_f32_e32 v78, v78, v78
	v_mul_f32_e32 v75, v75, v75
	v_mul_f32_e32 v76, v76, v76
	v_mul_f32_e32 v77, v77, v77
	v_cvt_pk_bf16_f32 v74, v78, v74
	v_max_f32_e32 v66, 0, v66
	v_max_f32_e32 v67, 0, v67
	v_max_f32_e32 v68, 0, v68
	v_cvt_pk_bf16_f32 v75, v75, v76
	v_cvt_pk_bf16_f32 v76, v84, v79
	v_cvt_pk_bf16_f32 v77, v80, v77
	global_store_dwordx4 v[82:83], v[74:77], off nt
	v_max_f32_e32 v69, v69, v69
	v_max_f32_e32 v70, v70, v70
	v_mul_f32_e32 v74, v66, v66
	v_max_f32_e32 v66, v71, v71
	v_mul_f32_e32 v71, v67, v67
	v_max_f32_e32 v67, v72, v72
	v_mul_f32_e32 v72, v68, v68
	v_max_f32_e32 v68, v73, v73
	v_max_f32_e32 v67, 0, v67
	v_max_f32_e32 v68, 0, v68
	v_max_f32_e32 v66, 0, v66
	v_mul_f32_e32 v67, v67, v67
	v_max_f32_e32 v69, 0, v69
	v_mul_f32_e32 v68, v68, v68
	v_max_f32_e32 v58, v58, v58
	v_max_f32_e32 v70, 0, v70
	v_mul_f32_e32 v66, v66, v66
	v_mul_f32_e32 v69, v69, v69
	v_cvt_pk_bf16_f32 v67, v67, v68
	v_cvt_pk_bf16_f32 v68, v74, v71
	v_max_f32_e32 v58, 0, v58
	v_max_f32_e32 v59, v59, v59
	v_max_f32_e32 v60, v60, v60
	v_mul_f32_e32 v70, v70, v70
	v_cvt_pk_bf16_f32 v66, v70, v66
	v_cvt_pk_bf16_f32 v69, v72, v69
	global_store_dwordx4 v[82:83], v[66:69], off offset:256 nt
	v_max_f32_e32 v62, v62, v62
	v_max_f32_e32 v59, 0, v59
	v_mul_f32_e32 v68, v58, v58
	v_max_f32_e32 v58, v63, v63
	v_max_f32_e32 v60, 0, v60
	v_max_f32_e32 v62, 0, v62
	v_max_f32_e32 v58, 0, v58
	v_mul_f32_e32 v63, v59, v59
	v_max_f32_e32 v59, v64, v64
	v_mul_f32_e32 v64, v60, v60
	v_max_f32_e32 v60, v65, v65
	v_mul_f32_e32 v62, v62, v62
	v_mul_f32_e32 v58, v58, v58
	v_max_f32_e32 v59, 0, v59
	v_max_f32_e32 v60, 0, v60
	v_max_f32_e32 v61, v61, v61
	s_mov_b32 s8, 0x200000
	v_mul_f32_e32 v59, v59, v59
	v_max_f32_e32 v61, 0, v61
	v_mul_f32_e32 v60, v60, v60
	v_cvt_pk_bf16_f32 v58, v62, v58
	v_add_co_u32_e32 v62, vcc, s8, v140
	v_max_f32_e32 v50, v50, v50
	v_max_f32_e32 v51, v51, v51
	v_max_f32_e32 v52, v52, v52
	v_mul_f32_e32 v61, v61, v61
	v_cvt_pk_bf16_f32 v59, v59, v60
	v_cvt_pk_bf16_f32 v60, v68, v63
	v_addc_co_u32_e32 v63, vcc, 0, v141, vcc
	v_max_f32_e32 v50, 0, v50
	v_max_f32_e32 v51, 0, v51
	v_max_f32_e32 v52, 0, v52
	v_cvt_pk_bf16_f32 v61, v64, v61
	global_store_dwordx4 v[62:63], v[58:61], off nt
	v_max_f32_e32 v53, v53, v53
	s_mov_b64 s[38:39], 0x200000
	v_mul_f32_e32 v58, v50, v50
	v_max_f32_e32 v50, v55, v55
	v_mul_f32_e32 v55, v51, v51
	v_max_f32_e32 v51, v56, v56
	v_mul_f32_e32 v56, v52, v52
	v_max_f32_e32 v52, v57, v57
	v_max_f32_e32 v51, 0, v51
	v_max_f32_e32 v52, 0, v52
	v_max_f32_e32 v54, v54, v54
	v_max_f32_e32 v50, 0, v50
	v_mul_f32_e32 v51, v51, v51
	v_max_f32_e32 v53, 0, v53
	v_mul_f32_e32 v52, v52, v52
	v_max_f32_e32 v42, v42, v42
	v_lshl_add_u64 v[66:67], v[140:141], 0, s[38:39]
	v_max_f32_e32 v54, 0, v54
	v_mul_f32_e32 v50, v50, v50
	v_mul_f32_e32 v53, v53, v53
	v_cvt_pk_bf16_f32 v51, v51, v52
	v_cvt_pk_bf16_f32 v52, v58, v55
	v_max_f32_e32 v42, 0, v42
	v_max_f32_e32 v43, v43, v43
	v_max_f32_e32 v44, v44, v44
	v_mul_f32_e32 v54, v54, v54
	v_cvt_pk_bf16_f32 v50, v54, v50
	v_cvt_pk_bf16_f32 v53, v56, v53
	global_store_dwordx4 v[66:67], v[50:53], off offset:256 nt
	v_max_f32_e32 v46, v46, v46
	v_max_f32_e32 v43, 0, v43
	v_mul_f32_e32 v52, v42, v42
	v_max_f32_e32 v42, v47, v47
	v_max_f32_e32 v44, 0, v44
	v_max_f32_e32 v46, 0, v46
	v_max_f32_e32 v42, 0, v42
	v_mul_f32_e32 v47, v43, v43
	v_max_f32_e32 v43, v48, v48
	v_mul_f32_e32 v48, v44, v44
	v_max_f32_e32 v44, v49, v49
	v_mul_f32_e32 v46, v46, v46
	v_mul_f32_e32 v42, v42, v42
	v_max_f32_e32 v43, 0, v43
	v_max_f32_e32 v44, 0, v44
	v_max_f32_e32 v45, v45, v45
	s_mov_b32 s8, 0x240000
	v_mul_f32_e32 v43, v43, v43
	v_max_f32_e32 v45, 0, v45
	v_mul_f32_e32 v44, v44, v44
	v_cvt_pk_bf16_f32 v42, v46, v42
; __device__ __forceinline__ unsigned cvt_pk_bf16(float lo, float hi) { unsigned r; asm("v_cvt_pk_bf16_f32 %0, %1, %2" : "=v"(r) : "v"(lo), "v"(hi)); return r; }
; #define PG8_WAIT_V(n) asm volatile("s_waitcnt vmcnt(" #n ")" ::: "memory")
; #define PG8_BAR __builtin_amdgcn_s_barrier()
;     __device__ __forceinline__ void operator()(const f32x4 (&acc)[2][2][4][2], const Unit& u, int wr, int wc, int fr, int fq) const {
;         const int row0 = u.pm * BM + wr * 64 + fr, col0 = u.pn * BM + wc * 32 + 8 * fq;
; #pragma unroll
;         for (int ai = 0; ai < 2; ++ai)
; #pragma unroll
;             for (int m = 0; m < 4; ++m) { bf16_t* rowp = O + (size_t)(row0 + ai * HALF + m * 16) * ldc + col0;
; #pragma unroll
;                 for (int bj = 0; bj < 2; ++bj) { f32x4 v0 = acc[ai][bj][m][0], v1 = acc[ai][bj][m][1];
;                     if (ACT == 1) {
; #pragma unroll
;                         for (int j = 0; j < 4; ++j) { float a = fmaxf(v0[j], 0.f), b = fmaxf(v1[j], 0.f); v0[j] = a * a; v1[j] = b * b; } }
;                     u32x4 w; w.x = cvt_pk_bf16(v0[0], v0[1]); w.y = cvt_pk_bf16(v0[2], v0[3]); w.z = cvt_pk_bf16(v1[0], v1[1]); w.w = cvt_pk_bf16(v1[2], v1[3]);
;                     if (ACT == 1) __builtin_nontemporal_store(w, (u32x4*)(rowp + bj * HALF));
;                     else *(u32x4*)(rowp + bj * HALF) = w; } }
; template <class Epi, class Sched>
; __device__ __forceinline__ void gemm_phase(LAS unsigned char* lds, const Gemm g, const Sched& S, const Epi& E) {
;     ...
;         if (!has_next) break;
; #pragma unroll
;         for (int a = 0; a < 2; ++a)
; #pragma unroll
;             for (int b = 0; b < 2; ++b)
; #pragma unroll
;                 for (int m = 0; m < 4; ++m)
; #pragma unroll
;                     for (int n = 0; n < 2; ++n) acc[a][b][m][n] = (f32x4){0.f, 0.f, 0.f, 0.f};
;         cur = nxt; cA = nA; cB = nB; ++ui;
;     }
;     PG8_WAIT_V(0);
;     if (wr == 0) PG8_BAR;
;     PG8_BAR;
	v_add_co_u32_e32 v46, vcc, s8, v140
	v_max_f32_e32 v34, v34, v34
	v_max_f32_e32 v35, v35, v35
	v_max_f32_e32 v36, v36, v36
	v_mul_f32_e32 v45, v45, v45
	v_cvt_pk_bf16_f32 v43, v43, v44
	v_cvt_pk_bf16_f32 v44, v52, v47
	v_addc_co_u32_e32 v47, vcc, 0, v141, vcc
	v_max_f32_e32 v34, 0, v34
	v_max_f32_e32 v35, 0, v35
	v_max_f32_e32 v36, 0, v36
	v_cvt_pk_bf16_f32 v45, v48, v45
	global_store_dwordx4 v[46:47], v[42:45], off nt
	v_max_f32_e32 v37, v37, v37
	s_mov_b64 s[38:39], 0x240000
	v_mul_f32_e32 v42, v34, v34
	v_max_f32_e32 v34, v39, v39
	v_mul_f32_e32 v39, v35, v35
	v_max_f32_e32 v35, v40, v40
	v_mul_f32_e32 v40, v36, v36
	v_max_f32_e32 v36, v41, v41
	v_max_f32_e32 v35, 0, v35
	v_max_f32_e32 v36, 0, v36
	v_max_f32_e32 v38, v38, v38
	v_max_f32_e32 v34, 0, v34
	v_mul_f32_e32 v35, v35, v35
	v_max_f32_e32 v37, 0, v37
	v_mul_f32_e32 v36, v36, v36
	v_max_f32_e32 v26, v26, v26
	v_lshl_add_u64 v[50:51], v[140:141], 0, s[38:39]
	v_max_f32_e32 v38, 0, v38
	v_mul_f32_e32 v34, v34, v34
	v_mul_f32_e32 v37, v37, v37
	v_cvt_pk_bf16_f32 v35, v35, v36
	v_cvt_pk_bf16_f32 v36, v42, v39
	v_max_f32_e32 v26, 0, v26
	v_max_f32_e32 v27, v27, v27
	v_max_f32_e32 v28, v28, v28
	v_mul_f32_e32 v38, v38, v38
	v_cvt_pk_bf16_f32 v34, v38, v34
	v_cvt_pk_bf16_f32 v37, v40, v37
	global_store_dwordx4 v[50:51], v[34:37], off offset:256 nt
	v_max_f32_e32 v30, v30, v30
	v_max_f32_e32 v27, 0, v27
	v_mul_f32_e32 v36, v26, v26
	v_max_f32_e32 v26, v31, v31
	v_max_f32_e32 v28, 0, v28
	v_max_f32_e32 v30, 0, v30
	v_max_f32_e32 v26, 0, v26
	v_mul_f32_e32 v31, v27, v27
	v_max_f32_e32 v27, v32, v32
	v_mul_f32_e32 v32, v28, v28
	v_max_f32_e32 v28, v33, v33
	v_mul_f32_e32 v30, v30, v30
	v_mul_f32_e32 v26, v26, v26
	v_max_f32_e32 v27, 0, v27
	v_max_f32_e32 v28, 0, v28
	v_max_f32_e32 v29, v29, v29
	s_mov_b32 s8, 0x280000
	v_mul_f32_e32 v27, v27, v27
	v_max_f32_e32 v29, 0, v29
	v_mul_f32_e32 v28, v28, v28
	v_cvt_pk_bf16_f32 v26, v30, v26
	v_add_co_u32_e32 v30, vcc, s8, v140
	v_max_f32_e32 v18, v18, v18
	v_max_f32_e32 v19, v19, v19
	v_max_f32_e32 v20, v20, v20
	v_mul_f32_e32 v29, v29, v29
	v_cvt_pk_bf16_f32 v27, v27, v28
	v_cvt_pk_bf16_f32 v28, v36, v31
	v_addc_co_u32_e32 v31, vcc, 0, v141, vcc
	v_max_f32_e32 v18, 0, v18
	v_max_f32_e32 v19, 0, v19
	v_max_f32_e32 v20, 0, v20
	v_cvt_pk_bf16_f32 v29, v32, v29
	global_store_dwordx4 v[30:31], v[26:29], off nt
	v_max_f32_e32 v21, v21, v21
	s_mov_b64 s[38:39], 0x280000
	v_mul_f32_e32 v26, v18, v18
	v_max_f32_e32 v18, v23, v23
	v_mul_f32_e32 v23, v19, v19
	v_max_f32_e32 v19, v24, v24
	v_mul_f32_e32 v24, v20, v20
	v_max_f32_e32 v20, v25, v25
	v_max_f32_e32 v19, 0, v19
	v_max_f32_e32 v20, 0, v20
	v_max_f32_e32 v22, v22, v22
	v_max_f32_e32 v18, 0, v18
	v_mul_f32_e32 v19, v19, v19
	v_max_f32_e32 v21, 0, v21
	v_mul_f32_e32 v20, v20, v20
	v_max_f32_e32 v10, v10, v10
	v_lshl_add_u64 v[34:35], v[140:141], 0, s[38:39]
	v_max_f32_e32 v22, 0, v22
	v_mul_f32_e32 v18, v18, v18
	v_mul_f32_e32 v21, v21, v21
	v_cvt_pk_bf16_f32 v19, v19, v20
	v_cvt_pk_bf16_f32 v20, v26, v23
	v_max_f32_e32 v10, 0, v10
	v_max_f32_e32 v11, v11, v11
	v_max_f32_e32 v12, v12, v12
	v_mul_f32_e32 v22, v22, v22
	v_cvt_pk_bf16_f32 v18, v22, v18
	v_cvt_pk_bf16_f32 v21, v24, v21
	global_store_dwordx4 v[34:35], v[18:21], off offset:256 nt
	v_max_f32_e32 v14, v14, v14
	v_max_f32_e32 v11, 0, v11
	v_mul_f32_e32 v20, v10, v10
	v_max_f32_e32 v10, v15, v15
	v_max_f32_e32 v12, 0, v12
	v_max_f32_e32 v14, 0, v14
	v_max_f32_e32 v10, 0, v10
	v_mul_f32_e32 v15, v11, v11
	v_max_f32_e32 v11, v16, v16
	v_mul_f32_e32 v16, v12, v12
	v_max_f32_e32 v12, v17, v17
	v_mul_f32_e32 v14, v14, v14
	v_mul_f32_e32 v10, v10, v10
	v_max_f32_e32 v11, 0, v11
	v_max_f32_e32 v12, 0, v12
	v_max_f32_e32 v13, v13, v13
	s_mov_b32 s8, 0x2c0000
	v_mul_f32_e32 v11, v11, v11
	v_max_f32_e32 v13, 0, v13
	v_mul_f32_e32 v12, v12, v12
	v_cvt_pk_bf16_f32 v10, v14, v10
	v_add_co_u32_e32 v14, vcc, s8, v140
	v_max_f32_e32 v2, v2, v2
	v_max_f32_e32 v3, v3, v3
	v_max_f32_e32 v4, v4, v4
	v_mul_f32_e32 v13, v13, v13
	v_cvt_pk_bf16_f32 v11, v11, v12
	v_cvt_pk_bf16_f32 v12, v20, v15
	v_addc_co_u32_e32 v15, vcc, 0, v141, vcc
	v_max_f32_e32 v2, 0, v2
	v_max_f32_e32 v3, 0, v3
	v_max_f32_e32 v4, 0, v4
	v_cvt_pk_bf16_f32 v13, v16, v13
	global_store_dwordx4 v[14:15], v[10:13], off nt
	v_max_f32_e32 v5, v5, v5
	s_mov_b64 s[38:39], 0x2c0000
	v_mul_f32_e32 v10, v2, v2
	v_max_f32_e32 v2, v7, v7
	v_mul_f32_e32 v7, v3, v3
	v_max_f32_e32 v3, v8, v8
	v_mul_f32_e32 v8, v4, v4
	v_max_f32_e32 v4, v9, v9
	v_max_f32_e32 v6, v6, v6
	v_max_f32_e32 v2, 0, v2
	v_max_f32_e32 v3, 0, v3
	v_max_f32_e32 v4, 0, v4
	v_max_f32_e32 v5, 0, v5
	v_lshl_add_u64 v[18:19], v[140:141], 0, s[38:39]
	v_max_f32_e32 v6, 0, v6
	v_mul_f32_e32 v2, v2, v2
	v_mul_f32_e32 v3, v3, v3
	v_mul_f32_e32 v4, v4, v4
	v_mul_f32_e32 v5, v5, v5
	s_and_b64 vcc, exec, s[40:41]
	s_mov_b32 s68, s26
	s_mov_b32 s8, s28
	s_mov_b64 s[46:47], s[44:45]
	s_mov_b64 s[48:49], s[42:43]
	v_mul_f32_e32 v6, v6, v6
	v_cvt_pk_bf16_f32 v2, v6, v2
	v_cvt_pk_bf16_f32 v3, v3, v4
	v_cvt_pk_bf16_f32 v4, v10, v7
	v_cvt_pk_bf16_f32 v5, v8, v5
	global_store_dwordx4 v[18:19], v[2:5], off offset:256 nt
	s_cbranch_vccz .LBB0_70
	s_waitcnt vmcnt(0)
	s_cmpk_gt_u32 s52, 0xff
	s_cbranch_scc1 .LBB0_77
	s_barrier

; __device__ __forceinline__ int tid_o() { int t = (int)threadIdx.x; asm volatile("" : "+v"(t)); return t; }
; #define PG8_STAGE(bufoff, gbase, voff) do { _Pragma("unroll") for (int _i = 0; _i < 2; ++_i) \
;         __builtin_amdgcn_global_load_lds((const unsigned*)((const char*)(gbase) + (voff)[_i]), (LAS unsigned*)(lds + (bufoff) + ldsw + _i * 8192), 16, 0, 0); } while (0)
; #define PG8_WAIT_V(n) asm volatile("s_waitcnt vmcnt(" #n ")" ::: "memory")
; #define PG8_BAR __builtin_amdgcn_s_barrier()
; template <class Epi, class Sched>
; __device__ __forceinline__ void gemm_phase(LAS unsigned char* lds, const Gemm g, const Sched& S, const Epi& E) {
;     const int tid = tid_o(), wid = __builtin_amdgcn_readfirstlane(tid >> 6), lane = tid & 63, wr = wid >> 2, wc = wid & 3, fr = lane & 15, fq = lane >> 4;
;     const int K = g.K, nt = K / BK;
;     unsigned voffA[2], voffB[2];
; #pragma unroll
;     for (int i = 0; i < 2; ++i) { int R, C; stage_rc(tid * 16 + i * 8192, R, C); const int Rb = Epi::PERM ? ((R & ~31) + perm32(R & 31)) : R;
;         voffA[i] = (unsigned)(R * g.ld + C) * 2u; voffB[i] = (unsigned)(Rb * g.ld + C) * 2u; }
;     const size_t kstep = (size_t)(BK * 2);
;     const size_t hstep = (size_t)HALF * g.ld * 2;
;     const size_t tstep = 2 * hstep, sstep = (size_t)K * 2;
;     const unsigned ldsw = (unsigned)wid * 1024u;
;     const int aoff = lds_byte(wr * 64 + fr, fq * 8), boff = lds_byte(wc * 32 + fr, fq * 8);
;     ...
;     const char* cA = (const char*)g.A + (size_t)cur.pm * tstep + (size_t)cur.ks * sstep; const char* cB = (const char*)g.Bt + (size_t)cur.pn * tstep + (size_t)cur.ks * sstep;
;     PG8_STAGE(PG8_SB(0, 0), cB, voffB); PG8_STAGE(PG8_SA(0, 0), cA, voffA); PG8_STAGE(PG8_SB(0, 1), cB + hstep, voffB); PG8_STAGE(PG8_SA(0, 1), cA + hstep, voffA);
;     if (wr == 1) PG8_BAR;
;     PG8_WAIT_V(4); PG8_BAR;
;     PG8_STAGE(PG8_SB(1, 0), cB + kstep, voffB); PG8_STAGE(PG8_SA(1, 0), cA + kstep, voffA); PG8_STAGE(PG8_SB(1, 1), cB + hstep + kstep, voffB);
;     PG8_WAIT_V(6); PG8_BAR;
.LBB0_89:
	s_sext_i32_i8 s76, s30
	v_readlane_b32 s30, v255, 7
	v_bfe_u32 v19, v17, 4, 2
	s_add_u32 s30, s30, 0x4000
	v_readlane_b32 s38, v255, 8
	v_and_b32_e32 v20, 15, v17
	v_lshlrev_b32_e32 v21, 4, v19
	v_lshlrev_b32_e32 v17, 2, v17
	s_addc_u32 s71, s38, 0
	v_lshl_or_b32 v168, s40, 6, v20
	v_lshl_or_b32 v20, v20, 6, v21
	s_lshl_b32 s38, s40, 13
	v_and_b32_e32 v17, 32, v17
	v_bitop3_b32 v21, v20, s38, v17 bitop3:0xde
	s_lshl_b32 s38, s41, 5
	s_and_b32 s40, s38, 0x60
	s_add_i32 m0, s9, 0x18000
	v_lshl_add_u64 v[8:9], v[8:9], 0, s[36:37]
	s_lshl_b32 s38, s40, 7
	s_waitcnt vmcnt(4)
	s_barrier
	global_load_lds_dwordx4 v[8:9], off
	v_lshl_add_u64 v[6:7], v[6:7], 0, s[36:37]
	s_add_i32 m0, s9, 0x1a000
	s_add_i32 s72, s9, 0x8000
	s_add_i32 s73, s9, 0xa000
	v_bitop3_b32 v169, v20, s38, v17 bitop3:0xde
	v_add_u32_e32 v226, 0x10000, v169
	global_load_lds_dwordx4 v[6:7], off
	v_lshl_add_u64 v[4:5], v[4:5], 0, s[36:37]
	s_mov_b32 m0, s72
	s_add_u32 s38, s56, 0x80080
	global_load_lds_dwordx4 v[4:5], off
	v_lshl_add_u64 v[2:3], v[2:3], 0, s[36:37]
	s_mov_b32 m0, s73
	s_addc_u32 s39, s57, 0
	global_load_lds_dwordx4 v[2:3], off
	s_add_i32 m0, s9, 0x1c000
	v_lshl_add_u64 v[2:3], s[38:39], 0, v[0:1]
	global_load_lds_dwordx4 v[2:3], off
	v_lshl_add_u64 v[2:3], s[38:39], 0, v[146:147]
	s_add_i32 m0, s9, 0x1e000
	s_mov_b64 s[38:39], 0x80080
	global_load_lds_dwordx4 v[2:3], off
	v_lshlrev_b32_e32 v2, 14, v14
	v_and_b32_e32 v2, 0x7fff8000, v2
	v_lshl_add_u32 v2, v15, 11, v2
	v_or_b32_e32 v2, v2, v16
	v_add_lshl_u32 v2, v2, v18, 1
	v_mov_b32_e32 v3, v1
	v_lshl_add_u64 v[148:149], v[2:3], 0, s[38:39]
	v_lshlrev_b32_e32 v2, 14, v10
	v_and_b32_e32 v2, 0x7fff8000, v2
	v_lshl_add_u32 v2, v11, 11, v2
	s_waitcnt vmcnt(6)
	v_or_b32_e32 v2, v2, v12
	v_add_lshl_u32 v2, v2, v13, 1
	s_ashr_i32 s74, s63, 31
	v_lshl_or_b32 v170, v19, 2, s40
	v_lshl_add_u64 v[150:151], v[2:3], 0, s[38:39]
	s_mov_b32 s75, 0
	v_add_u32_e32 v171, 0, v21
	s_barrier
	s_branch .LBB0_92

; #define PG8_STAGE(bufoff, gbase, voff) do { _Pragma("unroll") for (int _i = 0; _i < 2; ++_i) \
;         __builtin_amdgcn_global_load_lds((const unsigned*)((const char*)(gbase) + (voff)[_i]), (LAS unsigned*)(lds + (bufoff) + ldsw + _i * 8192), 16, 0, 0); } while (0)
; #define PG8_LDA(dst, b, h) do { _Pragma("unroll") for (int m = 0; m < 4; ++m) _Pragma("unroll") for (int k = 0; k < 2; ++k) dst[m][k] = *(const LAS bf16x8*)(lds + PG8_SA(b, h) + aoff + m * 2048 + k * 1024); } while (0)
; #define PG8_LDB(dst, b, h) do { _Pragma("unroll") for (int n = 0; n < 2; ++n) _Pragma("unroll") for (int k = 0; k < 2; ++k) dst[n][k] = *(const LAS bf16x8*)(lds + PG8_SB(b, h) + boff + n * 2048 + k * 1024); } while (0)
; #define PG8_WAIT_V(n) asm volatile("s_waitcnt vmcnt(" #n ")" ::: "memory")
; #define PG8_WAIT_L(n) asm volatile("s_waitcnt lgkmcnt(" #n ")" ::: "memory")
; #define PG8_BAR __builtin_amdgcn_s_barrier()
; #define PG8_SCHED __builtin_amdgcn_sched_barrier(0)
; template <class Epi, class Sched>
; __device__ __forceinline__ void gemm_phase(LAS unsigned char* lds, const Gemm g, const Sched& S, const Epi& E) {
;     ...
;         const bool has_next = S.next(ui + 1, nxt);
;         const char* nA = has_next ? (const char*)g.A + (size_t)nxt.pm * tstep + (size_t)nxt.ks * sstep : cA; const char* nB = has_next ? (const char*)g.Bt + (size_t)nxt.pn * tstep + (size_t)nxt.ks * sstep : cB;
;         for (int t = 0; t < nt; t += 2) {
;             const bool last = (t == nt - 2);
;             const char* a1 = cA + (size_t)(t + 1) * kstep;
;             const char* a2 = last ? nA : cA + (size_t)(t + 2) * kstep; const char* b2 = last ? nB : cB + (size_t)(t + 2) * kstep;
;             const char* a3 = a2 + kstep; const char* b3 = b2 + kstep;
;             PG8_LDB(B0, 0, 0); PG8_SCHED; PG8_LDA(At, 0, 0); PG8_STAGE(PG8_SA(1, 1), a1 + hstep, voffA);
;             PG8_WAIT_L(8); PG8_BAR; PG8_WAIT_L(0); PG8_MMA(0, 0, At, B0); PG8_BAR; PG8_SCHED;
;             PG8_LDB(B1, 0, 1); PG8_STAGE(PG8_SB(0, 0), b2, voffB);
;             PG8_BAR; PG8_WAIT_L(0); PG8_MMA(0, 1, At, B1); PG8_BAR;
;             PG8_LDA(At, 0, 1); PG8_STAGE(PG8_SA(0, 0), a2, voffA);
;             PG8_BAR; PG8_WAIT_L(0); PG8_MMA(1, 0, At, B0); PG8_BAR; PG8_SCHED;
;             PG8_STAGE(PG8_SB(0, 1), b2 + hstep, voffB);
;             PG8_WAIT_V(6); PG8_BAR; PG8_MMA(1, 1, At, B1); PG8_BAR;
.LBB0_99:
	s_add_u32 s56, s28, 0x100
	s_addc_u32 s57, s29, 0
	s_cmp_eq_u32 s81, 28
	s_cselect_b32 s61, s51, s57
	s_cselect_b32 s60, s77, s56
	s_cselect_b32 s59, s49, s80
	s_cselect_b32 s58, s78, s79
	s_add_i32 m0, s9, 0xc000
	s_nop 0
	global_load_lds_dwordx4 v150, s[28:29]
	s_add_i32 m0, s9, 0xe000
	s_nop 0
	global_load_lds_dwordx4 v148, s[28:29]
	s_add_i32 s38, 0, 0x10000
	ds_read_b128 v[98:101], v226
	ds_read_b128 v[102:105], v226 offset:1024
	ds_read_b128 v[106:109], v226 offset:2048
	ds_read_b128 v[110:113], v226 offset:3072
	ds_read_b128 v[152:155], v171
	ds_read_b128 v[160:163], v171 offset:1024
	ds_read_b128 v[164:167], v171 offset:2048
	ds_read_b128 v[172:175], v171 offset:3072
	ds_read_b128 v[176:179], v171 offset:4096
	ds_read_b128 v[180:183], v171 offset:5120
	ds_read_b128 v[184:187], v171 offset:6144
	ds_read_b128 v[188:191], v171 offset:7168
	s_add_i32 s39, 0, 0x14000
	ds_read_b128 v[192:195], v226 offset:16384
	ds_read_b128 v[196:199], v226 offset:17408
	ds_read_b128 v[200:203], v226 offset:18432
	ds_read_b128 v[204:207], v226 offset:19456
	s_waitcnt lgkmcnt(4)
	s_barrier
	s_waitcnt lgkmcnt(0)
	v_mfma_f32_16x16x32_bf16 v[142:145], v[98:101], v[152:155], v[142:145]
	v_mfma_f32_16x16x32_bf16 v[138:141], v[106:109], v[152:155], v[138:141]
	v_mfma_f32_16x16x32_bf16 v[126:129], v[98:101], v[164:167], v[126:129]
	v_mfma_f32_16x16x32_bf16 v[122:125], v[106:109], v[164:167], v[122:125]
	v_mfma_f32_16x16x32_bf16 v[94:97], v[98:101], v[176:179], v[94:97]
	v_mfma_f32_16x16x32_bf16 v[90:93], v[106:109], v[176:179], v[90:93]
	v_mfma_f32_16x16x32_bf16 v[86:89], v[98:101], v[184:187], v[86:89]
	v_mfma_f32_16x16x32_bf16 v[82:85], v[106:109], v[184:187], v[82:85]
	v_mfma_f32_16x16x32_bf16 v[142:145], v[102:105], v[160:163], v[142:145]
	v_mfma_f32_16x16x32_bf16 v[138:141], v[110:113], v[160:163], v[138:141]
	v_mfma_f32_16x16x32_bf16 v[126:129], v[102:105], v[172:175], v[126:129]
	v_mfma_f32_16x16x32_bf16 v[122:125], v[110:113], v[172:175], v[122:125]
	v_mfma_f32_16x16x32_bf16 v[94:97], v[102:105], v[180:183], v[94:97]
	v_mfma_f32_16x16x32_bf16 v[90:93], v[110:113], v[180:183], v[90:93]
	v_mfma_f32_16x16x32_bf16 v[86:89], v[102:105], v[188:191], v[86:89]
	v_mfma_f32_16x16x32_bf16 v[82:85], v[110:113], v[188:191], v[82:85]
	v_mfma_f32_16x16x32_bf16 v[134:137], v[192:195], v[152:155], v[134:137]
	v_mfma_f32_16x16x32_bf16 v[130:133], v[200:203], v[152:155], v[130:133]
	v_mfma_f32_16x16x32_bf16 v[118:121], v[192:195], v[164:167], v[118:121]
	v_mfma_f32_16x16x32_bf16 v[114:117], v[200:203], v[164:167], v[114:117]
	v_mfma_f32_16x16x32_bf16 v[78:81], v[192:195], v[176:179], v[78:81]
	v_mfma_f32_16x16x32_bf16 v[74:77], v[200:203], v[176:179], v[74:77]
	v_mfma_f32_16x16x32_bf16 v[70:73], v[192:195], v[184:187], v[70:73]
	v_mfma_f32_16x16x32_bf16 v[66:69], v[200:203], v[184:187], v[66:69]
	v_mfma_f32_16x16x32_bf16 v[134:137], v[196:199], v[160:163], v[134:137]
	v_mfma_f32_16x16x32_bf16 v[130:133], v[204:207], v[160:163], v[130:133]
	v_mfma_f32_16x16x32_bf16 v[118:121], v[196:199], v[172:175], v[118:121]
	v_mfma_f32_16x16x32_bf16 v[114:117], v[204:207], v[172:175], v[114:117]
	v_mfma_f32_16x16x32_bf16 v[78:81], v[196:199], v[180:183], v[78:81]
	v_mfma_f32_16x16x32_bf16 v[74:77], v[204:207], v[180:183], v[74:77]
	v_mfma_f32_16x16x32_bf16 v[70:73], v[196:199], v[188:191], v[70:73]
	v_mfma_f32_16x16x32_bf16 v[66:69], v[204:207], v[188:191], v[66:69]
	s_barrier
	s_add_i32 s28, s38, s67
	s_mov_b32 m0, s28
	s_nop 0
	global_load_lds_dwordx4 v0, s[58:59]
	s_add_i32 m0, s28, 0x2000
	s_nop 0
	global_load_lds_dwordx4 v146, s[58:59]
	s_mov_b32 m0, s9
	s_nop 0
	global_load_lds_dwordx4 v0, s[60:61]
	s_mov_b32 m0, s68
	s_nop 0
	global_load_lds_dwordx4 v146, s[60:61]
	ds_read_b128 v[152:155], v171 offset:16384
	ds_read_b128 v[160:163], v171 offset:17408
	ds_read_b128 v[164:167], v171 offset:18432
	ds_read_b128 v[172:175], v171 offset:19456
	ds_read_b128 v[176:179], v171 offset:20480
	ds_read_b128 v[180:183], v171 offset:21504
	ds_read_b128 v[184:187], v171 offset:22528
	ds_read_b128 v[188:191], v171 offset:23552
	s_waitcnt vmcnt(4)
	s_waitcnt lgkmcnt(0)
	s_barrier
	v_mfma_f32_16x16x32_bf16 v[62:65], v[98:101], v[152:155], v[62:65]
	v_mfma_f32_16x16x32_bf16 v[58:61], v[106:109], v[152:155], v[58:61]
	v_mfma_f32_16x16x32_bf16 v[46:49], v[98:101], v[164:167], v[46:49]
	v_mfma_f32_16x16x32_bf16 v[42:45], v[106:109], v[164:167], v[42:45]
	v_mfma_f32_16x16x32_bf16 v[30:33], v[98:101], v[176:179], v[30:33]
	v_mfma_f32_16x16x32_bf16 v[26:29], v[106:109], v[176:179], v[26:29]
	v_mfma_f32_16x16x32_bf16 v[22:25], v[98:101], v[184:187], v[22:25]
	v_mfma_f32_16x16x32_bf16 v[18:21], v[106:109], v[184:187], v[18:21]
	v_mfma_f32_16x16x32_bf16 v[62:65], v[102:105], v[160:163], v[62:65]
	v_mfma_f32_16x16x32_bf16 v[58:61], v[110:113], v[160:163], v[58:61]
	v_mfma_f32_16x16x32_bf16 v[46:49], v[102:105], v[172:175], v[46:49]
	v_mfma_f32_16x16x32_bf16 v[42:45], v[110:113], v[172:175], v[42:45]
	v_mfma_f32_16x16x32_bf16 v[30:33], v[102:105], v[180:183], v[30:33]
	v_mfma_f32_16x16x32_bf16 v[26:29], v[110:113], v[180:183], v[26:29]
	v_mfma_f32_16x16x32_bf16 v[22:25], v[102:105], v[188:191], v[22:25]
	v_mfma_f32_16x16x32_bf16 v[18:21], v[110:113], v[188:191], v[18:21]
	v_mfma_f32_16x16x32_bf16 v[54:57], v[192:195], v[152:155], v[54:57]
	v_mfma_f32_16x16x32_bf16 v[50:53], v[200:203], v[152:155], v[50:53]
	v_mfma_f32_16x16x32_bf16 v[38:41], v[192:195], v[164:167], v[38:41]
	v_mfma_f32_16x16x32_bf16 v[34:37], v[200:203], v[164:167], v[34:37]
	v_mfma_f32_16x16x32_bf16 v[14:17], v[192:195], v[176:179], v[14:17]
	v_mfma_f32_16x16x32_bf16 v[10:13], v[200:203], v[176:179], v[10:13]
	v_mfma_f32_16x16x32_bf16 v[6:9], v[192:195], v[184:187], v[6:9]
	v_mfma_f32_16x16x32_bf16 v[2:5], v[200:203], v[184:187], v[2:5]
	v_mfma_f32_16x16x32_bf16 v[54:57], v[196:199], v[160:163], v[54:57]
	v_mfma_f32_16x16x32_bf16 v[50:53], v[204:207], v[160:163], v[50:53]
	v_mfma_f32_16x16x32_bf16 v[38:41], v[196:199], v[172:175], v[38:41]
	v_mfma_f32_16x16x32_bf16 v[34:37], v[204:207], v[172:175], v[34:37]
	v_mfma_f32_16x16x32_bf16 v[14:17], v[196:199], v[180:183], v[14:17]
	v_mfma_f32_16x16x32_bf16 v[10:13], v[204:207], v[180:183], v[10:13]
	v_mfma_f32_16x16x32_bf16 v[6:9], v[196:199], v[188:191], v[6:9]
	v_mfma_f32_16x16x32_bf16 v[2:5], v[204:207], v[188:191], v[2:5]
	s_barrier
; #define PG8_STAGE(bufoff, gbase, voff) do { _Pragma("unroll") for (int _i = 0; _i < 2; ++_i) \
;         __builtin_amdgcn_global_load_lds((const unsigned*)((const char*)(gbase) + (voff)[_i]), (LAS unsigned*)(lds + (bufoff) + ldsw + _i * 8192), 16, 0, 0); } while (0)
; #define PG8_LDA(dst, b, h) do { _Pragma("unroll") for (int m = 0; m < 4; ++m) _Pragma("unroll") for (int k = 0; k < 2; ++k) dst[m][k] = *(const LAS bf16x8*)(lds + PG8_SA(b, h) + aoff + m * 2048 + k * 1024); } while (0)
; #define PG8_LDB(dst, b, h) do { _Pragma("unroll") for (int n = 0; n < 2; ++n) _Pragma("unroll") for (int k = 0; k < 2; ++k) dst[n][k] = *(const LAS bf16x8*)(lds + PG8_SB(b, h) + boff + n * 2048 + k * 1024); } while (0)
; #define PG8_MMA(ai, bj, At, Bt) do { __builtin_amdgcn_s_setprio(1); _Pragma("unroll") for (int m = 0; m < 4; ++m) _Pragma("unroll") for (int n = 0; n < 2; ++n) _Pragma("unroll") for (int k = 0; k < 2; ++k) \
;         acc[ai][bj][m][n] = __builtin_amdgcn_mfma_f32_16x16x32_bf16(Bt[n][k], At[m][k], acc[ai][bj][m][n], 0, 0, 0); __builtin_amdgcn_s_setprio(0); } while (0)
; #define PG8_WAIT_V(n) asm volatile("s_waitcnt vmcnt(" #n ")" ::: "memory")
; #define PG8_WAIT_L(n) asm volatile("s_waitcnt lgkmcnt(" #n ")" ::: "memory")
; #define PG8_BAR __builtin_amdgcn_s_barrier()
; #define PG8_SCHED __builtin_amdgcn_sched_barrier(0)
; template <class Epi, class Sched>
; __device__ __forceinline__ void gemm_phase(LAS unsigned char* lds, const Gemm g, const Sched& S, const Epi& E) {
;     ...
;             PG8_STAGE(PG8_SB(0, 1), b2 + hstep, voffB);
;             PG8_WAIT_V(6); PG8_BAR; PG8_MMA(1, 1, At, B1); PG8_BAR;
;             PG8_LDB(B0, 1, 0); PG8_SCHED; PG8_LDA(At, 1, 0); PG8_STAGE(PG8_SA(0, 1), a2 + hstep, voffA);
;             PG8_WAIT_L(8); PG8_BAR; PG8_WAIT_L(0); PG8_MMA(0, 0, At, B0); PG8_BAR; PG8_SCHED;
;             PG8_LDB(B1, 1, 1); PG8_STAGE(PG8_SB(1, 0), b3, voffB);
;             PG8_BAR; PG8_WAIT_L(0); PG8_MMA(0, 1, At, B1); PG8_BAR;
	s_add_u32 s28, s58, 0x80000
	s_addc_u32 s29, s59, 0
	s_add_i32 s38, s39, s67
	s_mov_b32 m0, s38
	s_nop 0
	global_load_lds_dwordx4 v0, s[28:29]
	s_add_i32 m0, s38, 0x2000
	s_nop 0
	global_load_lds_dwordx4 v146, s[28:29]
	s_add_u32 s28, s60, 0x80000
	s_addc_u32 s29, s61, 0
	s_mov_b32 m0, s69
	s_nop 0
	global_load_lds_dwordx4 v0, s[28:29]
	s_mov_b32 m0, s70
	s_nop 0
	global_load_lds_dwordx4 v146, s[28:29]
	s_add_i32 s38, 0, 0x18000
	ds_read_b128 v[98:101], v226 offset:32768
	ds_read_b128 v[102:105], v226 offset:33792
	ds_read_b128 v[106:109], v226 offset:34816
	ds_read_b128 v[110:113], v226 offset:35840
	ds_read_b128 v[152:155], v171 offset:32768
	ds_read_b128 v[160:163], v171 offset:33792
	ds_read_b128 v[164:167], v171 offset:34816
	ds_read_b128 v[172:175], v171 offset:35840
	ds_read_b128 v[176:179], v171 offset:36864
	ds_read_b128 v[180:183], v171 offset:37888
	ds_read_b128 v[184:187], v171 offset:38912
	ds_read_b128 v[188:191], v171 offset:39936
	s_add_i32 s39, 0, 0x1c000
	ds_read_b128 v[192:195], v226 offset:49152
	ds_read_b128 v[196:199], v226 offset:50176
	ds_read_b128 v[200:203], v226 offset:51200
	ds_read_b128 v[204:207], v226 offset:52224
	s_waitcnt lgkmcnt(4)
	s_barrier
	s_waitcnt lgkmcnt(0)
	v_mfma_f32_16x16x32_bf16 v[142:145], v[98:101], v[152:155], v[142:145]
	v_mfma_f32_16x16x32_bf16 v[138:141], v[106:109], v[152:155], v[138:141]
	v_mfma_f32_16x16x32_bf16 v[126:129], v[98:101], v[164:167], v[126:129]
	v_mfma_f32_16x16x32_bf16 v[122:125], v[106:109], v[164:167], v[122:125]
	v_mfma_f32_16x16x32_bf16 v[94:97], v[98:101], v[176:179], v[94:97]
	v_mfma_f32_16x16x32_bf16 v[90:93], v[106:109], v[176:179], v[90:93]
	v_mfma_f32_16x16x32_bf16 v[86:89], v[98:101], v[184:187], v[86:89]
	v_mfma_f32_16x16x32_bf16 v[82:85], v[106:109], v[184:187], v[82:85]
	v_mfma_f32_16x16x32_bf16 v[142:145], v[102:105], v[160:163], v[142:145]
	v_mfma_f32_16x16x32_bf16 v[138:141], v[110:113], v[160:163], v[138:141]
	v_mfma_f32_16x16x32_bf16 v[126:129], v[102:105], v[172:175], v[126:129]
	v_mfma_f32_16x16x32_bf16 v[122:125], v[110:113], v[172:175], v[122:125]
	v_mfma_f32_16x16x32_bf16 v[94:97], v[102:105], v[180:183], v[94:97]
	v_mfma_f32_16x16x32_bf16 v[90:93], v[110:113], v[180:183], v[90:93]
	v_mfma_f32_16x16x32_bf16 v[86:89], v[102:105], v[188:191], v[86:89]
	v_mfma_f32_16x16x32_bf16 v[82:85], v[110:113], v[188:191], v[82:85]
	v_mfma_f32_16x16x32_bf16 v[134:137], v[192:195], v[152:155], v[134:137]
	v_mfma_f32_16x16x32_bf16 v[130:133], v[200:203], v[152:155], v[130:133]
	v_mfma_f32_16x16x32_bf16 v[118:121], v[192:195], v[164:167], v[118:121]
	v_mfma_f32_16x16x32_bf16 v[114:117], v[200:203], v[164:167], v[114:117]
	v_mfma_f32_16x16x32_bf16 v[78:81], v[192:195], v[176:179], v[78:81]
	v_mfma_f32_16x16x32_bf16 v[74:77], v[200:203], v[176:179], v[74:77]
	v_mfma_f32_16x16x32_bf16 v[70:73], v[192:195], v[184:187], v[70:73]
	v_mfma_f32_16x16x32_bf16 v[66:69], v[200:203], v[184:187], v[66:69]
	v_mfma_f32_16x16x32_bf16 v[134:137], v[196:199], v[160:163], v[134:137]
	v_mfma_f32_16x16x32_bf16 v[130:133], v[204:207], v[160:163], v[130:133]
	v_mfma_f32_16x16x32_bf16 v[118:121], v[196:199], v[172:175], v[118:121]
	v_mfma_f32_16x16x32_bf16 v[114:117], v[204:207], v[172:175], v[114:117]
	v_mfma_f32_16x16x32_bf16 v[78:81], v[196:199], v[180:183], v[78:81]
	v_mfma_f32_16x16x32_bf16 v[74:77], v[204:207], v[180:183], v[74:77]
	v_mfma_f32_16x16x32_bf16 v[70:73], v[196:199], v[188:191], v[70:73]
	v_mfma_f32_16x16x32_bf16 v[66:69], v[204:207], v[188:191], v[66:69]
	s_barrier
; #define PG8_STAGE(bufoff, gbase, voff) do { _Pragma("unroll") for (int _i = 0; _i < 2; ++_i) \
;         __builtin_amdgcn_global_load_lds((const unsigned*)((const char*)(gbase) + (voff)[_i]), (LAS unsigned*)(lds + (bufoff) + ldsw + _i * 8192), 16, 0, 0); } while (0)
; #define PG8_LDA(dst, b, h) do { _Pragma("unroll") for (int m = 0; m < 4; ++m) _Pragma("unroll") for (int k = 0; k < 2; ++k) dst[m][k] = *(const LAS bf16x8*)(lds + PG8_SA(b, h) + aoff + m * 2048 + k * 1024); } while (0)
; #define PG8_MMA(ai, bj, At, Bt) do { __builtin_amdgcn_s_setprio(1); _Pragma("unroll") for (int m = 0; m < 4; ++m) _Pragma("unroll") for (int n = 0; n < 2; ++n) _Pragma("unroll") for (int k = 0; k < 2; ++k) \
;         acc[ai][bj][m][n] = __builtin_amdgcn_mfma_f32_16x16x32_bf16(Bt[n][k], At[m][k], acc[ai][bj][m][n], 0, 0, 0); __builtin_amdgcn_s_setprio(0); } while (0)
; #define PG8_WAIT_V(n) asm volatile("s_waitcnt vmcnt(" #n ")" ::: "memory")
; #define PG8_WAIT_L(n) asm volatile("s_waitcnt lgkmcnt(" #n ")" ::: "memory")
; #define PG8_BAR __builtin_amdgcn_s_barrier()
; #define PG8_SCHED __builtin_amdgcn_sched_barrier(0)
;     __device__ __forceinline__ void operator()(const f32x4 (&acc)[2][2][4][2], const Unit& u, int wr, int wc, int fr, int fq) const {
;         const bool lat = u.pm < 64; const int r = lat ? (u.pm >> 3) : 8;
;         const float* s = lat ? src_lat : src_ctx; float* d = lat ? dst_lat : dst_ctx;
;         const int row0 = (lat ? u.pm : u.pm - 64) * BM + wr * 64 + fr, col0 = u.pn * BM + wc * 32 + 4 * fq;
; template <class Epi, class Sched>
; __device__ __forceinline__ void gemm_phase(LAS unsigned char* lds, const Gemm g, const Sched& S, const Epi& E) {
;     ...
;             PG8_LDA(At, 1, 1); PG8_STAGE(PG8_SA(1, 0), a3, voffA);
;             PG8_BAR; PG8_WAIT_L(0); PG8_MMA(1, 0, At, B0); PG8_BAR; PG8_SCHED;
;             PG8_STAGE(PG8_SB(1, 1), b3 + hstep, voffB);
;             PG8_WAIT_V(6); PG8_BAR; PG8_MMA(1, 1, At, B1); PG8_BAR;
;         }
;         E(acc, cur, wr, wc, fr, fq);
;         if (!has_next) break;
	s_add_i32 s28, s38, s67
	s_add_u32 s100, s58, s36
	s_addc_u32 s101, s59, s37
	s_mov_b32 m0, s28
	s_nop 0
	global_load_lds_dwordx4 v0, s[100:101]
	s_add_i32 m0, s28, 0x2000
	s_nop 0
	global_load_lds_dwordx4 v146, s[100:101]
	s_mov_b32 m0, s72
	s_add_u32 s100, s60, s36
	s_addc_u32 s101, s61, s37
	global_load_lds_dwordx4 v0, s[100:101]
	s_mov_b32 m0, s73
	s_nop 0
	global_load_lds_dwordx4 v146, s[100:101]
	ds_read_b128 v[152:155], v171 offset:49152
	ds_read_b128 v[160:163], v171 offset:50176
	ds_read_b128 v[164:167], v171 offset:51200
	ds_read_b128 v[172:175], v171 offset:52224
	ds_read_b128 v[176:179], v171 offset:53248
	ds_read_b128 v[180:183], v171 offset:54272
	ds_read_b128 v[184:187], v171 offset:55296
	ds_read_b128 v[188:191], v171 offset:56320
	s_waitcnt vmcnt(4)
	s_waitcnt lgkmcnt(0)
	s_barrier
	v_mfma_f32_16x16x32_bf16 v[62:65], v[98:101], v[152:155], v[62:65]
	v_mfma_f32_16x16x32_bf16 v[58:61], v[106:109], v[152:155], v[58:61]
	v_mfma_f32_16x16x32_bf16 v[46:49], v[98:101], v[164:167], v[46:49]
	v_mfma_f32_16x16x32_bf16 v[42:45], v[106:109], v[164:167], v[42:45]
	v_mfma_f32_16x16x32_bf16 v[30:33], v[98:101], v[176:179], v[30:33]
	v_mfma_f32_16x16x32_bf16 v[26:29], v[106:109], v[176:179], v[26:29]
	v_mfma_f32_16x16x32_bf16 v[22:25], v[98:101], v[184:187], v[22:25]
	v_mfma_f32_16x16x32_bf16 v[18:21], v[106:109], v[184:187], v[18:21]
	v_mfma_f32_16x16x32_bf16 v[62:65], v[102:105], v[160:163], v[62:65]
	v_mfma_f32_16x16x32_bf16 v[58:61], v[110:113], v[160:163], v[58:61]
	v_mfma_f32_16x16x32_bf16 v[46:49], v[102:105], v[172:175], v[46:49]
	v_mfma_f32_16x16x32_bf16 v[42:45], v[110:113], v[172:175], v[42:45]
	v_mfma_f32_16x16x32_bf16 v[30:33], v[102:105], v[180:183], v[30:33]
	v_mfma_f32_16x16x32_bf16 v[26:29], v[110:113], v[180:183], v[26:29]
	v_mfma_f32_16x16x32_bf16 v[22:25], v[102:105], v[188:191], v[22:25]
	v_mfma_f32_16x16x32_bf16 v[18:21], v[110:113], v[188:191], v[18:21]
	s_add_u32 s28, s58, 0x80080
	s_addc_u32 s29, s59, 0
	s_add_i32 s38, s39, s67
	s_mov_b32 m0, s38
	s_nop 0
	global_load_lds_dwordx4 v0, s[28:29]
	s_add_i32 m0, s38, 0x2000
	s_nop 0
	global_load_lds_dwordx4 v146, s[28:29]
	v_mfma_f32_16x16x32_bf16 v[54:57], v[192:195], v[152:155], v[54:57]
	v_mfma_f32_16x16x32_bf16 v[50:53], v[200:203], v[152:155], v[50:53]
	v_mfma_f32_16x16x32_bf16 v[38:41], v[192:195], v[164:167], v[38:41]
	v_mfma_f32_16x16x32_bf16 v[34:37], v[200:203], v[164:167], v[34:37]
	v_mfma_f32_16x16x32_bf16 v[14:17], v[192:195], v[176:179], v[14:17]
	v_mfma_f32_16x16x32_bf16 v[10:13], v[200:203], v[176:179], v[10:13]
	v_mfma_f32_16x16x32_bf16 v[6:9], v[192:195], v[184:187], v[6:9]
	v_mfma_f32_16x16x32_bf16 v[2:5], v[200:203], v[184:187], v[2:5]
	v_mfma_f32_16x16x32_bf16 v[54:57], v[196:199], v[160:163], v[54:57]
	v_mfma_f32_16x16x32_bf16 v[50:53], v[204:207], v[160:163], v[50:53]
	v_mfma_f32_16x16x32_bf16 v[38:41], v[196:199], v[172:175], v[38:41]
	v_mfma_f32_16x16x32_bf16 v[34:37], v[204:207], v[172:175], v[34:37]
	v_mfma_f32_16x16x32_bf16 v[14:17], v[196:199], v[180:183], v[14:17]
	v_mfma_f32_16x16x32_bf16 v[10:13], v[204:207], v[180:183], v[10:13]
	v_mfma_f32_16x16x32_bf16 v[6:9], v[196:199], v[188:191], v[6:9]
	v_mfma_f32_16x16x32_bf16 v[2:5], v[204:207], v[188:191], v[2:5]
	s_add_i32 s81, s81, 2
	s_add_u32 s79, s79, 0x100
	s_addc_u32 s80, s80, 0
	s_cmp_gt_u32 s81, 29
	s_mov_b64 s[28:29], s[56:57]
	s_barrier
	s_cbranch_scc0 .LBB0_99
	s_cmp_lt_i32 s8, 64
	s_cselect_b64 s[58:59], -1, 0
	s_cmp_gt_i32 s8, 63
	s_cbranch_scc0 .LBB0_90
	s_mov_b64 s[60:61], 0x18000
	s_mov_b64 s[28:29], s[46:47]
	s_mov_b64 s[56:57], s[24:25]
	s_branch .LBB0_91

; __device__ __forceinline__ int tid_o() { int t = (int)threadIdx.x; asm volatile("" : "+v"(t)); return t; }
; #define PG8_STAGE(bufoff, gbase, voff) do { _Pragma("unroll") for (int _i = 0; _i < 2; ++_i) \
;         __builtin_amdgcn_global_load_lds((const unsigned*)((const char*)(gbase) + (voff)[_i]), (LAS unsigned*)(lds + (bufoff) + ldsw + _i * 8192), 16, 0, 0); } while (0)
; #define PG8_WAIT_V(n) asm volatile("s_waitcnt vmcnt(" #n ")" ::: "memory")
; #define PG8_BAR __builtin_amdgcn_s_barrier()
; template <class Epi, class Sched>
; __device__ __forceinline__ void gemm_phase(LAS unsigned char* lds, const Gemm g, const Sched& S, const Epi& E) {
;     const int tid = tid_o(), wid = __builtin_amdgcn_readfirstlane(tid >> 6), lane = tid & 63, wr = wid >> 2, wc = wid & 3, fr = lane & 15, fq = lane >> 4;
;     const int K = g.K, nt = K / BK;
;     unsigned voffA[2], voffB[2];
; #pragma unroll
;     for (int i = 0; i < 2; ++i) { int R, C; stage_rc(tid * 16 + i * 8192, R, C); const int Rb = Epi::PERM ? ((R & ~31) + perm32(R & 31)) : R;
;         voffA[i] = (unsigned)(R * g.ld + C) * 2u; voffB[i] = (unsigned)(Rb * g.ld + C) * 2u; }
;     const size_t kstep = (size_t)(BK * 2);
;     const size_t hstep = (size_t)HALF * g.ld * 2;
;     const size_t tstep = 2 * hstep, sstep = (size_t)K * 2;
;     const unsigned ldsw = (unsigned)wid * 1024u;
;     const int aoff = lds_byte(wr * 64 + fr, fq * 8), boff = lds_byte(wc * 32 + fr, fq * 8);
;     ...
;     const char* cA = (const char*)g.A + (size_t)cur.pm * tstep + (size_t)cur.ks * sstep; const char* cB = (const char*)g.Bt + (size_t)cur.pn * tstep + (size_t)cur.ks * sstep;
;     PG8_STAGE(PG8_SB(0, 0), cB, voffB); PG8_STAGE(PG8_SA(0, 0), cA, voffA); PG8_STAGE(PG8_SB(0, 1), cB + hstep, voffB); PG8_STAGE(PG8_SA(0, 1), cA + hstep, voffA);
;     if (wr == 1) PG8_BAR;
;     PG8_WAIT_V(4); PG8_BAR;
;     PG8_STAGE(PG8_SB(1, 0), cB + kstep, voffB); PG8_STAGE(PG8_SA(1, 0), cA + kstep, voffA); PG8_STAGE(PG8_SB(1, 1), cB + hstep + kstep, voffB);
;     PG8_WAIT_V(6); PG8_BAR;
.LBB0_109:
	s_waitcnt vmcnt(0)
	v_bfe_u32 v20, v10, 4, 2
	v_and_b32_e32 v11, 15, v10
	v_lshlrev_b32_e32 v21, 4, v20
	v_lshlrev_b32_e32 v10, 2, v10
	v_lshl_or_b32 v136, s29, 6, v11
	v_lshl_or_b32 v11, v11, 6, v21
	s_lshl_b32 s11, s29, 13
	v_and_b32_e32 v10, 32, v10
	v_bitop3_b32 v21, v11, s11, v10 bitop3:0xde
	s_lshl_b32 s11, s28, 5
	s_and_b32 s11, s11, 0x60
	v_lshl_add_u64 v[12:13], s[54:55], 0, v[0:1]
	v_mov_b32_e32 v131, v1
	s_lshl_b32 s28, s11, 7
	v_lshl_add_u64 v[14:15], s[54:55], 0, v[130:131]
	v_bitop3_b32 v137, v11, s28, v10 bitop3:0xde
	v_add_u32_e32 v226, 0x10000, v137
	s_add_i32 m0, s25, 0x18000
	v_lshl_add_u64 v[10:11], v[12:13], 0, s[36:37]
	v_lshl_add_u64 v[16:17], s[52:53], 0, v[0:1]
	s_waitcnt vmcnt(4)
	s_barrier
	global_load_lds_dwordx4 v[10:11], off
	v_lshl_add_u64 v[10:11], v[14:15], 0, s[36:37]
	s_add_i32 m0, s25, 0x1a000
	s_add_i32 s68, s25, 0x8000
	s_add_i32 s69, s25, 0xa000
	v_lshl_add_u64 v[18:19], s[52:53], 0, v[130:131]
	global_load_lds_dwordx4 v[10:11], off
	v_lshl_add_u64 v[10:11], v[16:17], 0, s[36:37]
	s_mov_b32 m0, s68
	s_add_u32 s28, s54, 0x80080
	global_load_lds_dwordx4 v[10:11], off
	v_lshl_add_u64 v[10:11], v[18:19], 0, s[36:37]
	s_mov_b32 m0, s69
	s_addc_u32 s29, s55, 0
	global_load_lds_dwordx4 v[10:11], off
	s_add_i32 m0, s25, 0x1c000
	v_lshl_add_u64 v[10:11], s[28:29], 0, v[0:1]
	global_load_lds_dwordx4 v[10:11], off
	v_lshl_add_u64 v[10:11], s[28:29], 0, v[130:131]
	s_add_i32 m0, s25, 0x1e000
	v_lshlrev_b32_e32 v2, 14, v2
	global_load_lds_dwordx4 v[10:11], off
	v_and_b32_e32 v2, 0x7fff8000, v2
	v_lshl_add_u32 v2, v3, 11, v2
	v_or_b32_e32 v2, v2, v4
	v_add_lshl_u32 v2, v2, v5, 1
	v_mov_b32_e32 v3, v1
	s_mov_b64 s[28:29], 0x80080
	v_lshl_add_u64 v[132:133], v[2:3], 0, s[28:29]
	v_lshlrev_b32_e32 v2, 14, v7
	v_and_b32_e32 v2, 0x7fff8000, v2
	v_lshl_add_u32 v2, v6, 11, v2
	s_waitcnt vmcnt(6)
	v_or_b32_e32 v2, v2, v8
	v_add_lshl_u32 v2, v2, v9, 1
	v_lshl_or_b32 v138, v20, 2, s11
	v_lshl_add_u64 v[134:135], v[2:3], 0, s[28:29]
	s_mov_b32 s70, 0
	v_add_u32_e32 v139, 0, v21
	s_barrier

; #define PG8_STAGE(bufoff, gbase, voff) do { _Pragma("unroll") for (int _i = 0; _i < 2; ++_i) \
;         __builtin_amdgcn_global_load_lds((const unsigned*)((const char*)(gbase) + (voff)[_i]), (LAS unsigned*)(lds + (bufoff) + ldsw + _i * 8192), 16, 0, 0); } while (0)
; #define PG8_LDA(dst, b, h) do { _Pragma("unroll") for (int m = 0; m < 4; ++m) _Pragma("unroll") for (int k = 0; k < 2; ++k) dst[m][k] = *(const LAS bf16x8*)(lds + PG8_SA(b, h) + aoff + m * 2048 + k * 1024); } while (0)
; #define PG8_LDB(dst, b, h) do { _Pragma("unroll") for (int n = 0; n < 2; ++n) _Pragma("unroll") for (int k = 0; k < 2; ++k) dst[n][k] = *(const LAS bf16x8*)(lds + PG8_SB(b, h) + boff + n * 2048 + k * 1024); } while (0)
; #define PG8_WAIT_V(n) asm volatile("s_waitcnt vmcnt(" #n ")" ::: "memory")
; #define PG8_WAIT_L(n) asm volatile("s_waitcnt lgkmcnt(" #n ")" ::: "memory")
; #define PG8_BAR __builtin_amdgcn_s_barrier()
; #define PG8_SCHED __builtin_amdgcn_sched_barrier(0)
; template <class Epi, class Sched>
; __device__ __forceinline__ void gemm_phase(LAS unsigned char* lds, const Gemm g, const Sched& S, const Epi& E) {
;     ...
;         const bool has_next = S.next(ui + 1, nxt);
;         const char* nA = has_next ? (const char*)g.A + (size_t)nxt.pm * tstep + (size_t)nxt.ks * sstep : cA; const char* nB = has_next ? (const char*)g.Bt + (size_t)nxt.pn * tstep + (size_t)nxt.ks * sstep : cB;
;         for (int t = 0; t < nt; t += 2) {
;             const bool last = (t == nt - 2);
;             const char* a1 = cA + (size_t)(t + 1) * kstep;
;             const char* a2 = last ? nA : cA + (size_t)(t + 2) * kstep; const char* b2 = last ? nB : cB + (size_t)(t + 2) * kstep;
;             const char* a3 = a2 + kstep; const char* b3 = b2 + kstep;
;             PG8_LDB(B0, 0, 0); PG8_SCHED; PG8_LDA(At, 0, 0); PG8_STAGE(PG8_SA(1, 1), a1 + hstep, voffA);
;             PG8_WAIT_L(8); PG8_BAR; PG8_WAIT_L(0); PG8_MMA(0, 0, At, B0); PG8_BAR; PG8_SCHED;
;             PG8_LDB(B1, 0, 1); PG8_STAGE(PG8_SB(0, 0), b2, voffB);
;             PG8_BAR; PG8_WAIT_L(0); PG8_MMA(0, 1, At, B1); PG8_BAR;
;             PG8_LDA(At, 0, 1); PG8_STAGE(PG8_SA(0, 0), a2, voffA);
;             PG8_BAR; PG8_WAIT_L(0); PG8_MMA(1, 0, At, B0); PG8_BAR; PG8_SCHED;
;             PG8_STAGE(PG8_SB(0, 1), b2 + hstep, voffB);
;             PG8_WAIT_V(6); PG8_BAR; PG8_MMA(1, 1, At, B1); PG8_BAR;
.LBB0_113:
	s_add_u32 s54, s52, 0x100
	s_addc_u32 s55, s53, 0
	s_cmp_eq_u32 s73, 4
	s_cselect_b32 s59, s11, s55
	s_cselect_b32 s58, s29, s54
	s_cselect_b32 s57, s41, s72
	s_cselect_b32 s56, s45, s71
	s_add_i32 m0, s25, 0xc000
	s_nop 0
	global_load_lds_dwordx4 v134, s[52:53]
	s_add_i32 m0, s25, 0xe000
	s_nop 0
	global_load_lds_dwordx4 v132, s[52:53]
	s_add_i32 s38, 0, 0x10000
	ds_read_b128 v[140:143], v226
	ds_read_b128 v[144:147], v226 offset:1024
	ds_read_b128 v[148:151], v226 offset:2048
	ds_read_b128 v[152:155], v226 offset:3072
	ds_read_b128 v[160:163], v139
	ds_read_b128 v[164:167], v139 offset:1024
	ds_read_b128 v[168:171], v139 offset:2048
	ds_read_b128 v[172:175], v139 offset:3072
	ds_read_b128 v[176:179], v139 offset:4096
	ds_read_b128 v[180:183], v139 offset:5120
	ds_read_b128 v[184:187], v139 offset:6144
	ds_read_b128 v[188:191], v139 offset:7168
	s_add_i32 s52, 0, 0x14000
	ds_read_b128 v[192:195], v226 offset:16384
	ds_read_b128 v[196:199], v226 offset:17408
	ds_read_b128 v[200:203], v226 offset:18432
	ds_read_b128 v[204:207], v226 offset:19456
	s_waitcnt lgkmcnt(4)
	s_barrier
	s_waitcnt lgkmcnt(0)
	v_mfma_f32_16x16x32_bf16 v[126:129], v[140:143], v[160:163], v[126:129]
	v_mfma_f32_16x16x32_bf16 v[122:125], v[148:151], v[160:163], v[122:125]
	v_mfma_f32_16x16x32_bf16 v[118:121], v[140:143], v[168:171], v[118:121]
	v_mfma_f32_16x16x32_bf16 v[114:117], v[148:151], v[168:171], v[114:117]
	v_mfma_f32_16x16x32_bf16 v[106:109], v[140:143], v[176:179], v[106:109]
	v_mfma_f32_16x16x32_bf16 v[98:101], v[148:151], v[176:179], v[98:101]
	v_mfma_f32_16x16x32_bf16 v[90:93], v[140:143], v[184:187], v[90:93]
	v_mfma_f32_16x16x32_bf16 v[82:85], v[148:151], v[184:187], v[82:85]
	v_mfma_f32_16x16x32_bf16 v[126:129], v[144:147], v[164:167], v[126:129]
	v_mfma_f32_16x16x32_bf16 v[122:125], v[152:155], v[164:167], v[122:125]
	v_mfma_f32_16x16x32_bf16 v[118:121], v[144:147], v[172:175], v[118:121]
	v_mfma_f32_16x16x32_bf16 v[114:117], v[152:155], v[172:175], v[114:117]
	v_mfma_f32_16x16x32_bf16 v[106:109], v[144:147], v[180:183], v[106:109]
	v_mfma_f32_16x16x32_bf16 v[98:101], v[152:155], v[180:183], v[98:101]
	v_mfma_f32_16x16x32_bf16 v[90:93], v[144:147], v[188:191], v[90:93]
	v_mfma_f32_16x16x32_bf16 v[82:85], v[152:155], v[188:191], v[82:85]
	v_mfma_f32_16x16x32_bf16 v[110:113], v[192:195], v[160:163], v[110:113]
	v_mfma_f32_16x16x32_bf16 v[102:105], v[200:203], v[160:163], v[102:105]
	v_mfma_f32_16x16x32_bf16 v[94:97], v[192:195], v[168:171], v[94:97]
	v_mfma_f32_16x16x32_bf16 v[86:89], v[200:203], v[168:171], v[86:89]
	v_mfma_f32_16x16x32_bf16 v[78:81], v[192:195], v[176:179], v[78:81]
	v_mfma_f32_16x16x32_bf16 v[74:77], v[200:203], v[176:179], v[74:77]
	v_mfma_f32_16x16x32_bf16 v[70:73], v[192:195], v[184:187], v[70:73]
	v_mfma_f32_16x16x32_bf16 v[66:69], v[200:203], v[184:187], v[66:69]
	v_mfma_f32_16x16x32_bf16 v[110:113], v[196:199], v[164:167], v[110:113]
	v_mfma_f32_16x16x32_bf16 v[102:105], v[204:207], v[164:167], v[102:105]
	v_mfma_f32_16x16x32_bf16 v[94:97], v[196:199], v[172:175], v[94:97]
	v_mfma_f32_16x16x32_bf16 v[86:89], v[204:207], v[172:175], v[86:89]
	v_mfma_f32_16x16x32_bf16 v[78:81], v[196:199], v[180:183], v[78:81]
	v_mfma_f32_16x16x32_bf16 v[74:77], v[204:207], v[180:183], v[74:77]
	v_mfma_f32_16x16x32_bf16 v[70:73], v[196:199], v[188:191], v[70:73]
	v_mfma_f32_16x16x32_bf16 v[66:69], v[204:207], v[188:191], v[66:69]
	s_barrier
	s_add_i32 s38, s38, s65
	s_mov_b32 m0, s38
	s_nop 0
	global_load_lds_dwordx4 v0, s[56:57]
	s_add_i32 m0, s38, 0x2000
	s_nop 0
	global_load_lds_dwordx4 v130, s[56:57]
	s_mov_b32 m0, s25
	s_nop 0
	global_load_lds_dwordx4 v0, s[58:59]
	s_mov_b32 m0, s27
	s_nop 0
	global_load_lds_dwordx4 v130, s[58:59]
	ds_read_b128 v[160:163], v139 offset:16384
	ds_read_b128 v[164:167], v139 offset:17408
	ds_read_b128 v[168:171], v139 offset:18432
	ds_read_b128 v[172:175], v139 offset:19456
	ds_read_b128 v[176:179], v139 offset:20480
	ds_read_b128 v[180:183], v139 offset:21504
	ds_read_b128 v[184:187], v139 offset:22528
	ds_read_b128 v[188:191], v139 offset:23552
	s_waitcnt vmcnt(4)
	s_waitcnt lgkmcnt(0)
	s_barrier
	v_mfma_f32_16x16x32_bf16 v[62:65], v[140:143], v[160:163], v[62:65]
	v_mfma_f32_16x16x32_bf16 v[58:61], v[148:151], v[160:163], v[58:61]
	v_mfma_f32_16x16x32_bf16 v[54:57], v[140:143], v[168:171], v[54:57]
	v_mfma_f32_16x16x32_bf16 v[50:53], v[148:151], v[168:171], v[50:53]
	v_mfma_f32_16x16x32_bf16 v[38:41], v[140:143], v[176:179], v[38:41]
	v_mfma_f32_16x16x32_bf16 v[34:37], v[148:151], v[176:179], v[34:37]
	v_mfma_f32_16x16x32_bf16 v[22:25], v[140:143], v[184:187], v[22:25]
	v_mfma_f32_16x16x32_bf16 v[18:21], v[148:151], v[184:187], v[18:21]
	v_mfma_f32_16x16x32_bf16 v[62:65], v[144:147], v[164:167], v[62:65]
	v_mfma_f32_16x16x32_bf16 v[58:61], v[152:155], v[164:167], v[58:61]
	v_mfma_f32_16x16x32_bf16 v[54:57], v[144:147], v[172:175], v[54:57]
	v_mfma_f32_16x16x32_bf16 v[50:53], v[152:155], v[172:175], v[50:53]
	v_mfma_f32_16x16x32_bf16 v[38:41], v[144:147], v[180:183], v[38:41]
	v_mfma_f32_16x16x32_bf16 v[34:37], v[152:155], v[180:183], v[34:37]
	v_mfma_f32_16x16x32_bf16 v[22:25], v[144:147], v[188:191], v[22:25]
	v_mfma_f32_16x16x32_bf16 v[18:21], v[152:155], v[188:191], v[18:21]
	v_mfma_f32_16x16x32_bf16 v[46:49], v[192:195], v[160:163], v[46:49]
	v_mfma_f32_16x16x32_bf16 v[42:45], v[200:203], v[160:163], v[42:45]
	v_mfma_f32_16x16x32_bf16 v[30:33], v[192:195], v[168:171], v[30:33]
	v_mfma_f32_16x16x32_bf16 v[26:29], v[200:203], v[168:171], v[26:29]
	v_mfma_f32_16x16x32_bf16 v[14:17], v[192:195], v[176:179], v[14:17]
	v_mfma_f32_16x16x32_bf16 v[10:13], v[200:203], v[176:179], v[10:13]
	v_mfma_f32_16x16x32_bf16 v[6:9], v[192:195], v[184:187], v[6:9]
	v_mfma_f32_16x16x32_bf16 v[2:5], v[200:203], v[184:187], v[2:5]
	v_mfma_f32_16x16x32_bf16 v[46:49], v[196:199], v[164:167], v[46:49]
	v_mfma_f32_16x16x32_bf16 v[42:45], v[204:207], v[164:167], v[42:45]
	v_mfma_f32_16x16x32_bf16 v[30:33], v[196:199], v[172:175], v[30:33]
	v_mfma_f32_16x16x32_bf16 v[26:29], v[204:207], v[172:175], v[26:29]
	v_mfma_f32_16x16x32_bf16 v[14:17], v[196:199], v[180:183], v[14:17]
	v_mfma_f32_16x16x32_bf16 v[10:13], v[204:207], v[180:183], v[10:13]
	v_mfma_f32_16x16x32_bf16 v[6:9], v[196:199], v[188:191], v[6:9]
	v_mfma_f32_16x16x32_bf16 v[2:5], v[204:207], v[188:191], v[2:5]
	s_barrier
; #define PG8_STAGE(bufoff, gbase, voff) do { _Pragma("unroll") for (int _i = 0; _i < 2; ++_i) \
;         __builtin_amdgcn_global_load_lds((const unsigned*)((const char*)(gbase) + (voff)[_i]), (LAS unsigned*)(lds + (bufoff) + ldsw + _i * 8192), 16, 0, 0); } while (0)
; #define PG8_LDA(dst, b, h) do { _Pragma("unroll") for (int m = 0; m < 4; ++m) _Pragma("unroll") for (int k = 0; k < 2; ++k) dst[m][k] = *(const LAS bf16x8*)(lds + PG8_SA(b, h) + aoff + m * 2048 + k * 1024); } while (0)
; #define PG8_LDB(dst, b, h) do { _Pragma("unroll") for (int n = 0; n < 2; ++n) _Pragma("unroll") for (int k = 0; k < 2; ++k) dst[n][k] = *(const LAS bf16x8*)(lds + PG8_SB(b, h) + boff + n * 2048 + k * 1024); } while (0)
; #define PG8_MMA(ai, bj, At, Bt) do { __builtin_amdgcn_s_setprio(1); _Pragma("unroll") for (int m = 0; m < 4; ++m) _Pragma("unroll") for (int n = 0; n < 2; ++n) _Pragma("unroll") for (int k = 0; k < 2; ++k) \
;         acc[ai][bj][m][n] = __builtin_amdgcn_mfma_f32_16x16x32_bf16(Bt[n][k], At[m][k], acc[ai][bj][m][n], 0, 0, 0); __builtin_amdgcn_s_setprio(0); } while (0)
; #define PG8_WAIT_V(n) asm volatile("s_waitcnt vmcnt(" #n ")" ::: "memory")
; #define PG8_WAIT_L(n) asm volatile("s_waitcnt lgkmcnt(" #n ")" ::: "memory")
; #define PG8_BAR __builtin_amdgcn_s_barrier()
; #define PG8_SCHED __builtin_amdgcn_sched_barrier(0)
; template <class Epi, class Sched>
; __device__ __forceinline__ void gemm_phase(LAS unsigned char* lds, const Gemm g, const Sched& S, const Epi& E) {
;     ...
;             PG8_STAGE(PG8_SB(0, 1), b2 + hstep, voffB);
;             PG8_WAIT_V(6); PG8_BAR; PG8_MMA(1, 1, At, B1); PG8_BAR;
;             PG8_LDB(B0, 1, 0); PG8_SCHED; PG8_LDA(At, 1, 0); PG8_STAGE(PG8_SA(0, 1), a2 + hstep, voffA);
;             PG8_WAIT_L(8); PG8_BAR; PG8_WAIT_L(0); PG8_MMA(0, 0, At, B0); PG8_BAR; PG8_SCHED;
;             PG8_LDB(B1, 1, 1); PG8_STAGE(PG8_SB(1, 0), b3, voffB);
;             PG8_BAR; PG8_WAIT_L(0); PG8_MMA(0, 1, At, B1); PG8_BAR;
;             PG8_LDA(At, 1, 1); PG8_STAGE(PG8_SA(1, 0), a3, voffA);
;             PG8_BAR; PG8_WAIT_L(0); PG8_MMA(1, 0, At, B0); PG8_BAR; PG8_SCHED;
	s_add_u32 s38, s56, 0x80000
	s_addc_u32 s39, s57, 0
	s_add_i32 s52, s52, s65
	s_mov_b32 m0, s52
	s_nop 0
	global_load_lds_dwordx4 v0, s[38:39]
	s_add_i32 m0, s52, 0x2000
	s_nop 0
	global_load_lds_dwordx4 v130, s[38:39]
	s_add_u32 s38, s58, 0x80000
	s_addc_u32 s39, s59, 0
	s_mov_b32 m0, s66
	s_nop 0
	global_load_lds_dwordx4 v0, s[38:39]
	s_mov_b32 m0, s67
	s_nop 0
	global_load_lds_dwordx4 v130, s[38:39]
	s_add_i32 s52, 0, 0x18000
	ds_read_b128 v[140:143], v226 offset:32768
	ds_read_b128 v[144:147], v226 offset:33792
	ds_read_b128 v[148:151], v226 offset:34816
	ds_read_b128 v[152:155], v226 offset:35840
	ds_read_b128 v[160:163], v139 offset:32768
	ds_read_b128 v[164:167], v139 offset:33792
	ds_read_b128 v[168:171], v139 offset:34816
	ds_read_b128 v[172:175], v139 offset:35840
	ds_read_b128 v[176:179], v139 offset:36864
	ds_read_b128 v[180:183], v139 offset:37888
	ds_read_b128 v[184:187], v139 offset:38912
	ds_read_b128 v[188:191], v139 offset:39936
	s_add_i32 s53, 0, 0x1c000
	ds_read_b128 v[192:195], v226 offset:49152
	ds_read_b128 v[196:199], v226 offset:50176
	ds_read_b128 v[200:203], v226 offset:51200
	ds_read_b128 v[204:207], v226 offset:52224
	s_waitcnt lgkmcnt(4)
	s_barrier
	s_waitcnt lgkmcnt(0)
	v_mfma_f32_16x16x32_bf16 v[126:129], v[140:143], v[160:163], v[126:129]
	v_mfma_f32_16x16x32_bf16 v[122:125], v[148:151], v[160:163], v[122:125]
	v_mfma_f32_16x16x32_bf16 v[118:121], v[140:143], v[168:171], v[118:121]
	v_mfma_f32_16x16x32_bf16 v[114:117], v[148:151], v[168:171], v[114:117]
	v_mfma_f32_16x16x32_bf16 v[106:109], v[140:143], v[176:179], v[106:109]
	v_mfma_f32_16x16x32_bf16 v[98:101], v[148:151], v[176:179], v[98:101]
	v_mfma_f32_16x16x32_bf16 v[90:93], v[140:143], v[184:187], v[90:93]
	v_mfma_f32_16x16x32_bf16 v[82:85], v[148:151], v[184:187], v[82:85]
	v_mfma_f32_16x16x32_bf16 v[126:129], v[144:147], v[164:167], v[126:129]
	v_mfma_f32_16x16x32_bf16 v[122:125], v[152:155], v[164:167], v[122:125]
	v_mfma_f32_16x16x32_bf16 v[118:121], v[144:147], v[172:175], v[118:121]
	v_mfma_f32_16x16x32_bf16 v[114:117], v[152:155], v[172:175], v[114:117]
	v_mfma_f32_16x16x32_bf16 v[106:109], v[144:147], v[180:183], v[106:109]
	v_mfma_f32_16x16x32_bf16 v[98:101], v[152:155], v[180:183], v[98:101]
	v_mfma_f32_16x16x32_bf16 v[90:93], v[144:147], v[188:191], v[90:93]
	v_mfma_f32_16x16x32_bf16 v[82:85], v[152:155], v[188:191], v[82:85]
	v_mfma_f32_16x16x32_bf16 v[110:113], v[192:195], v[160:163], v[110:113]
	v_mfma_f32_16x16x32_bf16 v[102:105], v[200:203], v[160:163], v[102:105]
	v_mfma_f32_16x16x32_bf16 v[94:97], v[192:195], v[168:171], v[94:97]
	v_mfma_f32_16x16x32_bf16 v[86:89], v[200:203], v[168:171], v[86:89]
	v_mfma_f32_16x16x32_bf16 v[78:81], v[192:195], v[176:179], v[78:81]
	v_mfma_f32_16x16x32_bf16 v[74:77], v[200:203], v[176:179], v[74:77]
	v_mfma_f32_16x16x32_bf16 v[70:73], v[192:195], v[184:187], v[70:73]
	v_mfma_f32_16x16x32_bf16 v[66:69], v[200:203], v[184:187], v[66:69]
	v_mfma_f32_16x16x32_bf16 v[110:113], v[196:199], v[164:167], v[110:113]
	v_mfma_f32_16x16x32_bf16 v[102:105], v[204:207], v[164:167], v[102:105]
	v_mfma_f32_16x16x32_bf16 v[94:97], v[196:199], v[172:175], v[94:97]
	v_mfma_f32_16x16x32_bf16 v[86:89], v[204:207], v[172:175], v[86:89]
	v_mfma_f32_16x16x32_bf16 v[78:81], v[196:199], v[180:183], v[78:81]
	v_mfma_f32_16x16x32_bf16 v[74:77], v[204:207], v[180:183], v[74:77]
	v_mfma_f32_16x16x32_bf16 v[70:73], v[196:199], v[188:191], v[70:73]
	v_mfma_f32_16x16x32_bf16 v[66:69], v[204:207], v[188:191], v[66:69]
	s_barrier
	s_add_i32 s38, s52, s65
	s_add_u32 s100, s56, s36
	s_addc_u32 s101, s57, s37
	s_mov_b32 m0, s38
	s_nop 0
	global_load_lds_dwordx4 v0, s[100:101]
	s_add_i32 m0, s38, 0x2000
	s_nop 0
	global_load_lds_dwordx4 v130, s[100:101]
	s_mov_b32 m0, s68
	s_add_u32 s100, s58, s36
	s_addc_u32 s101, s59, s37
	global_load_lds_dwordx4 v0, s[100:101]
	s_mov_b32 m0, s69
	s_nop 0
	global_load_lds_dwordx4 v130, s[100:101]
	ds_read_b128 v[160:163], v139 offset:49152
	ds_read_b128 v[164:167], v139 offset:50176
	ds_read_b128 v[168:171], v139 offset:51200
	ds_read_b128 v[172:175], v139 offset:52224
	ds_read_b128 v[176:179], v139 offset:53248
	ds_read_b128 v[180:183], v139 offset:54272
	ds_read_b128 v[184:187], v139 offset:55296
	ds_read_b128 v[188:191], v139 offset:56320
	s_waitcnt vmcnt(4)
	s_waitcnt lgkmcnt(0)
	s_barrier
; #define PG8_STAGE(bufoff, gbase, voff) do { _Pragma("unroll") for (int _i = 0; _i < 2; ++_i) \
;         __builtin_amdgcn_global_load_lds((const unsigned*)((const char*)(gbase) + (voff)[_i]), (LAS unsigned*)(lds + (bufoff) + ldsw + _i * 8192), 16, 0, 0); } while (0)
; #define PG8_LDA(dst, b, h) do { _Pragma("unroll") for (int m = 0; m < 4; ++m) _Pragma("unroll") for (int k = 0; k < 2; ++k) dst[m][k] = *(const LAS bf16x8*)(lds + PG8_SA(b, h) + aoff + m * 2048 + k * 1024); } while (0)
; #define PG8_MMA(ai, bj, At, Bt) do { __builtin_amdgcn_s_setprio(1); _Pragma("unroll") for (int m = 0; m < 4; ++m) _Pragma("unroll") for (int n = 0; n < 2; ++n) _Pragma("unroll") for (int k = 0; k < 2; ++k) \
;         acc[ai][bj][m][n] = __builtin_amdgcn_mfma_f32_16x16x32_bf16(Bt[n][k], At[m][k], acc[ai][bj][m][n], 0, 0, 0); __builtin_amdgcn_s_setprio(0); } while (0)
; #define PG8_WAIT_V(n) asm volatile("s_waitcnt vmcnt(" #n ")" ::: "memory")
; #define PG8_WAIT_L(n) asm volatile("s_waitcnt lgkmcnt(" #n ")" ::: "memory")
; #define PG8_BAR __builtin_amdgcn_s_barrier()
; #define PG8_SCHED __builtin_amdgcn_sched_barrier(0)
;     __device__ __forceinline__ void operator()(const f32x4 (&acc)[2][2][4][2], const Unit& u, int wr, int wc, int fr, int fq) const {
;         const int row0 = u.pm * BM + wr * 64 + fr, col0 = u.pn * BM + wc * 32 + 4 * fq;
;         float* base = part + (size_t)u.ks * Mp * ldc;
; #pragma unroll
;         for (int ai = 0; ai < 2; ++ai)
; #pragma unroll
;             for (int m = 0; m < 4; ++m) { float* rowp = base + (size_t)(row0 + ai * HALF + m * 16) * ldc + col0;
; #pragma unroll
;                 for (int bj = 0; bj < 2; ++bj)
; #pragma unroll
;                     for (int n = 0; n < 2; ++n) *(f32x4*)(rowp + bj * HALF + n * 16) = acc[ai][bj][m][n]; }
; template <class Epi, class Sched>
; __device__ __forceinline__ void gemm_phase(LAS unsigned char* lds, const Gemm g, const Sched& S, const Epi& E) {
;     ...
;             PG8_LDA(At, 1, 1); PG8_STAGE(PG8_SA(1, 0), a3, voffA);
;             PG8_BAR; PG8_WAIT_L(0); PG8_MMA(1, 0, At, B0); PG8_BAR; PG8_SCHED;
;             PG8_STAGE(PG8_SB(1, 1), b3 + hstep, voffB);
;             PG8_WAIT_V(6); PG8_BAR; PG8_MMA(1, 1, At, B1); PG8_BAR;
;         }
;         E(acc, cur, wr, wc, fr, fq);
;         if (!has_next) break;
	v_mfma_f32_16x16x32_bf16 v[62:65], v[140:143], v[160:163], v[62:65]
	v_mfma_f32_16x16x32_bf16 v[58:61], v[148:151], v[160:163], v[58:61]
	v_mfma_f32_16x16x32_bf16 v[54:57], v[140:143], v[168:171], v[54:57]
	v_mfma_f32_16x16x32_bf16 v[50:53], v[148:151], v[168:171], v[50:53]
	v_mfma_f32_16x16x32_bf16 v[38:41], v[140:143], v[176:179], v[38:41]
	v_mfma_f32_16x16x32_bf16 v[34:37], v[148:151], v[176:179], v[34:37]
	v_mfma_f32_16x16x32_bf16 v[22:25], v[140:143], v[184:187], v[22:25]
	v_mfma_f32_16x16x32_bf16 v[18:21], v[148:151], v[184:187], v[18:21]
	v_mfma_f32_16x16x32_bf16 v[62:65], v[144:147], v[164:167], v[62:65]
	v_mfma_f32_16x16x32_bf16 v[58:61], v[152:155], v[164:167], v[58:61]
	v_mfma_f32_16x16x32_bf16 v[54:57], v[144:147], v[172:175], v[54:57]
	v_mfma_f32_16x16x32_bf16 v[50:53], v[152:155], v[172:175], v[50:53]
	v_mfma_f32_16x16x32_bf16 v[38:41], v[144:147], v[180:183], v[38:41]
	v_mfma_f32_16x16x32_bf16 v[34:37], v[152:155], v[180:183], v[34:37]
	v_mfma_f32_16x16x32_bf16 v[22:25], v[144:147], v[188:191], v[22:25]
	v_mfma_f32_16x16x32_bf16 v[18:21], v[152:155], v[188:191], v[18:21]
	s_add_u32 s38, s56, 0x80080
	s_addc_u32 s39, s57, 0
	s_add_i32 s52, s53, s65
	s_mov_b32 m0, s52
	s_nop 0
	global_load_lds_dwordx4 v0, s[38:39]
	s_add_i32 m0, s52, 0x2000
	s_nop 0
	global_load_lds_dwordx4 v130, s[38:39]
	v_mfma_f32_16x16x32_bf16 v[46:49], v[192:195], v[160:163], v[46:49]
	v_mfma_f32_16x16x32_bf16 v[42:45], v[200:203], v[160:163], v[42:45]
	v_mfma_f32_16x16x32_bf16 v[30:33], v[192:195], v[168:171], v[30:33]
	v_mfma_f32_16x16x32_bf16 v[26:29], v[200:203], v[168:171], v[26:29]
	v_mfma_f32_16x16x32_bf16 v[14:17], v[192:195], v[176:179], v[14:17]
	v_mfma_f32_16x16x32_bf16 v[10:13], v[200:203], v[176:179], v[10:13]
	v_mfma_f32_16x16x32_bf16 v[6:9], v[192:195], v[184:187], v[6:9]
	v_mfma_f32_16x16x32_bf16 v[2:5], v[200:203], v[184:187], v[2:5]
	v_mfma_f32_16x16x32_bf16 v[46:49], v[196:199], v[164:167], v[46:49]
	v_mfma_f32_16x16x32_bf16 v[42:45], v[204:207], v[164:167], v[42:45]
	v_mfma_f32_16x16x32_bf16 v[30:33], v[196:199], v[172:175], v[30:33]
	v_mfma_f32_16x16x32_bf16 v[26:29], v[204:207], v[172:175], v[26:29]
	v_mfma_f32_16x16x32_bf16 v[14:17], v[196:199], v[180:183], v[14:17]
	v_mfma_f32_16x16x32_bf16 v[10:13], v[204:207], v[180:183], v[10:13]
	v_mfma_f32_16x16x32_bf16 v[6:9], v[196:199], v[188:191], v[6:9]
	v_mfma_f32_16x16x32_bf16 v[2:5], v[204:207], v[188:191], v[2:5]
	s_add_i32 s73, s73, 2
	s_add_u32 s71, s71, 0x100
	s_addc_u32 s72, s72, 0
	s_cmp_gt_u32 s73, 5
	s_mov_b64 s[52:53], s[54:55]
	s_barrier
	s_cbranch_scc0 .LBB0_113
	s_ashr_i32 s11, s10, 31
	s_lshl_b64 s[10:11], s[10:11], 24
	v_lshl_or_b32 v140, s26, 8, v138
	s_add_u32 s10, s8, s10
	v_lshl_add_u32 v142, s24, 8, v136
	s_addc_u32 s11, s9, s11
	v_ashrrev_i32_e32 v141, 31, v140
	v_ashrrev_i32_e32 v143, 31, v142
	v_lshl_add_u64 v[140:141], v[140:141], 2, s[10:11]
	v_lshlrev_b64 v[144:145], 13, v[142:143]
	v_lshl_add_u64 v[144:145], v[140:141], 0, v[144:145]
	global_store_dwordx4 v[144:145], v[126:129], off
	global_store_dwordx4 v[144:145], v[122:125], off offset:64
	global_store_dwordx4 v[144:145], v[110:113], off offset:512
	global_store_dwordx4 v[144:145], v[102:105], off offset:576
	s_mov_b64 s[10:11], 0x100000
	s_mov_b32 s26, s40
	v_or_b32_e32 v102, 16, v142
	v_ashrrev_i32_e32 v103, 31, v102
	v_lshlrev_b64 v[102:103], 13, v[102:103]
	v_lshl_add_u64 v[102:103], v[140:141], 0, v[102:103]
	global_store_dwordx4 v[102:103], v[118:121], off
	global_store_dwordx4 v[102:103], v[114:117], off offset:64
	global_store_dwordx4 v[102:103], v[94:97], off offset:512
	global_store_dwordx4 v[102:103], v[86:89], off offset:576
	s_mov_b32 s24, s44
	s_mov_b64 s[54:55], s[50:51]
	v_or_b32_e32 v86, 32, v142
	v_ashrrev_i32_e32 v87, 31, v86
	v_lshlrev_b64 v[86:87], 13, v[86:87]
	v_lshl_add_u64 v[86:87], v[140:141], 0, v[86:87]
	global_store_dwordx4 v[86:87], v[106:109], off
	global_store_dwordx4 v[86:87], v[98:101], off offset:64
	global_store_dwordx4 v[86:87], v[78:81], off offset:512
	global_store_dwordx4 v[86:87], v[74:77], off offset:576
	s_mov_b64 s[52:53], s[48:49]
	s_nop 0
	v_or_b32_e32 v74, 48, v142
	v_ashrrev_i32_e32 v75, 31, v74
	v_lshlrev_b64 v[74:75], 13, v[74:75]
	v_lshl_add_u64 v[74:75], v[140:141], 0, v[74:75]
	global_store_dwordx4 v[74:75], v[90:93], off
	global_store_dwordx4 v[74:75], v[82:85], off offset:64
	global_store_dwordx4 v[74:75], v[70:73], off offset:512
	global_store_dwordx4 v[74:75], v[66:69], off offset:576
	s_nop 1
	v_add_co_u32_e32 v68, vcc, s93, v144
	v_lshl_add_u64 v[66:67], v[144:145], 0, s[10:11]
	s_nop 0
	v_addc_co_u32_e32 v69, vcc, 0, v145, vcc
	s_mov_b64 s[10:11], 0x120000
	global_store_dwordx4 v[68:69], v[62:65], off
	global_store_dwordx4 v[66:67], v[58:61], off offset:64
	global_store_dwordx4 v[66:67], v[46:49], off offset:512
	global_store_dwordx4 v[66:67], v[42:45], off offset:576
	s_nop 1
	v_lshl_add_u64 v[42:43], v[144:145], 0, s[10:11]
	s_mov_b32 s10, 0x120000
	v_add_co_u32_e32 v44, vcc, s10, v144
	s_mov_b64 s[10:11], 0x140000
	s_nop 0
	v_addc_co_u32_e32 v45, vcc, 0, v145, vcc
	global_store_dwordx4 v[44:45], v[54:57], off
	global_store_dwordx4 v[42:43], v[50:53], off offset:64
	global_store_dwordx4 v[42:43], v[30:33], off offset:512
	global_store_dwordx4 v[42:43], v[26:29], off offset:576
	s_nop 1
	v_lshl_add_u64 v[26:27], v[144:145], 0, s[10:11]
	s_mov_b32 s10, 0x140000
	v_add_co_u32_e32 v28, vcc, s10, v144
	s_mov_b64 s[10:11], 0x160000
	s_nop 0
	v_addc_co_u32_e32 v29, vcc, 0, v145, vcc
	global_store_dwordx4 v[28:29], v[38:41], off
	global_store_dwordx4 v[26:27], v[34:37], off offset:64
	global_store_dwordx4 v[26:27], v[14:17], off offset:512
	global_store_dwordx4 v[26:27], v[10:13], off offset:576
	s_nop 1
	v_add_co_u32_e32 v12, vcc, 0x160000, v144
	v_lshl_add_u64 v[10:11], v[144:145], 0, s[10:11]
	s_nop 0
	v_addc_co_u32_e32 v13, vcc, 0, v145, vcc
	s_and_b64 vcc, exec, s[46:47]
	s_mov_b32 s10, s28
	global_store_dwordx4 v[12:13], v[22:25], off
	global_store_dwordx4 v[10:11], v[18:21], off offset:64
	global_store_dwordx4 v[10:11], v[6:9], off offset:512
	global_store_dwordx4 v[10:11], v[2:5], off offset:576
	s_cbranch_vccz .LBB0_110
	s_waitcnt vmcnt(0)
	s_cmpk_gt_u32 s60, 0xff
	s_cbranch_scc1 .LBB0_117
	s_barrier

; __device__ __forceinline__ int tid_o() { int t = (int)threadIdx.x; asm volatile("" : "+v"(t)); return t; }
; #define PG8_STAGE(bufoff, gbase, voff) do { _Pragma("unroll") for (int _i = 0; _i < 2; ++_i) \
;         __builtin_amdgcn_global_load_lds((const unsigned*)((const char*)(gbase) + (voff)[_i]), (LAS unsigned*)(lds + (bufoff) + ldsw + _i * 8192), 16, 0, 0); } while (0)
; #define PG8_WAIT_V(n) asm volatile("s_waitcnt vmcnt(" #n ")" ::: "memory")
; #define PG8_BAR __builtin_amdgcn_s_barrier()
; template <class Epi, class Sched>
; __device__ __forceinline__ void gemm_phase(LAS unsigned char* lds, const Gemm g, const Sched& S, const Epi& E) {
;     const int tid = tid_o(), wid = __builtin_amdgcn_readfirstlane(tid >> 6), lane = tid & 63, wr = wid >> 2, wc = wid & 3, fr = lane & 15, fq = lane >> 4;
;     const int K = g.K, nt = K / BK;
;     unsigned voffA[2], voffB[2];
; #pragma unroll
;     for (int i = 0; i < 2; ++i) { int R, C; stage_rc(tid * 16 + i * 8192, R, C); const int Rb = Epi::PERM ? ((R & ~31) + perm32(R & 31)) : R;
;         voffA[i] = (unsigned)(R * g.ld + C) * 2u; voffB[i] = (unsigned)(Rb * g.ld + C) * 2u; }
;     const size_t kstep = (size_t)(BK * 2);
;     const size_t hstep = (size_t)HALF * g.ld * 2;
;     const size_t tstep = 2 * hstep, sstep = (size_t)K * 2;
;     const unsigned ldsw = (unsigned)wid * 1024u;
;     const int aoff = lds_byte(wr * 64 + fr, fq * 8), boff = lds_byte(wc * 32 + fr, fq * 8);
;     ...
;     const char* cA = (const char*)g.A + (size_t)cur.pm * tstep + (size_t)cur.ks * sstep; const char* cB = (const char*)g.Bt + (size_t)cur.pn * tstep + (size_t)cur.ks * sstep;
;     PG8_STAGE(PG8_SB(0, 0), cB, voffB); PG8_STAGE(PG8_SA(0, 0), cA, voffA); PG8_STAGE(PG8_SB(0, 1), cB + hstep, voffB); PG8_STAGE(PG8_SA(0, 1), cA + hstep, voffA);
;     if (wr == 1) PG8_BAR;
;     PG8_WAIT_V(4); PG8_BAR;
;     PG8_STAGE(PG8_SB(1, 0), cB + kstep, voffB); PG8_STAGE(PG8_SA(1, 0), cA + kstep, voffA); PG8_STAGE(PG8_SB(1, 1), cB + hstep + kstep, voffB);
;     PG8_WAIT_V(6); PG8_BAR;
.LBB0_345:
	s_waitcnt vmcnt(0)
	v_lshrrev_b32_e32 v18, 1, v11
	v_and_b32_e32 v18, 24, v18
	v_and_b32_e32 v17, 15, v11
	v_lshlrev_b32_e32 v19, 1, v18
	v_lshlrev_b32_e32 v11, 2, v11
	v_lshl_or_b32 v144, s8, 6, v17
	v_lshl_or_b32 v17, v17, 6, v19
	s_lshl_b32 s8, s8, 13
	v_and_b32_e32 v11, 32, v11
	v_bitop3_b32 v19, v17, s8, v11 bitop3:0xde
	s_lshl_b32 s8, s9, 5
	s_and_b32 s38, s8, 0x60
	s_add_i32 m0, s29, 0x18000
	v_lshl_add_u64 v[8:9], v[8:9], 0, s[36:37]
	s_lshl_b32 s8, s38, 7
	s_waitcnt vmcnt(4)
	s_barrier
	global_load_lds_dwordx4 v[8:9], off
	v_lshl_add_u64 v[6:7], v[6:7], 0, s[36:37]
	s_add_i32 m0, s29, 0x1a000
	s_add_i32 s59, s29, 0x8000
	s_add_i32 s60, s29, 0xa000
	v_bitop3_b32 v145, v17, s8, v11 bitop3:0xde
	v_add_u32_e32 v226, 0x10000, v145
	global_load_lds_dwordx4 v[6:7], off
	v_lshl_add_u64 v[4:5], v[4:5], 0, s[36:37]
	s_mov_b32 m0, s59
	s_add_u32 s8, s50, 0x80080
	global_load_lds_dwordx4 v[4:5], off
	v_lshl_add_u64 v[2:3], v[2:3], 0, s[36:37]
	s_mov_b32 m0, s60
	s_addc_u32 s9, s51, 0
	global_load_lds_dwordx4 v[2:3], off
	s_add_i32 m0, s29, 0x1c000
	v_lshl_add_u64 v[2:3], s[8:9], 0, v[0:1]
	global_load_lds_dwordx4 v[2:3], off
	v_lshl_add_u64 v[2:3], s[8:9], 0, v[134:135]
	s_add_i32 m0, s29, 0x1e000
	s_sub_i32 s8, 0, s24
	global_load_lds_dwordx4 v[2:3], off
	v_cvt_f32_ubyte0_e32 v2, s24
	v_rcp_iflag_f32_e32 v2, v2
	v_and_b32_e32 v3, 1, v14
	s_waitcnt vmcnt(6)
	s_lshl_b32 s61, s24, 3
	v_mul_f32_e32 v2, 0x4f7ffffe, v2
	v_cvt_u32_f32_e32 v2, v2
	s_ashr_i32 s62, s30, 31
	s_ashr_i32 s63, s13, 31
	v_or_b32_e32 v146, s38, v18
	v_readfirstlane_b32 s9, v2
	v_lshlrev_b32_e32 v2, 15, v14
	v_and_b32_e32 v2, 0xffff0000, v2
	v_lshl_add_u32 v2, v15, 12, v2
	v_lshl_or_b32 v2, v3, 6, v2
	v_lshl_add_u32 v136, v16, 1, v2
	v_lshlrev_b32_e32 v2, 15, v10
	v_and_b32_e32 v2, 0xffff0000, v2
	s_mul_i32 s8, s8, s9
	v_lshl_add_u32 v2, v12, 12, v2
	v_and_b32_e32 v3, 1, v10
	s_mul_hi_u32 s8, s9, s8
	v_lshl_or_b32 v2, v3, 6, v2
	s_mov_b32 s64, 0
	s_add_i32 s65, s9, s8
	v_mov_b32_e32 v137, v1
	v_lshl_add_u32 v138, v13, 1, v2
	v_mov_b32_e32 v139, v1
	v_add_u32_e32 v147, 0, v19
	s_barrier

; #define PG8_STAGE(bufoff, gbase, voff) do { _Pragma("unroll") for (int _i = 0; _i < 2; ++_i) \
;         __builtin_amdgcn_global_load_lds((const unsigned*)((const char*)(gbase) + (voff)[_i]), (LAS unsigned*)(lds + (bufoff) + ldsw + _i * 8192), 16, 0, 0); } while (0)
; #define PG8_LDA(dst, b, h) do { _Pragma("unroll") for (int m = 0; m < 4; ++m) _Pragma("unroll") for (int k = 0; k < 2; ++k) dst[m][k] = *(const LAS bf16x8*)(lds + PG8_SA(b, h) + aoff + m * 2048 + k * 1024); } while (0)
; #define PG8_LDB(dst, b, h) do { _Pragma("unroll") for (int n = 0; n < 2; ++n) _Pragma("unroll") for (int k = 0; k < 2; ++k) dst[n][k] = *(const LAS bf16x8*)(lds + PG8_SB(b, h) + boff + n * 2048 + k * 1024); } while (0)
; #define PG8_WAIT_V(n) asm volatile("s_waitcnt vmcnt(" #n ")" ::: "memory")
; #define PG8_WAIT_L(n) asm volatile("s_waitcnt lgkmcnt(" #n ")" ::: "memory")
; #define PG8_BAR __builtin_amdgcn_s_barrier()
; #define PG8_SCHED __builtin_amdgcn_sched_barrier(0)
; template <class Epi, class Sched>
; __device__ __forceinline__ void gemm_phase(LAS unsigned char* lds, const Gemm g, const Sched& S, const Epi& E) {
;     ...
;         const bool has_next = S.next(ui + 1, nxt);
;         const char* nA = has_next ? (const char*)g.A + (size_t)nxt.pm * tstep + (size_t)nxt.ks * sstep : cA; const char* nB = has_next ? (const char*)g.Bt + (size_t)nxt.pn * tstep + (size_t)nxt.ks * sstep : cB;
;         for (int t = 0; t < nt; t += 2) {
;             const bool last = (t == nt - 2);
;             const char* a1 = cA + (size_t)(t + 1) * kstep;
;             const char* a2 = last ? nA : cA + (size_t)(t + 2) * kstep; const char* b2 = last ? nB : cB + (size_t)(t + 2) * kstep;
;             const char* a3 = a2 + kstep; const char* b3 = b2 + kstep;
;             PG8_LDB(B0, 0, 0); PG8_SCHED; PG8_LDA(At, 0, 0); PG8_STAGE(PG8_SA(1, 1), a1 + hstep, voffA);
;             PG8_WAIT_L(8); PG8_BAR; PG8_WAIT_L(0); PG8_MMA(0, 0, At, B0); PG8_BAR; PG8_SCHED;
;             PG8_LDB(B1, 0, 1); PG8_STAGE(PG8_SB(0, 0), b2, voffB);
;             PG8_BAR; PG8_WAIT_L(0); PG8_MMA(0, 1, At, B1); PG8_BAR;
;             PG8_LDA(At, 0, 1); PG8_STAGE(PG8_SA(0, 0), a2, voffA);
;             PG8_BAR; PG8_WAIT_L(0); PG8_MMA(1, 0, At, B0); PG8_BAR; PG8_SCHED;
;             PG8_STAGE(PG8_SB(0, 1), b2 + hstep, voffB);
;             PG8_WAIT_V(6); PG8_BAR; PG8_MMA(1, 1, At, B1); PG8_BAR;
.LBB0_354:
	s_add_u32 s38, s50, 0xfff80080
	s_addc_u32 s39, s51, -1
	s_cmp_eq_u32 s70, 28
	s_cselect_b32 s55, s9, s39
	s_cselect_b32 s54, s66, s38
	s_cselect_b32 s53, s43, s69
	s_cselect_b32 s52, s67, s68
	s_add_i32 m0, s29, 0xc000
	s_nop 0
	global_load_lds_dwordx4 v138, s[50:51]
	s_add_i32 m0, s29, 0xe000
	s_nop 0
	global_load_lds_dwordx4 v136, s[50:51]
	s_add_i32 s71, 0, 0x10000
	ds_read_b128 v[140:143], v226
	ds_read_b128 v[148:151], v226 offset:1024
	ds_read_b128 v[152:155], v226 offset:2048
	ds_read_b128 v[160:163], v226 offset:3072
	ds_read_b128 v[164:167], v147
	ds_read_b128 v[168:171], v147 offset:1024
	ds_read_b128 v[172:175], v147 offset:2048
	ds_read_b128 v[176:179], v147 offset:3072
	ds_read_b128 v[180:183], v147 offset:4096
	ds_read_b128 v[184:187], v147 offset:5120
	ds_read_b128 v[188:191], v147 offset:6144
	ds_read_b128 v[192:195], v147 offset:7168
	s_add_i32 s38, 0, 0x14000
	ds_read_b128 v[196:199], v226 offset:16384
	ds_read_b128 v[200:203], v226 offset:17408
	ds_read_b128 v[204:207], v226 offset:18432
	ds_read_b128 v[210:213], v226 offset:19456
	s_waitcnt lgkmcnt(4)
	s_barrier
	s_waitcnt lgkmcnt(0)
	v_mfma_f32_16x16x32_bf16 v[126:129], v[140:143], v[164:167], v[126:129]
	v_mfma_f32_16x16x32_bf16 v[122:125], v[152:155], v[164:167], v[122:125]
	v_mfma_f32_16x16x32_bf16 v[118:121], v[140:143], v[172:175], v[118:121]
	v_mfma_f32_16x16x32_bf16 v[110:113], v[152:155], v[172:175], v[110:113]
	v_mfma_f32_16x16x32_bf16 v[102:105], v[140:143], v[180:183], v[102:105]
	v_mfma_f32_16x16x32_bf16 v[94:97], v[152:155], v[180:183], v[94:97]
	v_mfma_f32_16x16x32_bf16 v[86:89], v[140:143], v[188:191], v[86:89]
	v_mfma_f32_16x16x32_bf16 v[78:81], v[152:155], v[188:191], v[78:81]
	v_mfma_f32_16x16x32_bf16 v[126:129], v[148:151], v[168:171], v[126:129]
	v_mfma_f32_16x16x32_bf16 v[122:125], v[160:163], v[168:171], v[122:125]
	v_mfma_f32_16x16x32_bf16 v[118:121], v[148:151], v[176:179], v[118:121]
	v_mfma_f32_16x16x32_bf16 v[110:113], v[160:163], v[176:179], v[110:113]
	v_mfma_f32_16x16x32_bf16 v[102:105], v[148:151], v[184:187], v[102:105]
	v_mfma_f32_16x16x32_bf16 v[94:97], v[160:163], v[184:187], v[94:97]
	v_mfma_f32_16x16x32_bf16 v[86:89], v[148:151], v[192:195], v[86:89]
	v_mfma_f32_16x16x32_bf16 v[78:81], v[160:163], v[192:195], v[78:81]
	v_mfma_f32_16x16x32_bf16 v[114:117], v[196:199], v[164:167], v[114:117]
	v_mfma_f32_16x16x32_bf16 v[106:109], v[204:207], v[164:167], v[106:109]
	v_mfma_f32_16x16x32_bf16 v[98:101], v[196:199], v[172:175], v[98:101]
	v_mfma_f32_16x16x32_bf16 v[90:93], v[204:207], v[172:175], v[90:93]
	v_mfma_f32_16x16x32_bf16 v[82:85], v[196:199], v[180:183], v[82:85]
	v_mfma_f32_16x16x32_bf16 v[74:77], v[204:207], v[180:183], v[74:77]
	v_mfma_f32_16x16x32_bf16 v[70:73], v[196:199], v[188:191], v[70:73]
	v_mfma_f32_16x16x32_bf16 v[66:69], v[204:207], v[188:191], v[66:69]
	v_mfma_f32_16x16x32_bf16 v[114:117], v[200:203], v[168:171], v[114:117]
	v_mfma_f32_16x16x32_bf16 v[106:109], v[210:213], v[168:171], v[106:109]
	v_mfma_f32_16x16x32_bf16 v[98:101], v[200:203], v[176:179], v[98:101]
	v_mfma_f32_16x16x32_bf16 v[90:93], v[210:213], v[176:179], v[90:93]
	v_mfma_f32_16x16x32_bf16 v[82:85], v[200:203], v[184:187], v[82:85]
	v_mfma_f32_16x16x32_bf16 v[74:77], v[210:213], v[184:187], v[74:77]
	v_mfma_f32_16x16x32_bf16 v[70:73], v[200:203], v[192:195], v[70:73]
	v_mfma_f32_16x16x32_bf16 v[66:69], v[210:213], v[192:195], v[66:69]
	s_barrier
	s_add_i32 s39, s71, s56
	s_mov_b32 m0, s39
	s_nop 0
	global_load_lds_dwordx4 v0, s[52:53]
	s_add_i32 m0, s39, 0x2000
	s_nop 0
	global_load_lds_dwordx4 v134, s[52:53]
	s_mov_b32 m0, s29
	s_nop 0
	global_load_lds_dwordx4 v130, s[54:55]
	s_mov_b32 m0, s41
	s_nop 0
	global_load_lds_dwordx4 v132, s[54:55]
	ds_read_b128 v[164:167], v147 offset:16384
	ds_read_b128 v[168:171], v147 offset:17408
	ds_read_b128 v[172:175], v147 offset:18432
	ds_read_b128 v[176:179], v147 offset:19456
	ds_read_b128 v[180:183], v147 offset:20480
	ds_read_b128 v[184:187], v147 offset:21504
	ds_read_b128 v[188:191], v147 offset:22528
	ds_read_b128 v[192:195], v147 offset:23552
	s_waitcnt vmcnt(4)
	s_waitcnt lgkmcnt(0)
	s_barrier
	v_mfma_f32_16x16x32_bf16 v[62:65], v[140:143], v[164:167], v[62:65]
	v_mfma_f32_16x16x32_bf16 v[58:61], v[152:155], v[164:167], v[58:61]
	v_mfma_f32_16x16x32_bf16 v[54:57], v[140:143], v[172:175], v[54:57]
	v_mfma_f32_16x16x32_bf16 v[46:49], v[152:155], v[172:175], v[46:49]
	v_mfma_f32_16x16x32_bf16 v[38:41], v[140:143], v[180:183], v[38:41]
	v_mfma_f32_16x16x32_bf16 v[30:33], v[152:155], v[180:183], v[30:33]
	v_mfma_f32_16x16x32_bf16 v[22:25], v[140:143], v[188:191], v[22:25]
	v_mfma_f32_16x16x32_bf16 v[14:17], v[152:155], v[188:191], v[14:17]
	v_mfma_f32_16x16x32_bf16 v[62:65], v[148:151], v[168:171], v[62:65]
	v_mfma_f32_16x16x32_bf16 v[58:61], v[160:163], v[168:171], v[58:61]
	v_mfma_f32_16x16x32_bf16 v[54:57], v[148:151], v[176:179], v[54:57]
	v_mfma_f32_16x16x32_bf16 v[46:49], v[160:163], v[176:179], v[46:49]
	v_mfma_f32_16x16x32_bf16 v[38:41], v[148:151], v[184:187], v[38:41]
	v_mfma_f32_16x16x32_bf16 v[30:33], v[160:163], v[184:187], v[30:33]
	v_mfma_f32_16x16x32_bf16 v[22:25], v[148:151], v[192:195], v[22:25]
	v_mfma_f32_16x16x32_bf16 v[14:17], v[160:163], v[192:195], v[14:17]
	v_mfma_f32_16x16x32_bf16 v[50:53], v[196:199], v[164:167], v[50:53]
	v_mfma_f32_16x16x32_bf16 v[42:45], v[204:207], v[164:167], v[42:45]
	v_mfma_f32_16x16x32_bf16 v[34:37], v[196:199], v[172:175], v[34:37]
	v_mfma_f32_16x16x32_bf16 v[26:29], v[204:207], v[172:175], v[26:29]
	v_mfma_f32_16x16x32_bf16 v[18:21], v[196:199], v[180:183], v[18:21]
	v_mfma_f32_16x16x32_bf16 v[10:13], v[204:207], v[180:183], v[10:13]
	v_mfma_f32_16x16x32_bf16 v[6:9], v[196:199], v[188:191], v[6:9]
	v_mfma_f32_16x16x32_bf16 v[2:5], v[204:207], v[188:191], v[2:5]
	v_mfma_f32_16x16x32_bf16 v[50:53], v[200:203], v[168:171], v[50:53]
	v_mfma_f32_16x16x32_bf16 v[42:45], v[210:213], v[168:171], v[42:45]
	v_mfma_f32_16x16x32_bf16 v[34:37], v[200:203], v[176:179], v[34:37]
	v_mfma_f32_16x16x32_bf16 v[26:29], v[210:213], v[176:179], v[26:29]
	v_mfma_f32_16x16x32_bf16 v[18:21], v[200:203], v[184:187], v[18:21]
	v_mfma_f32_16x16x32_bf16 v[10:13], v[210:213], v[184:187], v[10:13]
	v_mfma_f32_16x16x32_bf16 v[6:9], v[200:203], v[192:195], v[6:9]
	v_mfma_f32_16x16x32_bf16 v[2:5], v[210:213], v[192:195], v[2:5]
	s_barrier
; #define PG8_STAGE(bufoff, gbase, voff) do { _Pragma("unroll") for (int _i = 0; _i < 2; ++_i) \
;         __builtin_amdgcn_global_load_lds((const unsigned*)((const char*)(gbase) + (voff)[_i]), (LAS unsigned*)(lds + (bufoff) + ldsw + _i * 8192), 16, 0, 0); } while (0)
; #define PG8_LDA(dst, b, h) do { _Pragma("unroll") for (int m = 0; m < 4; ++m) _Pragma("unroll") for (int k = 0; k < 2; ++k) dst[m][k] = *(const LAS bf16x8*)(lds + PG8_SA(b, h) + aoff + m * 2048 + k * 1024); } while (0)
; #define PG8_LDB(dst, b, h) do { _Pragma("unroll") for (int n = 0; n < 2; ++n) _Pragma("unroll") for (int k = 0; k < 2; ++k) dst[n][k] = *(const LAS bf16x8*)(lds + PG8_SB(b, h) + boff + n * 2048 + k * 1024); } while (0)
; #define PG8_MMA(ai, bj, At, Bt) do { __builtin_amdgcn_s_setprio(1); _Pragma("unroll") for (int m = 0; m < 4; ++m) _Pragma("unroll") for (int n = 0; n < 2; ++n) _Pragma("unroll") for (int k = 0; k < 2; ++k) \
;         acc[ai][bj][m][n] = __builtin_amdgcn_mfma_f32_16x16x32_bf16(Bt[n][k], At[m][k], acc[ai][bj][m][n], 0, 0, 0); __builtin_amdgcn_s_setprio(0); } while (0)
; #define PG8_WAIT_V(n) asm volatile("s_waitcnt vmcnt(" #n ")" ::: "memory")
; #define PG8_WAIT_L(n) asm volatile("s_waitcnt lgkmcnt(" #n ")" ::: "memory")
; #define PG8_BAR __builtin_amdgcn_s_barrier()
; #define PG8_SCHED __builtin_amdgcn_sched_barrier(0)
; template <class Epi, class Sched>
; __device__ __forceinline__ void gemm_phase(LAS unsigned char* lds, const Gemm g, const Sched& S, const Epi& E) {
;     ...
;             PG8_STAGE(PG8_SB(0, 1), b2 + hstep, voffB);
;             PG8_WAIT_V(6); PG8_BAR; PG8_MMA(1, 1, At, B1); PG8_BAR;
;             PG8_LDB(B0, 1, 0); PG8_SCHED; PG8_LDA(At, 1, 0); PG8_STAGE(PG8_SA(0, 1), a2 + hstep, voffA);
;             PG8_WAIT_L(8); PG8_BAR; PG8_WAIT_L(0); PG8_MMA(0, 0, At, B0); PG8_BAR; PG8_SCHED;
;             PG8_LDB(B1, 1, 1); PG8_STAGE(PG8_SB(1, 0), b3, voffB);
;             PG8_BAR; PG8_WAIT_L(0); PG8_MMA(0, 1, At, B1); PG8_BAR;
;             PG8_LDA(At, 1, 1); PG8_STAGE(PG8_SA(1, 0), a3, voffA);
;             PG8_BAR; PG8_WAIT_L(0); PG8_MMA(1, 0, At, B0); PG8_BAR; PG8_SCHED;
	s_add_u32 s72, s52, 0x80000
	s_addc_u32 s73, s53, 0
	s_add_i32 s38, s38, s56
	s_mov_b32 m0, s38
	s_nop 0
	global_load_lds_dwordx4 v0, s[72:73]
	s_add_i32 m0, s38, 0x2000
	s_nop 0
	global_load_lds_dwordx4 v134, s[72:73]
	s_add_u32 s54, s54, 0x80000
	s_addc_u32 s55, s55, 0
	s_mov_b32 m0, s57
	s_nop 0
	global_load_lds_dwordx4 v130, s[54:55]
	s_mov_b32 m0, s58
	s_nop 0
	global_load_lds_dwordx4 v132, s[54:55]
	s_add_i32 s38, 0, 0x18000
	ds_read_b128 v[140:143], v226 offset:32768
	ds_read_b128 v[148:151], v226 offset:33792
	ds_read_b128 v[152:155], v226 offset:34816
	ds_read_b128 v[160:163], v226 offset:35840
	ds_read_b128 v[164:167], v147 offset:32768
	ds_read_b128 v[168:171], v147 offset:33792
	ds_read_b128 v[172:175], v147 offset:34816
	ds_read_b128 v[176:179], v147 offset:35840
	ds_read_b128 v[180:183], v147 offset:36864
	ds_read_b128 v[184:187], v147 offset:37888
	ds_read_b128 v[188:191], v147 offset:38912
	ds_read_b128 v[192:195], v147 offset:39936
	s_add_i32 s39, 0, 0x1c000
	ds_read_b128 v[196:199], v226 offset:49152
	ds_read_b128 v[200:203], v226 offset:50176
	ds_read_b128 v[204:207], v226 offset:51200
	ds_read_b128 v[210:213], v226 offset:52224
	s_waitcnt lgkmcnt(4)
	s_barrier
	s_waitcnt lgkmcnt(0)
	v_mfma_f32_16x16x32_bf16 v[126:129], v[140:143], v[164:167], v[126:129]
	v_mfma_f32_16x16x32_bf16 v[122:125], v[152:155], v[164:167], v[122:125]
	v_mfma_f32_16x16x32_bf16 v[118:121], v[140:143], v[172:175], v[118:121]
	v_mfma_f32_16x16x32_bf16 v[110:113], v[152:155], v[172:175], v[110:113]
	v_mfma_f32_16x16x32_bf16 v[102:105], v[140:143], v[180:183], v[102:105]
	v_mfma_f32_16x16x32_bf16 v[94:97], v[152:155], v[180:183], v[94:97]
	v_mfma_f32_16x16x32_bf16 v[86:89], v[140:143], v[188:191], v[86:89]
	v_mfma_f32_16x16x32_bf16 v[78:81], v[152:155], v[188:191], v[78:81]
	v_mfma_f32_16x16x32_bf16 v[126:129], v[148:151], v[168:171], v[126:129]
	v_mfma_f32_16x16x32_bf16 v[122:125], v[160:163], v[168:171], v[122:125]
	v_mfma_f32_16x16x32_bf16 v[118:121], v[148:151], v[176:179], v[118:121]
	v_mfma_f32_16x16x32_bf16 v[110:113], v[160:163], v[176:179], v[110:113]
	v_mfma_f32_16x16x32_bf16 v[102:105], v[148:151], v[184:187], v[102:105]
	v_mfma_f32_16x16x32_bf16 v[94:97], v[160:163], v[184:187], v[94:97]
	v_mfma_f32_16x16x32_bf16 v[86:89], v[148:151], v[192:195], v[86:89]
	v_mfma_f32_16x16x32_bf16 v[78:81], v[160:163], v[192:195], v[78:81]
	v_mfma_f32_16x16x32_bf16 v[114:117], v[196:199], v[164:167], v[114:117]
	v_mfma_f32_16x16x32_bf16 v[106:109], v[204:207], v[164:167], v[106:109]
	v_mfma_f32_16x16x32_bf16 v[98:101], v[196:199], v[172:175], v[98:101]
	v_mfma_f32_16x16x32_bf16 v[90:93], v[204:207], v[172:175], v[90:93]
	v_mfma_f32_16x16x32_bf16 v[82:85], v[196:199], v[180:183], v[82:85]
	v_mfma_f32_16x16x32_bf16 v[74:77], v[204:207], v[180:183], v[74:77]
	v_mfma_f32_16x16x32_bf16 v[70:73], v[196:199], v[188:191], v[70:73]
	v_mfma_f32_16x16x32_bf16 v[66:69], v[204:207], v[188:191], v[66:69]
	v_mfma_f32_16x16x32_bf16 v[114:117], v[200:203], v[168:171], v[114:117]
	v_mfma_f32_16x16x32_bf16 v[106:109], v[210:213], v[168:171], v[106:109]
	v_mfma_f32_16x16x32_bf16 v[98:101], v[200:203], v[176:179], v[98:101]
	v_mfma_f32_16x16x32_bf16 v[90:93], v[210:213], v[176:179], v[90:93]
	v_mfma_f32_16x16x32_bf16 v[82:85], v[200:203], v[184:187], v[82:85]
	v_mfma_f32_16x16x32_bf16 v[74:77], v[210:213], v[184:187], v[74:77]
	v_mfma_f32_16x16x32_bf16 v[70:73], v[200:203], v[192:195], v[70:73]
	v_mfma_f32_16x16x32_bf16 v[66:69], v[210:213], v[192:195], v[66:69]
	s_barrier
	s_add_i32 s38, s38, s56
	s_add_u32 s100, s52, s36
	s_addc_u32 s101, s53, s37
	s_mov_b32 m0, s38
	s_nop 0
	global_load_lds_dwordx4 v0, s[100:101]
	s_add_i32 m0, s38, 0x2000
	s_nop 0
	global_load_lds_dwordx4 v134, s[100:101]
	s_mov_b32 m0, s59
	s_add_u32 s100, s54, s36
	s_addc_u32 s101, s55, s37
	s_sub_u32 s100, s100, 0x80000
	s_subb_u32 s101, s101, 0
	global_load_lds_dwordx4 v130, s[100:101]
	s_mov_b32 m0, s60
	s_nop 0
	global_load_lds_dwordx4 v132, s[100:101]
	ds_read_b128 v[164:167], v147 offset:49152
	ds_read_b128 v[168:171], v147 offset:50176
	ds_read_b128 v[172:175], v147 offset:51200
	ds_read_b128 v[176:179], v147 offset:52224
	ds_read_b128 v[180:183], v147 offset:53248
	ds_read_b128 v[184:187], v147 offset:54272
	ds_read_b128 v[188:191], v147 offset:55296
	ds_read_b128 v[192:195], v147 offset:56320
	s_waitcnt vmcnt(4)
	s_waitcnt lgkmcnt(0)
	s_barrier
; #define PG8_STAGE(bufoff, gbase, voff) do { _Pragma("unroll") for (int _i = 0; _i < 2; ++_i) \
;         __builtin_amdgcn_global_load_lds((const unsigned*)((const char*)(gbase) + (voff)[_i]), (LAS unsigned*)(lds + (bufoff) + ldsw + _i * 8192), 16, 0, 0); } while (0)
; #define PG8_LDA(dst, b, h) do { _Pragma("unroll") for (int m = 0; m < 4; ++m) _Pragma("unroll") for (int k = 0; k < 2; ++k) dst[m][k] = *(const LAS bf16x8*)(lds + PG8_SA(b, h) + aoff + m * 2048 + k * 1024); } while (0)
; #define PG8_MMA(ai, bj, At, Bt) do { __builtin_amdgcn_s_setprio(1); _Pragma("unroll") for (int m = 0; m < 4; ++m) _Pragma("unroll") for (int n = 0; n < 2; ++n) _Pragma("unroll") for (int k = 0; k < 2; ++k) \
;         acc[ai][bj][m][n] = __builtin_amdgcn_mfma_f32_16x16x32_bf16(Bt[n][k], At[m][k], acc[ai][bj][m][n], 0, 0, 0); __builtin_amdgcn_s_setprio(0); } while (0)
; #define PG8_WAIT_V(n) asm volatile("s_waitcnt vmcnt(" #n ")" ::: "memory")
; #define PG8_WAIT_L(n) asm volatile("s_waitcnt lgkmcnt(" #n ")" ::: "memory")
; #define PG8_BAR __builtin_amdgcn_s_barrier()
; #define PG8_SCHED __builtin_amdgcn_sched_barrier(0)
; template <class Epi, class Sched>
; __device__ __forceinline__ void gemm_phase(LAS unsigned char* lds, const Gemm g, const Sched& S, const Epi& E) {
;     ...
;             PG8_LDA(At, 1, 1); PG8_STAGE(PG8_SA(1, 0), a3, voffA);
;             PG8_BAR; PG8_WAIT_L(0); PG8_MMA(1, 0, At, B0); PG8_BAR; PG8_SCHED;
;             PG8_STAGE(PG8_SB(1, 1), b3 + hstep, voffB);
;             PG8_WAIT_V(6); PG8_BAR; PG8_MMA(1, 1, At, B1); PG8_BAR;
	v_mfma_f32_16x16x32_bf16 v[62:65], v[140:143], v[164:167], v[62:65]
	v_mfma_f32_16x16x32_bf16 v[58:61], v[152:155], v[164:167], v[58:61]
	v_mfma_f32_16x16x32_bf16 v[54:57], v[140:143], v[172:175], v[54:57]
	v_mfma_f32_16x16x32_bf16 v[46:49], v[152:155], v[172:175], v[46:49]
	v_mfma_f32_16x16x32_bf16 v[38:41], v[140:143], v[180:183], v[38:41]
	v_mfma_f32_16x16x32_bf16 v[30:33], v[152:155], v[180:183], v[30:33]
	v_mfma_f32_16x16x32_bf16 v[22:25], v[140:143], v[188:191], v[22:25]
	v_mfma_f32_16x16x32_bf16 v[14:17], v[152:155], v[188:191], v[14:17]
	v_mfma_f32_16x16x32_bf16 v[62:65], v[148:151], v[168:171], v[62:65]
	v_mfma_f32_16x16x32_bf16 v[58:61], v[160:163], v[168:171], v[58:61]
	v_mfma_f32_16x16x32_bf16 v[54:57], v[148:151], v[176:179], v[54:57]
	v_mfma_f32_16x16x32_bf16 v[46:49], v[160:163], v[176:179], v[46:49]
	v_mfma_f32_16x16x32_bf16 v[38:41], v[148:151], v[184:187], v[38:41]
	v_mfma_f32_16x16x32_bf16 v[30:33], v[160:163], v[184:187], v[30:33]
	v_mfma_f32_16x16x32_bf16 v[22:25], v[148:151], v[192:195], v[22:25]
	v_mfma_f32_16x16x32_bf16 v[14:17], v[160:163], v[192:195], v[14:17]
	s_add_u32 s52, s52, 0x80080
	s_addc_u32 s53, s53, 0
	s_add_i32 s38, s39, s56
	s_mov_b32 m0, s38
	s_nop 0
	global_load_lds_dwordx4 v0, s[52:53]
	s_add_i32 m0, s38, 0x2000
	s_nop 0
	global_load_lds_dwordx4 v134, s[52:53]
	v_mfma_f32_16x16x32_bf16 v[50:53], v[196:199], v[164:167], v[50:53]
	v_mfma_f32_16x16x32_bf16 v[42:45], v[204:207], v[164:167], v[42:45]
	v_mfma_f32_16x16x32_bf16 v[34:37], v[196:199], v[172:175], v[34:37]
	v_mfma_f32_16x16x32_bf16 v[26:29], v[204:207], v[172:175], v[26:29]
	v_mfma_f32_16x16x32_bf16 v[18:21], v[196:199], v[180:183], v[18:21]
	v_mfma_f32_16x16x32_bf16 v[10:13], v[204:207], v[180:183], v[10:13]
	v_mfma_f32_16x16x32_bf16 v[6:9], v[196:199], v[188:191], v[6:9]
	v_mfma_f32_16x16x32_bf16 v[2:5], v[204:207], v[188:191], v[2:5]
	v_mfma_f32_16x16x32_bf16 v[50:53], v[200:203], v[168:171], v[50:53]
	v_mfma_f32_16x16x32_bf16 v[42:45], v[210:213], v[168:171], v[42:45]
	v_mfma_f32_16x16x32_bf16 v[34:37], v[200:203], v[176:179], v[34:37]
	v_mfma_f32_16x16x32_bf16 v[26:29], v[210:213], v[176:179], v[26:29]
	v_mfma_f32_16x16x32_bf16 v[18:21], v[200:203], v[184:187], v[18:21]
	v_mfma_f32_16x16x32_bf16 v[10:13], v[210:213], v[184:187], v[10:13]
	v_mfma_f32_16x16x32_bf16 v[6:9], v[200:203], v[192:195], v[6:9]
	v_mfma_f32_16x16x32_bf16 v[2:5], v[210:213], v[192:195], v[2:5]
	s_add_i32 s70, s70, 2
	s_add_u32 s68, s68, 0x100
	s_addc_u32 s69, s69, 0
	s_add_u32 s50, s50, 0x100
	s_addc_u32 s51, s51, 0
	s_cmp_gt_u32 s70, 29
	s_barrier
	s_cbranch_scc0 .LBB0_354
; __device__ __forceinline__ unsigned cvt_pk_bf16(float lo, float hi) { unsigned r; asm("v_cvt_pk_bf16_f32 %0, %1, %2" : "=v"(r) : "v"(lo), "v"(hi)); return r; }
;     __device__ __forceinline__ void operator()(const f32x4 (&acc)[2][2][4][2], const Unit& u, int wr, int wc, int fr, int fq) const {
;         const int row0 = u.pm * BM + wr * 64 + fr, col0 = u.pn * BM + wc * 32 + 8 * fq;
; #pragma unroll
;         for (int ai = 0; ai < 2; ++ai)
; #pragma unroll
;             for (int m = 0; m < 4; ++m) { bf16_t* rowp = O + (size_t)(row0 + ai * HALF + m * 16) * ldc + col0;
; #pragma unroll
;                 for (int bj = 0; bj < 2; ++bj) { f32x4 v0 = acc[ai][bj][m][0], v1 = acc[ai][bj][m][1];
;                     if (ACT == 1) {
; #pragma unroll
;                         for (int j = 0; j < 4; ++j) { float a = fmaxf(v0[j], 0.f), b = fmaxf(v1[j], 0.f); v0[j] = a * a; v1[j] = b * b; } }
;                     u32x4 w; w.x = cvt_pk_bf16(v0[0], v0[1]); w.y = cvt_pk_bf16(v0[2], v0[3]); w.z = cvt_pk_bf16(v1[0], v1[1]); w.w = cvt_pk_bf16(v1[2], v1[3]);
;                     if (ACT == 1) __builtin_nontemporal_store(w, (u32x4*)(rowp + bj * HALF));
;                     else *(u32x4*)(rowp + bj * HALF) = w; } }
; template <class Epi, class Sched>
; __device__ __forceinline__ void gemm_phase(LAS unsigned char* lds, const Gemm g, const Sched& S, const Epi& E) {
;     ...
;         E(acc, cur, wr, wc, fr, fq);
;         if (!has_next) break;
	s_load_dwordx2 s[50:51], s[0:1], 0xc0
	v_lshl_add_u32 v150, s28, 8, v144
	v_lshl_or_b32 v142, s40, 8, v146
	v_ashrrev_i32_e32 v143, 31, v142
	v_cvt_pk_bf16_f32 v70, v70, v71
	s_waitcnt lgkmcnt(0)
	v_mov_b64_e32 v[140:141], s[50:51]
	v_cvt_pk_bf16_f32 v71, v72, v73
	v_cvt_pk_bf16_f32 v72, v66, v67
	v_add_u32_e32 v66, 0x80, v150
	v_mad_i64_i32 v[148:149], s[50:51], v150, s17, v[140:141]
	v_lshlrev_b64 v[142:143], 1, v[142:143]
	v_cvt_pk_bf16_f32 v114, v114, v115
	v_cvt_pk_bf16_f32 v115, v116, v117
	v_cvt_pk_bf16_f32 v116, v106, v107
	v_or_b32_e32 v106, 16, v150
	v_mad_i64_i32 v[66:67], s[50:51], v66, s17, v[140:141]
	v_cvt_pk_bf16_f32 v50, v50, v51
	v_cvt_pk_bf16_f32 v51, v52, v53
	v_cvt_pk_bf16_f32 v52, v42, v43
	v_add_u32_e32 v42, 0x90, v150
	v_lshl_add_u64 v[148:149], v[148:149], 0, v[142:143]
	v_mad_i64_i32 v[106:107], s[50:51], v106, s17, v[140:141]
	v_cvt_pk_bf16_f32 v98, v98, v99
	v_cvt_pk_bf16_f32 v99, v100, v101
	v_cvt_pk_bf16_f32 v100, v90, v91
	v_or_b32_e32 v90, 32, v150
	v_lshl_add_u64 v[66:67], v[66:67], 0, v[142:143]
	v_mad_i64_i32 v[42:43], s[50:51], v42, s17, v[140:141]
	v_cvt_pk_bf16_f32 v34, v34, v35
	v_cvt_pk_bf16_f32 v35, v36, v37
	v_cvt_pk_bf16_f32 v36, v26, v27
	v_add_u32_e32 v26, 0xa0, v150
	v_cvt_pk_bf16_f32 v117, v108, v109
	global_store_dwordx4 v[148:149], v[114:117], off offset:256
	v_mad_i64_i32 v[90:91], s[50:51], v90, s17, v[140:141]
	s_nop 0
	v_lshl_add_u64 v[114:115], v[106:107], 0, v[142:143]
	v_cvt_pk_bf16_f32 v82, v82, v83
	v_cvt_pk_bf16_f32 v83, v84, v85
	v_cvt_pk_bf16_f32 v84, v74, v75
	v_or_b32_e32 v74, 48, v150
	v_cvt_pk_bf16_f32 v53, v44, v45
	global_store_dwordx4 v[66:67], v[50:53], off offset:256
	v_mad_i64_i32 v[26:27], s[50:51], v26, s17, v[140:141]
	s_nop 0
	v_lshl_add_u64 v[50:51], v[42:43], 0, v[142:143]
	v_cvt_pk_bf16_f32 v18, v18, v19
	v_cvt_pk_bf16_f32 v19, v20, v21
	v_cvt_pk_bf16_f32 v20, v10, v11
	v_add_u32_e32 v10, 0xb0, v150
	v_cvt_pk_bf16_f32 v101, v92, v93
	global_store_dwordx4 v[114:115], v[98:101], off offset:256
	v_mad_i64_i32 v[74:75], s[50:51], v74, s17, v[140:141]
	s_nop 0
	v_lshl_add_u64 v[98:99], v[90:91], 0, v[142:143]
	v_cvt_pk_bf16_f32 v37, v28, v29
	global_store_dwordx4 v[50:51], v[34:37], off offset:256
	v_mad_i64_i32 v[10:11], s[50:51], v10, s17, v[140:141]
	s_nop 0
	v_lshl_add_u64 v[34:35], v[26:27], 0, v[142:143]
	v_cvt_pk_bf16_f32 v85, v76, v77
	global_store_dwordx4 v[98:99], v[82:85], off offset:256
	v_cvt_pk_bf16_f32 v21, v12, v13
	global_store_dwordx4 v[34:35], v[18:21], off offset:256
	s_and_b64 vcc, exec, s[46:47]
	v_lshl_add_u64 v[82:83], v[74:75], 0, v[142:143]
	v_lshl_add_u64 v[18:19], v[10:11], 0, v[142:143]
	s_mov_b32 s40, s42
	s_mov_b32 s28, s8
	s_mov_b32 s43, s42
	s_mov_b32 s46, s8
	s_mov_b64 s[50:51], s[48:49]
	s_mov_b64 s[52:53], s[44:45]
	v_cvt_pk_bf16_f32 v126, v126, v127
	v_cvt_pk_bf16_f32 v127, v128, v129
	v_cvt_pk_bf16_f32 v128, v122, v123
	v_cvt_pk_bf16_f32 v129, v124, v125
	global_store_dwordx4 v[148:149], v[126:129], off
	v_cvt_pk_bf16_f32 v106, v118, v119
	v_cvt_pk_bf16_f32 v107, v120, v121
	v_cvt_pk_bf16_f32 v108, v110, v111
	v_cvt_pk_bf16_f32 v109, v112, v113
	global_store_dwordx4 v[114:115], v[106:109], off
	v_cvt_pk_bf16_f32 v90, v102, v103
	v_cvt_pk_bf16_f32 v91, v104, v105
	v_cvt_pk_bf16_f32 v92, v94, v95
	v_cvt_pk_bf16_f32 v93, v96, v97
	global_store_dwordx4 v[98:99], v[90:93], off
	v_cvt_pk_bf16_f32 v74, v86, v87
	v_cvt_pk_bf16_f32 v75, v88, v89
	v_cvt_pk_bf16_f32 v76, v78, v79
	v_cvt_pk_bf16_f32 v77, v80, v81
	global_store_dwordx4 v[82:83], v[74:77], off
	v_cvt_pk_bf16_f32 v73, v68, v69
	global_store_dwordx4 v[82:83], v[70:73], off offset:256
	v_cvt_pk_bf16_f32 v62, v62, v63
	v_cvt_pk_bf16_f32 v63, v64, v65
	v_cvt_pk_bf16_f32 v64, v58, v59
	v_cvt_pk_bf16_f32 v65, v60, v61
	global_store_dwordx4 v[66:67], v[62:65], off
	v_cvt_pk_bf16_f32 v42, v54, v55
	v_cvt_pk_bf16_f32 v43, v56, v57
	v_cvt_pk_bf16_f32 v44, v46, v47
	v_cvt_pk_bf16_f32 v45, v48, v49
	global_store_dwordx4 v[50:51], v[42:45], off
	v_cvt_pk_bf16_f32 v26, v38, v39
	v_cvt_pk_bf16_f32 v27, v40, v41
	v_cvt_pk_bf16_f32 v28, v30, v31
	v_cvt_pk_bf16_f32 v29, v32, v33
	global_store_dwordx4 v[34:35], v[26:29], off
	v_cvt_pk_bf16_f32 v10, v22, v23
	v_cvt_pk_bf16_f32 v11, v24, v25
	v_cvt_pk_bf16_f32 v12, v14, v15
	v_cvt_pk_bf16_f32 v13, v16, v17
	global_store_dwordx4 v[18:19], v[10:13], off
	v_cvt_pk_bf16_f32 v6, v6, v7
	v_cvt_pk_bf16_f32 v7, v8, v9
	v_cvt_pk_bf16_f32 v8, v2, v3
	v_cvt_pk_bf16_f32 v9, v4, v5
	global_store_dwordx4 v[18:19], v[6:9], off offset:256
	s_cbranch_vccz .LBB0_346
	s_waitcnt vmcnt(0)
	s_cmpk_gt_u32 s25, 0xff
	s_cbranch_scc1 .LBB0_358
	s_barrier
